# scan phase: bare v_sqrt_f32 instead of the 15-instruction sqrtf fix-up expansion (62 sites), hazard distances kept with s_nop
# speedup vs baseline: 1.0736x; 1.0071x over previous
; __device__ __forceinline__ void scan_phase(KP p, int l, LAS unsigned char* lds) {
;     ...
;         LDS_WAIT();
;         {
;             const int ch = hc0 + lane;
; #pragma unroll
;             for (int k = 0; k < 4; ++k) CST[k * 64 + lane] = p->in[14][(size_t)(l * 4 + k) * D + ch];
;             CST[4 * 64 + lane] = p->in[15][l * D + ch]; CST[5 * 64 + lane] = p->in[17][l * D + ch]; CST[6 * 64 + lane] = p->in[19][l * D + ch]; CST[7 * 64 + lane] = SP[ch];
;         }
;         bf16x8 Wa[4][2], Wx[4][2];
; #pragma unroll
;         for (int n = 0; n < 4; ++n)
; #pragma unroll
;             for (int s = 0; s < 2; ++s) { const size_t o = (size_t)head * 4096 + (16 * n + fr) * 64 + 32 * s + 8 * fq;
;                 Wa[n][s] = *(const bf16x8*)((const bf16_t*)(p->ws + WS_RGA) + o); Wx[n][s] = *(const bf16x8*)((const bf16_t*)(p->ws + WS_RGX) + o); }
;         if (ck < 128) {
;             const int b = ck >> 4, q = ck & 15, tile0 = b * 129 + 8 * q;
;             float Hc[4], Pc[4];
; #pragma unroll
;             for (int n = 0; n < 4; ++n) { Hc[n] = 0.f; Pc[n] = 1.f; }
;             for (int tt = 0; tt < 8; tt += 2) scan_tiles<2>(p, l, P, HLOC, PCUM, XC, CST, Wa, Wx, b, hc0, (tile0 + tt) * 16, lane, fr, fq, Hc, Pc);
;             if (q == 15) scan_tiles<1>(p, l, P, HLOC, PCUM, XC, CST, Wa, Wx, b, hc0, (tile0 + 8) * 16, lane, fr, fq, Hc, Pc);
;             if (fq == 0) {
; #pragma unroll
;                 for (int n = 0; n < 4; ++n) { const int ch = hc0 + 16 * n + fr; SUMM[(size_t)ck * 2 * D + ch] = Pc[n]; SUMM[(size_t)ck * 2 * D + D + ch] = Hc[n]; } }
;         } else {
;             const int m0 = (1032 + (ck - 128)) * 16;
;             LDS_WAIT();
;             {   const int rr = lane >> 2, cb = lane & 3, cl = cb * 16, m = m0 + rr, sb = m - MP;
;                 float xv[4][16];
;                 const float* st = p->in[3] + ((size_t)(l * MS + sb) * 3) * D + hc0 + cl;
; #pragma unroll
;                 for (int k = 0; k < 3; ++k)
; #pragma unroll
;                     for (int e = 0; e < 16; e += 4) { const f32x4 v = *(const f32x4*)(st + (size_t)k * D + e); xv[k][e] = v[0]; xv[k][e + 1] = v[1]; xv[k][e + 2] = v[2]; xv[k][e + 3] = v[3]; }
;                 const bf16_t* src = P + (size_t)m * DP + C_XR + hc0 + cl;
;                 float f0[8], f1[8]; unpack8(*(const u32x4*)src, f0); unpack8(*(const u32x4*)(src + 8), f1);
; #pragma unroll
.LBB0_331:
	s_and_b32 s16, s54, 15
	s_waitcnt lgkmcnt(0)
	s_lshl_b32 s75, s16, 6
	s_load_dwordx4 s[12:15], s[58:59], 0x70
	s_load_dwordx2 s[10:11], s[58:59], 0x88
	s_load_dwordx2 s[18:19], s[58:59], 0x98
	s_waitcnt vmcnt(1)
	v_or_b32_e32 v6, s75, v205
	v_lshlrev_b32_e32 v0, 2, v6
	s_waitcnt vmcnt(0) lgkmcnt(0)
	v_lshl_add_u64 v[2:3], s[12:13], 0, v[0:1]
	v_lshl_add_u64 v[2:3], v[2:3], 0, s[68:69]
	v_add_co_u32_e32 v4, vcc, s43, v2
	global_load_dword v7, v[2:3], off
	s_nop 0
	v_addc_co_u32_e32 v5, vcc, 0, v3, vcc
	global_load_dword v8, v[4:5], off offset:-4096
	v_add_co_u32_e32 v2, vcc, s23, v2
	global_load_dword v4, v[4:5], off
	s_nop 0
	v_addc_co_u32_e32 v3, vcc, 0, v3, vcc
	global_load_dword v2, v[2:3], off
	v_mov_b32_e32 v3, v1
	s_ashr_i32 s74, s54, 4
	s_cmpk_gt_i32 s74, 0x7f
	v_add_u32_e32 v241, v232, v231
	s_waitcnt vmcnt(2)
	ds_write2st64_b32 v225, v7, v8 offset0:34 offset1:35
	s_waitcnt vmcnt(0)
	ds_write2st64_b32 v225, v4, v2 offset0:36 offset1:37
	v_or_b32_e32 v2, s77, v6
	v_lshlrev_b64 v[2:3], 2, v[2:3]
	v_lshl_add_u64 v[4:5], s[14:15], 0, v[2:3]
	global_load_dword v6, v[4:5], off
	v_lshl_add_u64 v[4:5], s[10:11], 0, v[2:3]
	global_load_dword v4, v[4:5], off
	v_lshl_add_u64 v[2:3], s[18:19], 0, v[2:3]
	s_mov_b64 s[10:11], -1
	s_waitcnt vmcnt(0)
	ds_write2st64_b32 v225, v6, v4 offset0:38 offset1:39
	global_load_dword v2, v[2:3], off
	s_nop 0
	global_load_dword v0, v0, s[66:67]
	s_waitcnt vmcnt(0)
	ds_write2st64_b32 v225, v2, v0 offset0:40 offset1:41
	v_lshl_or_b32 v0, s16, 13, v238
	v_or_b32_e32 v2, 64, v0
	global_load_dwordx4 v[34:37], v0, s[70:71]
	global_load_dwordx4 v[38:41], v0, s[72:73]
	global_load_dwordx4 v[10:13], v2, s[70:71]
	global_load_dwordx4 v[14:17], v2, s[72:73]
	v_or_b32_e32 v2, 0x800, v0
	global_load_dwordx4 v[42:45], v2, s[70:71]
	global_load_dwordx4 v[46:49], v2, s[72:73]
	v_or_b32_e32 v2, 0x840, v0
	global_load_dwordx4 v[22:25], v2, s[70:71]
	global_load_dwordx4 v[26:29], v2, s[72:73]
	v_or_b32_e32 v2, 0x1000, v0
	global_load_dwordx4 v[50:53], v2, s[70:71]
	global_load_dwordx4 v[54:57], v2, s[72:73]
	v_or_b32_e32 v2, 0x1040, v0
	global_load_dwordx4 v[30:33], v2, s[70:71]
	global_load_dwordx4 v[18:21], v2, s[72:73]
	v_or_b32_e32 v2, 0x1800, v0
	v_or_b32_e32 v0, 0x1840, v0
	global_load_dwordx4 v[62:65], v2, s[70:71]
	global_load_dwordx4 v[58:61], v2, s[72:73]
	global_load_dwordx4 v[6:9], v0, s[70:71]
	s_nop 0
	global_load_dwordx4 v[2:5], v0, s[72:73]
	v_lshlrev_b32_e32 v0, 1, v206
	s_cbranch_scc0 .LBB0_333
	s_waitcnt lgkmcnt(0)
	s_load_dwordx4 s[12:15], s[58:59], 0x18
	s_and_b32 s10, s54, -16
	s_add_i32 s11, s10, 0x3880
	v_or_b32_e32 v106, s11, v226
	v_add_u32_e32 v126, s78, v106
	s_waitcnt lgkmcnt(0)
	v_mov_b64_e32 v[66:67], s[12:13]
	v_mad_i64_i32 v[66:67], s[12:13], v126, s23, v[66:67]
	s_lshl_b32 s16, s75, 2
	v_lshl_add_u64 v[66:67], v[66:67], 0, s[16:17]
	v_lshlrev_b32_e32 v122, 2, v206
	v_mov_b32_e32 v123, v1
	v_lshl_add_u64 v[70:71], v[66:67], 0, v[122:123]
	v_add_co_u32_e32 v78, vcc, s43, v70
	v_lshl_add_u64 v[72:73], v[70:71], 0, s[28:29]
	s_nop 0
	v_addc_co_u32_e32 v79, vcc, 0, v71, vcc
	global_load_dwordx4 v[66:69], v[70:71], off offset:48
	global_load_dwordx4 v[82:85], v[70:71], off offset:32
	global_load_dwordx4 v[94:97], v[70:71], off offset:16
	global_load_dwordx4 v[110:113], v[70:71], off
	global_load_dwordx4 v[114:117], v[78:79], off offset:-4096
	global_load_dwordx4 v[74:77], v[72:73], off offset:48
	global_load_dwordx4 v[90:93], v[72:73], off offset:32
	global_load_dwordx4 v[102:105], v[72:73], off offset:16
	v_lshl_add_u64 v[80:81], v[70:71], 0, s[30:31]
	global_load_dwordx4 v[118:121], v[78:79], off
	global_load_dwordx4 v[70:73], v[80:81], off offset:48
	global_load_dwordx4 v[86:89], v[80:81], off offset:32
	global_load_dwordx4 v[98:101], v[80:81], off offset:16
	v_mov_b64_e32 v[78:79], s[60:61]
	v_mad_u64_u32 v[78:79], s[12:13], v106, s33, v[78:79]
	s_lshl_b32 s12, s75, 1
	s_mov_b32 s13, s17
	v_lshl_add_u64 v[78:79], v[78:79], 0, s[12:13]
	v_lshl_add_u64 v[78:79], v[78:79], 0, v[0:1]
	v_lshl_add_u64 v[80:81], v[78:79], 0, s[28:29]
	v_add_co_u32_e32 v78, vcc, s38, v78
	s_nop 1
	v_addc_co_u32_e32 v79, vcc, 0, v79, vcc
	global_load_dwordx4 v[106:109], v[78:79], off
	s_nop 0
	global_load_dwordx4 v[78:81], v[80:81], off offset:16
	s_load_dwordx2 s[12:13], s[58:59], 0xe0
	s_waitcnt lgkmcnt(0)
	v_mov_b64_e32 v[124:125], s[12:13]
	v_mad_i64_i32 v[124:125], s[18:19], v126, s23, v[124:125]
	v_lshl_add_u64 v[124:125], v[124:125], 0, s[16:17]
	v_lshl_add_u64 v[146:147], v[124:125], 0, v[122:123]
	s_mov_b32 s16, 0x45f1000
	v_add_co_u32_e32 v124, vcc, s16, v146
	s_mov_b64 s[18:19], 0x45f0000
	s_nop 0
	v_addc_co_u32_e32 v125, vcc, 0, v147, vcc
	v_lshl_add_u64 v[122:123], v[146:147], 0, s[18:19]
	s_mov_b32 s16, 0x45f2000
	s_mov_b64 s[18:19], 0x4bf0000
	s_waitcnt vmcnt(9)
	global_store_dwordx4 v[124:125], v[114:117], off offset:-4096
	s_waitcnt vmcnt(7)
	global_store_dwordx4 v[122:123], v[102:105], off offset:16
	global_store_dwordx4 v[122:123], v[90:93], off offset:32
	global_store_dwordx4 v[122:123], v[74:77], off offset:48
	s_waitcnt vmcnt(9)
	global_store_dwordx4 v[124:125], v[118:121], off
	s_waitcnt vmcnt(7)
	global_store_dwordx4 v[124:125], v[98:101], off offset:16
	global_store_dwordx4 v[124:125], v[86:89], off offset:32
	global_store_dwordx4 v[124:125], v[70:73], off offset:48
	ds_read_b128 v[122:125], v227 offset:8704
	ds_read_b128 v[126:129], v227 offset:8960
	ds_read_b128 v[130:133], v227 offset:9216
	ds_read_b128 v[134:137], v227 offset:9472
	ds_read_b128 v[138:141], v227 offset:9728
	s_waitcnt lgkmcnt(3)
; #define LAS __attribute__((address_space(3)))
; __device__ __forceinline__ unsigned cvt_pk_bf16(float lo, float hi) { unsigned r; asm volatile("v_cvt_pk_bf16_f32 %0, %1, %2" : "=v"(r) : "v"(lo), "v"(hi)); return r; }
; __device__ __forceinline__ void scan_phase(KP p, int l, LAS unsigned char* lds) {
;     ...
;                 for (int e = 0; e < 16; e += 4) {
;                     const f32x4 w0 = *(const LAS f32x4*)(CST + 0 * 64 + cl + e), w1 = *(const LAS f32x4*)(CST + 1 * 64 + cl + e), w2 = *(const LAS f32x4*)(CST + 2 * 64 + cl + e),
;                                 w3 = *(const LAS f32x4*)(CST + 3 * 64 + cl + e), bb = *(const LAS f32x4*)(CST + 4 * 64 + cl + e);
;                     f32x4 r;
; #pragma unroll
;                     for (int q = 0; q < 4; ++q) r[q] = w0[q] * xv[0][e + q] + w1[q] * xv[1][e + q] + w2[q] * xv[2][e + q] + w3[q] * xv[3][e + q] + bb[q];
;                     *(LAS f32x4*)(XC + rr * 68 + cl + e) = r;
;                 }
;             }
;             LDS_WAIT();
;             f32x4 ar[4], ai[4];
; #pragma unroll
;             for (int n = 0; n < 4; ++n) { ar[n] = (f32x4){0.f, 0.f, 0.f, 0.f}; ai[n] = (f32x4){0.f, 0.f, 0.f, 0.f}; }
; #pragma unroll
;             for (int s = 0; s < 2; ++s) {
;                 const f32x4 x0 = *(const LAS f32x4*)(XC + fr * 68 + 32 * s + 8 * fq), x1 = *(const LAS f32x4*)(XC + fr * 68 + 32 * s + 8 * fq + 4);
;                 u32x4 aw; aw.x = cvt_pk_bf16(x0[0], x0[1]); aw.y = cvt_pk_bf16(x0[2], x0[3]); aw.z = cvt_pk_bf16(x1[0], x1[1]); aw.w = cvt_pk_bf16(x1[2], x1[3]);
;                 const bf16x8 af = __builtin_bit_cast(bf16x8, aw);
; #pragma unroll
;                 for (int n = 0; n < 4; ++n) { ar[n] = __builtin_amdgcn_mfma_f32_16x16x32_bf16(af, Wa[n][s], ar[n], 0, 0, 0); ai[n] = __builtin_amdgcn_mfma_f32_16x16x32_bf16(af, Wx[n][s], ai[n], 0, 0, 0); }
;             }
; #pragma unroll
;             for (int n = 0; n < 4; ++n) {
;                 const int cc = 16 * n + fr, ch = hc0 + cc;
;                 const float ba = CST[5 * 64 + cc], bx = CST[6 * 64 + cc], sp = CST[7 * 64 + cc];
; #pragma unroll
;                 for (int j = 0; j < 4; ++j) {
;                     const float xc = XC[(4 * fq + j) * 68 + cc];
;                     const float r = sigmoidf_(ar[n][j] + ba), ig = sigmoidf_(ai[n][j] + bx);
;                     const float a = __expf(-8.0f * r * sp);
	v_pk_mul_f32 v[116:117], v[116:117], v[128:129]
	v_pk_mul_f32 v[114:115], v[114:115], v[126:127]
	v_pk_fma_f32 v[112:113], v[112:113], v[124:125], v[116:117]
	v_pk_fma_f32 v[110:111], v[110:111], v[122:123], v[114:115]
	s_waitcnt lgkmcnt(2)
	v_pk_fma_f32 v[112:113], v[120:121], v[132:133], v[112:113]
	v_pk_fma_f32 v[110:111], v[118:119], v[130:131], v[110:111]
	s_waitcnt vmcnt(9)
	v_lshlrev_b32_e32 v142, 16, v106
	v_and_b32_e32 v143, 0xffff0000, v106
	v_lshlrev_b32_e32 v144, 16, v107
	v_and_b32_e32 v145, 0xffff0000, v107
	v_add_co_u32_e32 v106, vcc, s16, v146
	s_waitcnt lgkmcnt(1)
	v_pk_fma_f32 v[112:113], v[136:137], v[144:145], v[112:113]
	v_pk_fma_f32 v[110:111], v[134:135], v[142:143], v[110:111]
	v_addc_co_u32_e32 v107, vcc, 0, v147, vcc
	s_waitcnt lgkmcnt(0)
	v_pk_add_f32 v[112:113], v[140:141], v[112:113]
	v_pk_add_f32 v[110:111], v[138:139], v[110:111]
	global_store_dwordx4 v[106:107], v[142:145], off
	ds_write_b128 v228, v[110:113]
	ds_read_b128 v[110:113], v227 offset:8720
	ds_read_b128 v[114:117], v227 offset:8976
	ds_read_b128 v[118:121], v227 offset:9232
	ds_read_b128 v[122:125], v227 offset:9488
	ds_read_b128 v[126:129], v227 offset:9744
	v_lshlrev_b32_e32 v130, 16, v108
	s_waitcnt lgkmcnt(3)
	v_pk_mul_f32 v[104:105], v[104:105], v[116:117]
	v_pk_mul_f32 v[102:103], v[102:103], v[114:115]
	v_pk_fma_f32 v[96:97], v[96:97], v[112:113], v[104:105]
	v_pk_fma_f32 v[94:95], v[94:95], v[110:111], v[102:103]
	v_and_b32_e32 v131, 0xffff0000, v108
	v_lshlrev_b32_e32 v132, 16, v109
	v_and_b32_e32 v133, 0xffff0000, v109
	s_waitcnt lgkmcnt(2)
	v_pk_fma_f32 v[96:97], v[100:101], v[120:121], v[96:97]
	v_pk_fma_f32 v[94:95], v[98:99], v[118:119], v[94:95]
	s_waitcnt lgkmcnt(1)
	v_pk_fma_f32 v[96:97], v[124:125], v[132:133], v[96:97]
	v_pk_fma_f32 v[94:95], v[122:123], v[130:131], v[94:95]
	s_waitcnt lgkmcnt(0)
	v_pk_add_f32 v[96:97], v[128:129], v[96:97]
	v_pk_add_f32 v[94:95], v[126:127], v[94:95]
	global_store_dwordx4 v[106:107], v[130:133], off offset:16
	ds_write_b128 v228, v[94:97] offset:16
	ds_read_b128 v[94:97], v227 offset:8736
	ds_read_b128 v[98:101], v227 offset:8992
	ds_read_b128 v[102:105], v227 offset:9248
	ds_read_b128 v[108:111], v227 offset:9504
	ds_read_b128 v[112:115], v227 offset:9760
	s_waitcnt vmcnt(10)
	v_lshlrev_b32_e32 v116, 16, v78
	v_and_b32_e32 v117, 0xffff0000, v78
	v_lshlrev_b32_e32 v118, 16, v79
	v_and_b32_e32 v119, 0xffff0000, v79
	s_waitcnt lgkmcnt(3)
	v_pk_mul_f32 v[78:79], v[92:93], v[100:101]
	v_pk_mul_f32 v[90:91], v[90:91], v[98:99]
	v_pk_fma_f32 v[78:79], v[84:85], v[96:97], v[78:79]
	v_pk_fma_f32 v[82:83], v[82:83], v[94:95], v[90:91]
	s_waitcnt lgkmcnt(2)
	v_pk_fma_f32 v[78:79], v[88:89], v[104:105], v[78:79]
	v_pk_fma_f32 v[82:83], v[86:87], v[102:103], v[82:83]
	s_waitcnt lgkmcnt(1)
	v_pk_fma_f32 v[78:79], v[110:111], v[118:119], v[78:79]
	v_pk_fma_f32 v[82:83], v[108:109], v[116:117], v[82:83]
	s_waitcnt lgkmcnt(0)
	v_pk_add_f32 v[84:85], v[114:115], v[78:79]
	v_pk_add_f32 v[82:83], v[112:113], v[82:83]
	global_store_dwordx4 v[106:107], v[116:119], off offset:32
	ds_write_b128 v228, v[82:85] offset:32
	ds_read_b128 v[82:85], v227 offset:8752
	ds_read_b128 v[86:89], v227 offset:9008
	ds_read_b128 v[90:93], v227 offset:9264
	ds_read_b128 v[94:97], v227 offset:9520
	ds_read_b128 v[98:101], v227 offset:9776
	v_lshlrev_b32_e32 v78, 16, v80
	s_waitcnt lgkmcnt(3)
	v_pk_mul_f32 v[76:77], v[76:77], v[88:89]
	v_pk_mul_f32 v[74:75], v[74:75], v[86:87]
	v_pk_fma_f32 v[68:69], v[68:69], v[84:85], v[76:77]
	v_pk_fma_f32 v[66:67], v[66:67], v[82:83], v[74:75]
	v_and_b32_e32 v79, 0xffff0000, v80
	v_lshlrev_b32_e32 v80, 16, v81
	v_and_b32_e32 v81, 0xffff0000, v81
	s_waitcnt lgkmcnt(2)
	v_pk_fma_f32 v[68:69], v[72:73], v[92:93], v[68:69]
	v_pk_fma_f32 v[66:67], v[70:71], v[90:91], v[66:67]
	s_waitcnt lgkmcnt(1)
	v_pk_fma_f32 v[68:69], v[96:97], v[80:81], v[68:69]
	v_pk_fma_f32 v[66:67], v[94:95], v[78:79], v[66:67]
	s_waitcnt lgkmcnt(0)
	v_pk_add_f32 v[68:69], v[100:101], v[68:69]
	v_pk_add_f32 v[66:67], v[98:99], v[66:67]
	global_store_dwordx4 v[106:107], v[78:81], off offset:48
	ds_write_b128 v228, v[66:69] offset:48
	s_waitcnt lgkmcnt(0)
	ds_read_b128 v[66:69], v239
	ds_read_b128 v[70:73], v239 offset:16
	s_waitcnt lgkmcnt(1)
	v_cvt_pk_bf16_f32 v66, v66, v67
	v_cvt_pk_bf16_f32 v67, v68, v69
	s_waitcnt lgkmcnt(0)
	v_cvt_pk_bf16_f32 v68, v70, v71
	v_cvt_pk_bf16_f32 v69, v72, v73
	ds_read_b128 v[86:89], v239 offset:128
	ds_read_b128 v[90:93], v239 offset:144
	v_mfma_f32_16x16x32_bf16 v[70:73], v[66:69], v[34:37], 0
	s_waitcnt lgkmcnt(1)
	v_cvt_pk_bf16_f32 v110, v86, v87
	v_cvt_pk_bf16_f32 v111, v88, v89
	s_waitcnt lgkmcnt(0)
	v_cvt_pk_bf16_f32 v112, v90, v91
	v_cvt_pk_bf16_f32 v113, v92, v93
	ds_read2st64_b32 v[120:121], v232 offset0:39 offset1:40
	ds_read_b32 v123, v232 offset:10496
	v_mfma_f32_16x16x32_bf16 v[94:97], v[110:113], v[10:13], v[70:73]
	v_or_b32_e32 v114, s11, v229
	v_or_b32_e32 v122, s75, v223
	v_lshlrev_b32_e32 v116, 2, v122
	v_mfma_f32_16x16x32_bf16 v[78:81], v[66:69], v[42:45], 0
	v_mov_b32_e32 v117, v1
	s_waitcnt lgkmcnt(1)
	s_nop 1
	v_add_f32_e32 v94, v94, v120
	v_mul_f32_e32 v94, 0xbfb8aa3b, v94
	v_exp_f32_e32 v94, v94
	v_mfma_f32_16x16x32_bf16 v[98:101], v[66:69], v[50:53], 0
	v_lshl_add_u64 v[118:119], s[14:15], 0, v[116:117]
	v_ashrrev_i32_e32 v115, 31, v114
	v_add_f32_e32 v94, 1.0, v94
	v_rcp_f32_e32 v94, v94
	v_mfma_f32_16x16x32_bf16 v[86:89], v[110:113], v[22:25], v[78:81]
	v_mul_f32_e32 v94, 0xc1000000, v94
	s_waitcnt lgkmcnt(0)
; __device__ __forceinline__ unsigned cvt_pk_bf16(float lo, float hi) { unsigned r; asm volatile("v_cvt_pk_bf16_f32 %0, %1, %2" : "=v"(r) : "v"(lo), "v"(hi)); return r; }
; __device__ __forceinline__ float sigmoidf_(float x) { return __builtin_amdgcn_rcpf(1.0f + __expf(-x)); }
; __device__ __forceinline__ void scan_phase(KP p, int l, LAS unsigned char* lds) {
;     ...
;             for (int n = 0; n < 4; ++n) {
;                 const int cc = 16 * n + fr, ch = hc0 + cc;
;                 const float ba = CST[5 * 64 + cc], bx = CST[6 * 64 + cc], sp = CST[7 * 64 + cc];
; #pragma unroll
;                 for (int j = 0; j < 4; ++j) {
;                     const float xc = XC[(4 * fq + j) * 68 + cc];
;                     const float r = sigmoidf_(ar[n][j] + ba), ig = sigmoidf_(ai[n][j] + bx);
;                     const float a = __expf(-8.0f * r * sp);
;                     const float mult = sqrtf(fmaxf(1.0f - a * a, 0.f));
;                     const int sb = m0 - MP + 4 * fq + j;
;                     const float h0 = p->in[4][(size_t)(l * MS + sb) * D + ch];
;                     const float h = a * h0 + mult * ig * xc;
;                     const size_t o = (size_t)(m0 + 4 * fq + j) * D + ch; HLOC[o] = (bf16_t)(cvt_pk_bf16(h, 0.f) & 0xffffu); PCUM[o] = 0;
;                     p->out[O_SRG + (size_t)(l * MS + sb) * D + ch] = h; }
	v_mul_f32_e32 v94, v123, v94
	v_mul_f32_e32 v94, 0x3fb8aa3b, v94
	v_exp_f32_e32 v94, v94
	v_mfma_f32_16x16x32_bf16 v[78:81], v[110:113], v[30:33], v[98:101]
	s_nop 2
	v_fma_f32 v98, -v94, v94, 1.0
	v_max_f32_e32 v98, 0, v98
	s_nop 0
	s_nop 0
	v_mfma_f32_16x16x32_bf16 v[74:77], v[66:69], v[38:41], 0
	s_nop 0
	s_nop 0
	ds_read_b32 v100, v241
	v_mfma_f32_16x16x32_bf16 v[102:105], v[66:69], v[54:57], 0
	s_nop 0
	v_mfma_f32_16x16x32_bf16 v[82:85], v[66:69], v[46:49], 0
	v_mfma_f32_16x16x32_bf16 v[106:109], v[66:69], v[62:65], 0
	v_mfma_f32_16x16x32_bf16 v[66:69], v[66:69], v[58:61], 0
	v_mfma_f32_16x16x32_bf16 v[90:93], v[110:113], v[14:17], v[74:77]
	v_mfma_f32_16x16x32_bf16 v[74:77], v[110:113], v[18:21], v[102:105]
	s_nop 2
	s_nop 0
	v_mfma_f32_16x16x32_bf16 v[82:85], v[110:113], v[26:29], v[82:85]
	s_nop 1
	v_add_f32_e32 v90, v90, v121
	v_mul_f32_e32 v90, 0xbfb8aa3b, v90
	v_exp_f32_e32 v90, v90
	v_mfma_f32_16x16x32_bf16 v[70:73], v[110:113], v[6:9], v[106:109]
	v_add_f32_e32 v91, v91, v121
	v_mul_f32_e32 v91, 0xbfb8aa3b, v91
	v_add_f32_e32 v90, 1.0, v90
	v_mfma_f32_16x16x32_bf16 v[66:69], v[110:113], v[2:5], v[66:69]
	v_add_u32_e32 v110, s10, v230
	s_nop 0
	s_nop 0
	v_ashrrev_i32_e32 v111, 31, v110
	s_nop 0
	s_nop 0
	s_nop 0
	v_lshlrev_b64 v[106:107], 12, v[110:111]
	v_rcp_f32_e32 v90, v90
	s_nop 0
	s_nop 0
	s_nop 0
	s_nop 0
	v_lshlrev_b64 v[102:103], 10, v[114:115]
	v_exp_f32_e32 v91, v91
	v_sqrt_f32_e32 v101, v98
	s_nop 0
	v_lshl_add_u64 v[98:99], v[118:119], 0, v[106:107]
	global_load_dword v98, v[98:99], off
	v_mul_f32_e32 v90, v90, v101
	s_waitcnt lgkmcnt(0)
	v_mul_f32_e32 v90, v100, v90
	v_mov_b32_e32 v99, v103
	v_add_f32_e32 v91, 1.0, v91
	v_add_f32_e32 v92, v92, v121
	v_mul_f32_e32 v92, 0xbfb8aa3b, v92
	v_exp_f32_e32 v92, v92
	v_add_f32_e32 v93, v93, v121
	v_mul_f32_e32 v93, 0xbfb8aa3b, v93
	v_exp_f32_e32 v93, v93
	v_add_f32_e32 v92, 1.0, v92
	v_rcp_f32_e32 v92, v92
	v_add_f32_e32 v93, 1.0, v93
	s_waitcnt vmcnt(0)
	v_fmac_f32_e32 v90, v98, v94
	v_or_b32_e32 v98, v102, v122
	v_lshlrev_b64 v[98:99], 1, v[98:99]
	v_lshl_add_u64 v[100:101], s[62:63], 0, v[98:99]
	v_lshl_add_u64 v[98:99], s[64:65], 0, v[98:99]
	v_cvt_pk_bf16_f32 v94, v90, v1
	global_store_short v[98:99], v1, off
	v_lshl_add_u64 v[98:99], s[12:13], 0, v[106:107]
	v_lshl_add_u64 v[98:99], v[98:99], 0, s[18:19]
	global_store_short v[100:101], v94, off
	v_lshl_add_u64 v[100:101], v[98:99], 0, v[116:117]
	global_store_dword v[100:101], v90, off
	v_add_f32_e32 v90, v95, v120
	v_mul_f32_e32 v90, 0xbfb8aa3b, v90
	v_exp_f32_e32 v90, v90
	v_rcp_f32_e32 v95, v91
	ds_read_b32 v94, v241 offset:272
	v_add_f32_e32 v90, 1.0, v90
	v_rcp_f32_e32 v90, v90
	s_nop 0
	v_mul_f32_e32 v90, 0xc1000000, v90
	v_mul_f32_e32 v90, v123, v90
	v_mul_f32_e32 v90, 0x3fb8aa3b, v90
	v_exp_f32_e32 v100, v90
	s_nop 0
	v_fma_f32 v90, -v100, v100, 1.0
	v_max_f32_e32 v90, 0, v90
	s_nop 0
	s_nop 0
	s_nop 0
	s_nop 0
	s_nop 0
	s_nop 0
	s_nop 0
	s_nop 0
	s_nop 0
	s_nop 0
	s_nop 0
	s_nop 0
	s_nop 0
	s_nop 0
	s_nop 1
	s_nop 0
	s_nop 0
	s_nop 0
	s_nop 0
	s_nop 1
	v_sqrt_f32_e32 v101, v90
	s_nop 0
	v_or_b32_e32 v90, 1, v110
	v_ashrrev_i32_e32 v91, 31, v90
	v_lshlrev_b64 v[112:113], 12, v[90:91]
	v_lshl_add_u64 v[90:91], v[118:119], 0, v[112:113]
	global_load_dword v90, v[90:91], off
	v_mul_f32_e32 v91, v95, v101
	s_waitcnt lgkmcnt(0)
	v_mul_f32_e32 v104, v94, v91
	s_waitcnt vmcnt(0)
	v_fmac_f32_e32 v104, v100, v90
	v_or_b32_e32 v90, 1, v114
	v_ashrrev_i32_e32 v91, 31, v90
	v_lshlrev_b64 v[100:101], 10, v[90:91]
	v_or_b32_e32 v90, v100, v122
	v_mov_b32_e32 v91, v101
	v_lshlrev_b64 v[90:91], 1, v[90:91]
	v_lshl_add_u64 v[94:95], s[62:63], 0, v[90:91]
	v_lshl_add_u64 v[90:91], s[64:65], 0, v[90:91]
	v_cvt_pk_bf16_f32 v105, v104, v1
	global_store_short v[90:91], v1, off
	v_lshl_add_u64 v[90:91], s[12:13], 0, v[112:113]
	v_lshl_add_u64 v[90:91], v[90:91], 0, s[18:19]
	global_store_short v[94:95], v105, off
	v_lshl_add_u64 v[94:95], v[90:91], 0, v[116:117]
	global_store_dword v[94:95], v104, off
	v_add_f32_e32 v94, v96, v120
	v_mul_f32_e32 v94, 0xbfb8aa3b, v94
	v_exp_f32_e32 v94, v94
	ds_read_b32 v104, v241 offset:544
	v_add_f32_e32 v94, 1.0, v94
	v_rcp_f32_e32 v94, v94
	s_nop 0
	v_mul_f32_e32 v94, 0xc1000000, v94
	v_mul_f32_e32 v94, v123, v94
	v_mul_f32_e32 v94, 0x3fb8aa3b, v94
	v_exp_f32_e32 v96, v94
	s_nop 0
	v_fma_f32 v94, -v96, v96, 1.0
	v_max_f32_e32 v94, 0, v94
	s_nop 0
	s_nop 0
	s_nop 0
	s_nop 0
	s_nop 0
	s_nop 0
	s_nop 0
	s_nop 0
	s_nop 0
	s_nop 0
	s_nop 0
	s_nop 0
	s_nop 0
	s_nop 0
	s_nop 1
	s_nop 0
	s_nop 0
	s_nop 0
	s_nop 0
	s_nop 1
	v_sqrt_f32_e32 v105, v94
	s_nop 0
	v_or_b32_e32 v94, 2, v110
	v_ashrrev_i32_e32 v95, 31, v94
	v_lshlrev_b64 v[108:109], 12, v[94:95]
	v_lshl_add_u64 v[94:95], v[118:119], 0, v[108:109]
	global_load_dword v94, v[94:95], off
	v_mul_f32_e32 v92, v92, v105
	s_waitcnt vmcnt(0)
	v_mul_f32_e32 v96, v96, v94
	v_or_b32_e32 v94, 2, v114
	v_ashrrev_i32_e32 v95, 31, v94
	s_waitcnt lgkmcnt(0)
	v_fmac_f32_e32 v96, v92, v104
	v_lshlrev_b64 v[104:105], 10, v[94:95]
	v_or_b32_e32 v94, v104, v122
	v_mov_b32_e32 v95, v105
	v_lshlrev_b64 v[94:95], 1, v[94:95]
	v_cvt_pk_bf16_f32 v92, v96, v1
	v_lshl_add_u64 v[124:125], s[62:63], 0, v[94:95]
	global_store_short v[124:125], v92, off
	v_add_f32_e32 v92, v97, v120
	v_mul_f32_e32 v92, 0xbfb8aa3b, v92
	v_exp_f32_e32 v92, v92
	v_rcp_f32_e32 v97, v93
	v_lshl_add_u64 v[94:95], s[64:65], 0, v[94:95]
	global_store_short v[94:95], v1, off
	v_add_f32_e32 v92, 1.0, v92
	v_rcp_f32_e32 v92, v92
	v_lshl_add_u64 v[94:95], s[12:13], 0, v[108:109]
	v_lshl_add_u64 v[94:95], v[94:95], 0, s[18:19]
	v_lshl_add_u64 v[124:125], v[94:95], 0, v[116:117]
	v_mul_f32_e32 v92, 0xc1000000, v92
	v_mul_f32_e32 v92, v123, v92
	v_mul_f32_e32 v92, 0x3fb8aa3b, v92
	v_exp_f32_e32 v115, v92
	global_store_dword v[124:125], v96, off
	ds_read_b32 v96, v241 offset:816
	v_fma_f32 v92, -v115, v115, 1.0
	v_max_f32_e32 v92, 0, v92
	s_nop 0
	s_nop 0
	s_nop 0
	s_nop 0
	s_nop 0
	s_nop 0
	s_nop 0
	s_nop 0
	s_nop 0
	s_nop 0
	s_nop 0
	s_nop 0
	s_nop 0
	s_nop 0
	s_nop 1
	s_nop 0
	s_nop 0
	s_nop 0
	s_nop 0
	s_nop 1
	v_sqrt_f32_e32 v120, v92
	s_nop 0
	v_or_b32_e32 v92, 3, v110
	v_ashrrev_i32_e32 v93, 31, v92
	v_lshlrev_b64 v[110:111], 12, v[92:93]
	v_lshl_add_u64 v[92:93], v[118:119], 0, v[110:111]
	global_load_dword v92, v[92:93], off
	s_waitcnt vmcnt(0)
; __device__ __forceinline__ unsigned cvt_pk_bf16(float lo, float hi) { unsigned r; asm volatile("v_cvt_pk_bf16_f32 %0, %1, %2" : "=v"(r) : "v"(lo), "v"(hi)); return r; }
; __device__ __forceinline__ float sigmoidf_(float x) { return __builtin_amdgcn_rcpf(1.0f + __expf(-x)); }
; __device__ __forceinline__ void scan_phase(KP p, int l, LAS unsigned char* lds) {
;     ...
;             for (int n = 0; n < 4; ++n) {
;                 const int cc = 16 * n + fr, ch = hc0 + cc;
;                 const float ba = CST[5 * 64 + cc], bx = CST[6 * 64 + cc], sp = CST[7 * 64 + cc];
; #pragma unroll
;                 for (int j = 0; j < 4; ++j) {
;                     const float xc = XC[(4 * fq + j) * 68 + cc];
;                     const float r = sigmoidf_(ar[n][j] + ba), ig = sigmoidf_(ai[n][j] + bx);
;                     const float a = __expf(-8.0f * r * sp);
;                     const float mult = sqrtf(fmaxf(1.0f - a * a, 0.f));
;                     const int sb = m0 - MP + 4 * fq + j;
;                     const float h0 = p->in[4][(size_t)(l * MS + sb) * D + ch];
;                     const float h = a * h0 + mult * ig * xc;
;                     const size_t o = (size_t)(m0 + 4 * fq + j) * D + ch; HLOC[o] = (bf16_t)(cvt_pk_bf16(h, 0.f) & 0xffffu); PCUM[o] = 0;
;                     p->out[O_SRG + (size_t)(l * MS + sb) * D + ch] = h; }
	v_mul_f32_e32 v118, v115, v92
	v_mul_f32_e32 v92, v97, v120
	s_waitcnt lgkmcnt(0)
	v_fmac_f32_e32 v118, v92, v96
	v_or_b32_e32 v92, 3, v114
	v_ashrrev_i32_e32 v93, 31, v92
	v_lshlrev_b64 v[96:97], 10, v[92:93]
	v_or_b32_e32 v92, v96, v122
	v_mov_b32_e32 v93, v97
	v_lshlrev_b64 v[92:93], 1, v[92:93]
	v_lshl_add_u64 v[114:115], s[62:63], 0, v[92:93]
	v_lshl_add_u64 v[92:93], s[64:65], 0, v[92:93]
	v_cvt_pk_bf16_f32 v119, v118, v1
	global_store_short v[92:93], v1, off
	v_lshl_add_u64 v[92:93], s[12:13], 0, v[110:111]
	v_lshl_add_u64 v[92:93], v[92:93], 0, s[18:19]
	global_store_short v[114:115], v119, off
	v_lshl_add_u64 v[114:115], v[92:93], 0, v[116:117]
	global_store_dword v[114:115], v118, off
	v_add_u32_e32 v114, 64, v232
	ds_read2st64_b32 v[118:119], v114 offset0:39 offset1:40
	ds_read_b32 v121, v232 offset:10560
	v_add_lshl_u32 v114, s75, v223, 2
	v_mov_b32_e32 v115, v1
	v_lshl_add_u64 v[114:115], s[14:15], 0, v[114:115]
	s_waitcnt lgkmcnt(1)
	v_add_f32_e32 v86, v86, v118
	v_mul_f32_e32 v86, 0xbfb8aa3b, v86
	v_exp_f32_e32 v86, v86
	v_lshl_add_u64 v[106:107], v[114:115], 0, v[106:107]
	v_add_f32_e32 v82, v82, v119
	v_mul_f32_e32 v82, 0xbfb8aa3b, v82
	v_add_f32_e32 v86, 1.0, v86
	v_rcp_f32_e32 v86, v86
	v_exp_f32_e32 v82, v82
	ds_read_b32 v116, v241 offset:64
	v_or_b32_e32 v120, s75, v233
	v_mul_f32_e32 v86, 0xc1000000, v86
	s_waitcnt lgkmcnt(1)
	v_mul_f32_e32 v86, v121, v86
	v_mul_f32_e32 v86, 0x3fb8aa3b, v86
	v_exp_f32_e32 v86, v86
	v_add_f32_e32 v82, 1.0, v82
	v_rcp_f32_e32 v82, v82
	v_add_f32_e32 v83, v83, v119
	v_fma_f32 v117, -v86, v86, 1.0
	v_max_f32_e32 v117, 0, v117
	s_nop 0
	s_nop 0
	v_mul_f32_e32 v83, 0xbfb8aa3b, v83
	s_nop 0
	s_nop 0
	v_exp_f32_e32 v83, v83
	v_add_f32_e32 v84, v84, v119
	v_mul_f32_e32 v84, 0xbfb8aa3b, v84
	s_nop 0
	s_nop 0
	s_nop 0
	s_nop 0
	v_add_f32_e32 v83, 1.0, v83
	s_nop 0
	s_nop 0
	s_nop 0
	v_exp_f32_e32 v84, v84
	v_add_f32_e32 v85, v85, v119
	s_nop 0
	s_nop 0
	s_nop 0
	s_nop 0
	v_add_f32_e32 v84, 1.0, v84
	v_rcp_f32_e32 v84, v84
	v_sqrt_f32_e32 v117, v117
	s_nop 0
	global_load_dword v122, v[106:107], off offset:64
	v_mul_f32_e32 v82, v82, v117
	s_waitcnt lgkmcnt(0)
	v_mul_f32_e32 v82, v116, v82
	v_or_b32_e32 v116, v102, v120
	v_mov_b32_e32 v117, v103
	v_lshlrev_b64 v[116:117], 1, v[116:117]
	v_mul_f32_e32 v85, 0xbfb8aa3b, v85
	v_exp_f32_e32 v85, v85
	s_waitcnt vmcnt(0)
	v_fmac_f32_e32 v82, v122, v86
	v_lshl_add_u64 v[122:123], s[62:63], 0, v[116:117]
	v_lshl_add_u64 v[116:117], s[64:65], 0, v[116:117]
	v_cvt_pk_bf16_f32 v86, v82, v1
	global_store_short v[116:117], v1, off
	v_lshlrev_b32_e32 v116, 2, v120
	v_mov_b32_e32 v117, v1
	global_store_short v[122:123], v86, off
	v_lshl_add_u64 v[122:123], v[98:99], 0, v[116:117]
	global_store_dword v[122:123], v82, off
	v_add_f32_e32 v82, v87, v118
	v_mul_f32_e32 v82, 0xbfb8aa3b, v82
	v_exp_f32_e32 v82, v82
	v_rcp_f32_e32 v87, v83
	ds_read_b32 v86, v241 offset:336
	v_add_f32_e32 v85, 1.0, v85
	v_add_f32_e32 v82, 1.0, v82
	v_rcp_f32_e32 v82, v82
	s_nop 0
	v_mul_f32_e32 v82, 0xc1000000, v82
	v_mul_f32_e32 v82, v121, v82
	v_mul_f32_e32 v82, 0x3fb8aa3b, v82
	v_exp_f32_e32 v122, v82
	s_nop 0
	v_fma_f32 v82, -v122, v122, 1.0
	v_max_f32_e32 v82, 0, v82
	s_nop 0
	s_nop 0
	s_nop 0
	s_nop 0
	s_nop 0
	s_nop 0
	s_nop 0
	s_nop 0
	s_nop 0
	s_nop 0
	s_nop 0
	s_nop 0
	s_nop 0
	s_nop 0
	s_nop 1
	s_nop 0
	s_nop 0
	s_nop 0
	s_nop 0
	s_nop 1
	v_sqrt_f32_e32 v123, v82
	s_nop 0
	v_lshl_add_u64 v[82:83], v[114:115], 0, v[112:113]
	global_load_dword v112, v[82:83], off offset:64
	v_mul_f32_e32 v87, v87, v123
	s_waitcnt lgkmcnt(0)
	v_mul_f32_e32 v123, v86, v87
	v_or_b32_e32 v86, v100, v120
	v_mov_b32_e32 v87, v101
	v_lshlrev_b64 v[86:87], 1, v[86:87]
	s_waitcnt vmcnt(0)
	v_fmac_f32_e32 v123, v122, v112
	v_lshl_add_u64 v[112:113], s[62:63], 0, v[86:87]
	v_lshl_add_u64 v[86:87], s[64:65], 0, v[86:87]
	v_cvt_pk_bf16_f32 v122, v123, v1
	global_store_short v[86:87], v1, off
	v_lshl_add_u64 v[86:87], v[90:91], 0, v[116:117]
	global_store_dword v[86:87], v123, off
	v_add_f32_e32 v86, v88, v118
	v_mul_f32_e32 v86, 0xbfb8aa3b, v86
	v_exp_f32_e32 v86, v86
	global_store_short v[112:113], v122, off
	ds_read_b32 v112, v241 offset:608
	v_add_f32_e32 v86, 1.0, v86
	v_rcp_f32_e32 v86, v86
	s_nop 0
	v_mul_f32_e32 v86, 0xc1000000, v86
	v_mul_f32_e32 v86, v121, v86
	v_mul_f32_e32 v86, 0x3fb8aa3b, v86
	v_exp_f32_e32 v88, v86
	s_nop 0
	v_fma_f32 v86, -v88, v88, 1.0
	v_max_f32_e32 v86, 0, v86
	s_nop 0
	s_nop 0
	s_nop 0
	s_nop 0
	s_nop 0
	s_nop 0
	s_nop 0
	s_nop 0
	s_nop 0
	s_nop 0
	s_nop 0
	s_nop 0
	s_nop 0
	s_nop 0
	s_nop 1
	s_nop 0
	s_nop 0
	s_nop 0
	s_nop 0
	s_nop 1
	v_sqrt_f32_e32 v113, v86
	s_nop 0
	v_lshl_add_u64 v[86:87], v[114:115], 0, v[108:109]
	global_load_dword v108, v[86:87], off offset:64
	v_mov_b32_e32 v109, v105
	v_mul_f32_e32 v84, v84, v113
	s_waitcnt vmcnt(0)
	v_mul_f32_e32 v88, v88, v108
	v_or_b32_e32 v108, v104, v120
	v_lshlrev_b64 v[108:109], 1, v[108:109]
	s_waitcnt lgkmcnt(0)
	v_fmac_f32_e32 v88, v84, v112
	v_cvt_pk_bf16_f32 v84, v88, v1
	v_lshl_add_u64 v[112:113], s[62:63], 0, v[108:109]
	global_store_short v[112:113], v84, off
	v_add_f32_e32 v84, v89, v118
	v_mul_f32_e32 v84, 0xbfb8aa3b, v84
	v_exp_f32_e32 v84, v84
	v_lshl_add_u64 v[108:109], s[64:65], 0, v[108:109]
	global_store_short v[108:109], v1, off
	v_lshl_add_u64 v[108:109], v[94:95], 0, v[116:117]
	v_add_f32_e32 v84, 1.0, v84
	v_rcp_f32_e32 v84, v84
	global_store_dword v[108:109], v88, off
	v_rcp_f32_e32 v89, v85
	ds_read_b32 v88, v241 offset:880
	v_mul_f32_e32 v84, 0xc1000000, v84
	v_mul_f32_e32 v84, v121, v84
	v_mul_f32_e32 v84, 0x3fb8aa3b, v84
	v_exp_f32_e32 v108, v84
	s_nop 0
	v_fma_f32 v84, -v108, v108, 1.0
	v_max_f32_e32 v84, 0, v84
	s_nop 0
	s_nop 0
	s_nop 0
	s_nop 0
	s_nop 0
	s_nop 0
	s_nop 0
	s_nop 0
	s_nop 0
	s_nop 0
	s_nop 0
	s_nop 0
	s_nop 0
	s_nop 0
	s_nop 1
	s_nop 0
	s_nop 0
	s_nop 0
	s_nop 0
	s_nop 1
	v_sqrt_f32_e32 v109, v84
	s_nop 0
	v_lshl_add_u64 v[84:85], v[114:115], 0, v[110:111]
	global_load_dword v110, v[84:85], off offset:64
	v_mul_f32_e32 v89, v89, v109
	s_waitcnt vmcnt(0)
; __device__ __forceinline__ unsigned cvt_pk_bf16(float lo, float hi) { unsigned r; asm volatile("v_cvt_pk_bf16_f32 %0, %1, %2" : "=v"(r) : "v"(lo), "v"(hi)); return r; }
; __device__ __forceinline__ float sigmoidf_(float x) { return __builtin_amdgcn_rcpf(1.0f + __expf(-x)); }
; __device__ __forceinline__ void scan_phase(KP p, int l, LAS unsigned char* lds) {
;     ...
;             for (int n = 0; n < 4; ++n) {
;                 const int cc = 16 * n + fr, ch = hc0 + cc;
;                 const float ba = CST[5 * 64 + cc], bx = CST[6 * 64 + cc], sp = CST[7 * 64 + cc];
; #pragma unroll
;                 for (int j = 0; j < 4; ++j) {
;                     const float xc = XC[(4 * fq + j) * 68 + cc];
;                     const float r = sigmoidf_(ar[n][j] + ba), ig = sigmoidf_(ai[n][j] + bx);
;                     const float a = __expf(-8.0f * r * sp);
;                     const float mult = sqrtf(fmaxf(1.0f - a * a, 0.f));
;                     const int sb = m0 - MP + 4 * fq + j;
;                     const float h0 = p->in[4][(size_t)(l * MS + sb) * D + ch];
;                     const float h = a * h0 + mult * ig * xc;
;                     const size_t o = (size_t)(m0 + 4 * fq + j) * D + ch; HLOC[o] = (bf16_t)(cvt_pk_bf16(h, 0.f) & 0xffffu); PCUM[o] = 0;
;                     p->out[O_SRG + (size_t)(l * MS + sb) * D + ch] = h; }
	v_mul_f32_e32 v110, v108, v110
	s_waitcnt lgkmcnt(0)
	v_fmac_f32_e32 v110, v89, v88
	v_or_b32_e32 v88, v96, v120
	v_mov_b32_e32 v89, v97
	v_lshlrev_b64 v[88:89], 1, v[88:89]
	v_lshl_add_u64 v[108:109], s[62:63], 0, v[88:89]
	v_lshl_add_u64 v[88:89], s[64:65], 0, v[88:89]
	v_cvt_pk_bf16_f32 v111, v110, v1
	global_store_short v[88:89], v1, off
	v_lshl_add_u64 v[88:89], v[92:93], 0, v[116:117]
	global_store_short v[108:109], v111, off
	global_store_dword v[88:89], v110, off
	v_add_u32_e32 v88, 0x80, v232
	ds_read2st64_b32 v[108:109], v88 offset0:39 offset1:40
	ds_read_b32 v111, v232 offset:10624
	ds_read_b32 v88, v241 offset:128
	v_or_b32_e32 v110, s75, v234
	s_waitcnt lgkmcnt(2)
	v_add_f32_e32 v78, v78, v108
	v_mul_f32_e32 v78, 0xbfb8aa3b, v78
	v_exp_f32_e32 v78, v78
	v_add_f32_e32 v74, v74, v109
	v_mul_f32_e32 v74, 0xbfb8aa3b, v74
	v_exp_f32_e32 v74, v74
	v_add_f32_e32 v78, 1.0, v78
	v_rcp_f32_e32 v78, v78
	v_add_f32_e32 v75, v75, v109
	v_add_f32_e32 v74, 1.0, v74
	v_rcp_f32_e32 v74, v74
	v_mul_f32_e32 v78, 0xc1000000, v78
	s_waitcnt lgkmcnt(1)
	v_mul_f32_e32 v78, v111, v78
	v_mul_f32_e32 v78, 0x3fb8aa3b, v78
	v_exp_f32_e32 v78, v78
	v_mul_f32_e32 v75, 0xbfb8aa3b, v75
	v_exp_f32_e32 v75, v75
	v_add_f32_e32 v76, v76, v109
	v_fma_f32 v89, -v78, v78, 1.0
	v_max_f32_e32 v89, 0, v89
	s_nop 0
	s_nop 0
	v_add_f32_e32 v75, 1.0, v75
	s_nop 0
	s_nop 0
	v_rcp_f32_e32 v75, v75
	v_mul_f32_e32 v76, 0xbfb8aa3b, v76
	v_exp_f32_e32 v76, v76
	s_nop 0
	s_nop 0
	s_nop 0
	s_nop 0
	v_add_f32_e32 v76, 1.0, v76
	s_nop 0
	s_nop 0
	s_nop 0
	v_rcp_f32_e32 v76, v76
	s_nop 0
	s_nop 0
	s_nop 0
	s_nop 0
	s_nop 0
	s_nop 1
	v_sqrt_f32_e32 v89, v89
	s_nop 0
	global_load_dword v112, v[106:107], off offset:128
	v_mul_f32_e32 v74, v74, v89
	s_waitcnt lgkmcnt(0)
	v_mul_f32_e32 v74, v88, v74
	v_or_b32_e32 v88, v102, v110
	v_mov_b32_e32 v89, v103
	v_lshlrev_b64 v[88:89], 1, v[88:89]
	s_waitcnt vmcnt(0)
	v_fmac_f32_e32 v74, v112, v78
	v_cvt_pk_bf16_f32 v78, v74, v1
	v_lshl_add_u64 v[112:113], s[62:63], 0, v[88:89]
	global_store_short v[112:113], v78, off
	v_add_f32_e32 v78, v79, v108
	v_mul_f32_e32 v78, 0xbfb8aa3b, v78
	v_exp_f32_e32 v78, v78
	v_lshl_add_u64 v[88:89], s[64:65], 0, v[88:89]
	global_store_short v[88:89], v1, off
	v_lshlrev_b32_e32 v88, 2, v110
	v_add_f32_e32 v78, 1.0, v78
	v_rcp_f32_e32 v78, v78
	v_mov_b32_e32 v89, v1
	v_lshl_add_u64 v[112:113], v[98:99], 0, v[88:89]
	global_store_dword v[112:113], v74, off
	v_mul_f32_e32 v78, 0xc1000000, v78
	v_mul_f32_e32 v78, v111, v78
	v_mul_f32_e32 v78, 0x3fb8aa3b, v78
	v_exp_f32_e32 v78, v78
	ds_read_b32 v74, v241 offset:400
	v_fma_f32 v79, -v78, v78, 1.0
	v_max_f32_e32 v79, 0, v79
	s_nop 0
	s_nop 0
	s_nop 0
	s_nop 0
	s_nop 0
	s_nop 0
	s_nop 0
	s_nop 0
	s_nop 0
	s_nop 0
	s_nop 0
	s_nop 0
	s_nop 0
	s_nop 0
	s_nop 1
	s_nop 0
	s_nop 0
	s_nop 0
	s_nop 0
	s_nop 1
	v_sqrt_f32_e32 v79, v79
	s_nop 0
	global_load_dword v112, v[82:83], off offset:128
	v_mul_f32_e32 v75, v75, v79
	s_waitcnt lgkmcnt(0)
	v_mul_f32_e32 v113, v74, v75
	v_or_b32_e32 v74, v100, v110
	v_mov_b32_e32 v75, v101
	v_lshlrev_b64 v[74:75], 1, v[74:75]
	s_waitcnt vmcnt(0)
	v_fmac_f32_e32 v113, v78, v112
	v_lshl_add_u64 v[78:79], s[62:63], 0, v[74:75]
	v_lshl_add_u64 v[74:75], s[64:65], 0, v[74:75]
	v_cvt_pk_bf16_f32 v112, v113, v1
	global_store_short v[74:75], v1, off
	v_lshl_add_u64 v[74:75], v[90:91], 0, v[88:89]
	global_store_dword v[74:75], v113, off
	v_add_f32_e32 v75, v80, v108
	v_mul_f32_e32 v75, 0xbfb8aa3b, v75
	v_exp_f32_e32 v75, v75
	global_store_short v[78:79], v112, off
	ds_read_b32 v74, v241 offset:672
	v_add_f32_e32 v75, 1.0, v75
	v_rcp_f32_e32 v75, v75
	s_nop 0
	v_mul_f32_e32 v75, 0xc1000000, v75
	v_mul_f32_e32 v75, v111, v75
	v_mul_f32_e32 v75, 0x3fb8aa3b, v75
	v_exp_f32_e32 v75, v75
	s_nop 0
	v_fma_f32 v78, -v75, v75, 1.0
	v_max_f32_e32 v78, 0, v78
	s_nop 0
	s_nop 0
	s_nop 0
	s_nop 0
	s_nop 0
	s_nop 0
	s_nop 0
	s_nop 0
	s_nop 0
	s_nop 0
	s_nop 0
	s_nop 0
	s_nop 0
	s_nop 0
	s_nop 1
	s_nop 0
	s_nop 0
	s_nop 0
	s_nop 0
	s_nop 1
	v_sqrt_f32_e32 v78, v78
	s_nop 0
	global_load_dword v79, v[86:87], off offset:128
	s_waitcnt vmcnt(0)
	v_mul_f32_e32 v80, v75, v79
	v_mul_f32_e32 v75, v76, v78
	s_waitcnt lgkmcnt(0)
	v_fmac_f32_e32 v80, v75, v74
	v_or_b32_e32 v74, v104, v110
	v_mov_b32_e32 v75, v105
	v_lshlrev_b64 v[74:75], 1, v[74:75]
	v_lshl_add_u64 v[78:79], s[62:63], 0, v[74:75]
	v_lshl_add_u64 v[74:75], s[64:65], 0, v[74:75]
	v_cvt_pk_bf16_f32 v76, v80, v1
	global_store_short v[74:75], v1, off
	v_lshl_add_u64 v[74:75], v[94:95], 0, v[88:89]
	global_store_dword v[74:75], v80, off
	v_add_f32_e32 v75, v81, v108
	v_mul_f32_e32 v75, 0xbfb8aa3b, v75
	v_exp_f32_e32 v75, v75
	global_store_short v[78:79], v76, off
	v_add_f32_e32 v76, v77, v109
	v_mul_f32_e32 v76, 0xbfb8aa3b, v76
	v_add_f32_e32 v75, 1.0, v75
	v_rcp_f32_e32 v75, v75
	v_exp_f32_e32 v76, v76
	ds_read_b32 v74, v241 offset:944
	v_mul_f32_e32 v75, 0xc1000000, v75
	v_mul_f32_e32 v75, v111, v75
	v_mul_f32_e32 v75, 0x3fb8aa3b, v75
	v_exp_f32_e32 v75, v75
	v_add_f32_e32 v76, 1.0, v76
	v_rcp_f32_e32 v76, v76
	v_fma_f32 v77, -v75, v75, 1.0
	v_max_f32_e32 v77, 0, v77
	s_nop 0
	s_nop 0
	s_nop 0
	s_nop 0
	s_nop 0
	s_nop 0
	s_nop 0
	s_nop 0
	s_nop 0
	s_nop 0
	s_nop 0
	s_nop 0
	s_nop 0
	s_nop 0
	s_nop 1
	s_nop 0
	s_nop 0
	s_nop 0
	s_nop 0
	s_nop 1
	v_sqrt_f32_e32 v77, v77
	s_nop 0
	global_load_dword v78, v[84:85], off offset:128
	s_waitcnt vmcnt(0)
	v_mul_f32_e32 v78, v75, v78
	v_mul_f32_e32 v75, v76, v77
	s_waitcnt lgkmcnt(0)
; __device__ __forceinline__ unsigned cvt_pk_bf16(float lo, float hi) { unsigned r; asm volatile("v_cvt_pk_bf16_f32 %0, %1, %2" : "=v"(r) : "v"(lo), "v"(hi)); return r; }
; __device__ __forceinline__ float sigmoidf_(float x) { return __builtin_amdgcn_rcpf(1.0f + __expf(-x)); }
; __device__ __forceinline__ void scan_phase(KP p, int l, LAS unsigned char* lds) {
;     ...
;             for (int n = 0; n < 4; ++n) {
;                 const int cc = 16 * n + fr, ch = hc0 + cc;
;                 const float ba = CST[5 * 64 + cc], bx = CST[6 * 64 + cc], sp = CST[7 * 64 + cc];
; #pragma unroll
;                 for (int j = 0; j < 4; ++j) {
;                     const float xc = XC[(4 * fq + j) * 68 + cc];
;                     const float r = sigmoidf_(ar[n][j] + ba), ig = sigmoidf_(ai[n][j] + bx);
;                     const float a = __expf(-8.0f * r * sp);
;                     const float mult = sqrtf(fmaxf(1.0f - a * a, 0.f));
;                     const int sb = m0 - MP + 4 * fq + j;
;                     const float h0 = p->in[4][(size_t)(l * MS + sb) * D + ch];
;                     const float h = a * h0 + mult * ig * xc;
;                     const size_t o = (size_t)(m0 + 4 * fq + j) * D + ch; HLOC[o] = (bf16_t)(cvt_pk_bf16(h, 0.f) & 0xffffu); PCUM[o] = 0;
;                     p->out[O_SRG + (size_t)(l * MS + sb) * D + ch] = h; }
;             }
	v_fmac_f32_e32 v78, v75, v74
	v_or_b32_e32 v74, v96, v110
	v_mov_b32_e32 v75, v97
	v_lshlrev_b64 v[74:75], 1, v[74:75]
	v_lshl_add_u64 v[76:77], s[62:63], 0, v[74:75]
	v_lshl_add_u64 v[74:75], s[64:65], 0, v[74:75]
	v_cvt_pk_bf16_f32 v79, v78, v1
	global_store_short v[74:75], v1, off
	v_lshl_add_u64 v[74:75], v[92:93], 0, v[88:89]
	global_store_short v[76:77], v79, off
	global_store_dword v[74:75], v78, off
	v_add_u32_e32 v74, 0xc0, v232
	ds_read2st64_b32 v[76:77], v74 offset0:39 offset1:40
	ds_read_b32 v79, v232 offset:10688
	ds_read_b32 v74, v241 offset:192
	v_or_b32_e32 v78, s75, v235
	v_or_b32_e32 v102, v102, v78
	s_waitcnt lgkmcnt(2)
	v_add_f32_e32 v70, v70, v76
	v_mul_f32_e32 v70, 0xbfb8aa3b, v70
	v_exp_f32_e32 v70, v70
	v_add_f32_e32 v66, v66, v77
	v_mul_f32_e32 v66, 0xbfb8aa3b, v66
	v_exp_f32_e32 v66, v66
	v_add_f32_e32 v70, 1.0, v70
	v_rcp_f32_e32 v70, v70
	v_add_f32_e32 v67, v67, v77
	v_add_f32_e32 v66, 1.0, v66
	v_rcp_f32_e32 v66, v66
	v_mul_f32_e32 v70, 0xc1000000, v70
	s_waitcnt lgkmcnt(1)
	v_mul_f32_e32 v70, v79, v70
	v_mul_f32_e32 v70, 0x3fb8aa3b, v70
	v_exp_f32_e32 v70, v70
	v_mul_f32_e32 v67, 0xbfb8aa3b, v67
	v_exp_f32_e32 v67, v67
	v_or_b32_e32 v100, v100, v78
	v_fma_f32 v75, -v70, v70, 1.0
	v_max_f32_e32 v75, 0, v75
	s_nop 0
	s_nop 0
	v_add_f32_e32 v67, 1.0, v67
	s_nop 0
	s_nop 0
	v_rcp_f32_e32 v67, v67
	v_add_f32_e32 v68, v68, v77
	v_mul_f32_e32 v68, 0xbfb8aa3b, v68
	s_nop 0
	s_nop 0
	s_nop 0
	s_nop 0
	v_exp_f32_e32 v68, v68
	s_nop 0
	s_nop 0
	s_nop 0
	v_add_f32_e32 v68, 1.0, v68
	v_rcp_f32_e32 v68, v68
	s_nop 0
	s_nop 0
	s_nop 0
	s_nop 0
	v_or_b32_e32 v104, v104, v78
	v_or_b32_e32 v96, v96, v78
	v_sqrt_f32_e32 v75, v75
	s_nop 0
	global_load_dword v80, v[106:107], off offset:192
	v_mul_f32_e32 v66, v66, v75
	s_waitcnt lgkmcnt(0)
	v_mul_f32_e32 v66, v74, v66
	v_lshlrev_b64 v[74:75], 1, v[102:103]
	s_waitcnt vmcnt(0)
	v_fmac_f32_e32 v66, v80, v70
	v_cvt_pk_bf16_f32 v70, v66, v1
	v_lshl_add_u64 v[80:81], s[62:63], 0, v[74:75]
	global_store_short v[80:81], v70, off
	v_add_f32_e32 v70, v71, v76
	v_mul_f32_e32 v70, 0xbfb8aa3b, v70
	v_exp_f32_e32 v70, v70
	v_lshl_add_u64 v[74:75], s[64:65], 0, v[74:75]
	global_store_short v[74:75], v1, off
	v_lshlrev_b32_e32 v74, 2, v78
	v_add_f32_e32 v70, 1.0, v70
	v_rcp_f32_e32 v70, v70
	v_mov_b32_e32 v75, v1
	v_lshl_add_u64 v[80:81], v[98:99], 0, v[74:75]
	global_store_dword v[80:81], v66, off
	v_mul_f32_e32 v70, 0xc1000000, v70
	v_mul_f32_e32 v70, v79, v70
	v_mul_f32_e32 v70, 0x3fb8aa3b, v70
	v_exp_f32_e32 v70, v70
	ds_read_b32 v66, v241 offset:464
	v_fma_f32 v71, -v70, v70, 1.0
	v_max_f32_e32 v71, 0, v71
	s_nop 0
	s_nop 0
	s_nop 0
	s_nop 0
	s_nop 0
	s_nop 0
	s_nop 0
	s_nop 0
	s_nop 0
	s_nop 0
	s_nop 0
	s_nop 0
	s_nop 0
	s_nop 0
	s_nop 1
	s_nop 0
	s_nop 0
	s_nop 0
	s_nop 0
	s_nop 1
	v_sqrt_f32_e32 v71, v71
	s_nop 0
	global_load_dword v80, v[82:83], off offset:192
	v_mul_f32_e32 v67, v67, v71
	s_waitcnt lgkmcnt(0)
	v_mul_f32_e32 v81, v66, v67
	v_lshlrev_b64 v[66:67], 1, v[100:101]
	s_waitcnt vmcnt(0)
	v_fmac_f32_e32 v81, v70, v80
	v_lshl_add_u64 v[70:71], s[62:63], 0, v[66:67]
	v_lshl_add_u64 v[66:67], s[64:65], 0, v[66:67]
	v_cvt_pk_bf16_f32 v80, v81, v1
	global_store_short v[66:67], v1, off
	v_lshl_add_u64 v[66:67], v[90:91], 0, v[74:75]
	global_store_dword v[66:67], v81, off
	v_add_f32_e32 v67, v72, v76
	v_mul_f32_e32 v67, 0xbfb8aa3b, v67
	v_exp_f32_e32 v67, v67
	global_store_short v[70:71], v80, off
	ds_read_b32 v66, v241 offset:736
	v_add_f32_e32 v67, 1.0, v67
	v_rcp_f32_e32 v67, v67
	s_nop 0
	v_mul_f32_e32 v67, 0xc1000000, v67
	v_mul_f32_e32 v67, v79, v67
	v_mul_f32_e32 v67, 0x3fb8aa3b, v67
	v_exp_f32_e32 v67, v67
	s_nop 0
	v_fma_f32 v70, -v67, v67, 1.0
	v_max_f32_e32 v70, 0, v70
	s_nop 0
	s_nop 0
	s_nop 0
	s_nop 0
	s_nop 0
	s_nop 0
	s_nop 0
	s_nop 0
	s_nop 0
	s_nop 0
	s_nop 0
	s_nop 0
	s_nop 0
	s_nop 0
	s_nop 1
	s_nop 0
	s_nop 0
	s_nop 0
	s_nop 0
	s_nop 1
	v_sqrt_f32_e32 v70, v70
	s_nop 0
	global_load_dword v71, v[86:87], off offset:192
	s_waitcnt vmcnt(0)
	v_mul_f32_e32 v72, v67, v71
	v_mul_f32_e32 v67, v68, v70
	s_waitcnt lgkmcnt(0)
	v_fmac_f32_e32 v72, v67, v66
	v_lshlrev_b64 v[66:67], 1, v[104:105]
	v_lshl_add_u64 v[70:71], s[62:63], 0, v[66:67]
	v_lshl_add_u64 v[66:67], s[64:65], 0, v[66:67]
	v_cvt_pk_bf16_f32 v68, v72, v1
	global_store_short v[66:67], v1, off
	v_lshl_add_u64 v[66:67], v[94:95], 0, v[74:75]
	global_store_dword v[66:67], v72, off
	v_add_f32_e32 v67, v73, v76
	v_mul_f32_e32 v67, 0xbfb8aa3b, v67
	v_exp_f32_e32 v67, v67
	global_store_short v[70:71], v68, off
	v_add_f32_e32 v68, v69, v77
	v_mul_f32_e32 v68, 0xbfb8aa3b, v68
	v_add_f32_e32 v67, 1.0, v67
	v_rcp_f32_e32 v67, v67
	v_exp_f32_e32 v68, v68
	ds_read_b32 v66, v241 offset:1008
	v_mul_f32_e32 v67, 0xc1000000, v67
	v_mul_f32_e32 v67, v79, v67
	v_mul_f32_e32 v67, 0x3fb8aa3b, v67
	v_exp_f32_e32 v67, v67
	v_add_f32_e32 v68, 1.0, v68
	v_rcp_f32_e32 v68, v68
	v_fma_f32 v69, -v67, v67, 1.0
	v_max_f32_e32 v69, 0, v69
	s_nop 0
	s_nop 0
	s_nop 0
	s_nop 0
	s_nop 0
	s_nop 0
	s_nop 0
	s_nop 0
	s_nop 0
	s_nop 0
	s_nop 0
	s_nop 0
	s_nop 0
	s_nop 0
	s_nop 1
	s_nop 0
	s_nop 0
	s_nop 0
	s_nop 0
	s_nop 1
	v_sqrt_f32_e32 v69, v69
	s_nop 0
	global_load_dword v70, v[84:85], off offset:192
	s_waitcnt vmcnt(0)
	v_mul_f32_e32 v70, v67, v70
	v_mul_f32_e32 v67, v68, v69
	s_waitcnt lgkmcnt(0)
	v_fmac_f32_e32 v70, v67, v66
	v_lshlrev_b64 v[66:67], 1, v[96:97]
	v_lshl_add_u64 v[68:69], s[62:63], 0, v[66:67]
	v_lshl_add_u64 v[66:67], s[64:65], 0, v[66:67]
	v_cvt_pk_bf16_f32 v71, v70, v1
	global_store_short v[66:67], v1, off
	v_lshl_add_u64 v[66:67], v[92:93], 0, v[74:75]
	global_store_short v[68:69], v71, off
	global_store_dword v[66:67], v70, off
	s_cbranch_execnz .LBB0_330
	s_branch .LBB0_334

; #define LAS __attribute__((address_space(3)))
; #define LDS_WAIT() asm volatile("s_waitcnt lgkmcnt(0)" ::: "memory")
; template <int NT> ...
;     ...
;     for (int u = 0; u < NT; ++u) { const int m = m0 + 16 * u + rr, t = m - b * TP;
; #pragma unroll
;         for (int k = 0; k < 4; ++k) {
;             if (t - 3 + k >= 0) { const bf16_t* src = P + (size_t)(m - 3 + k) * DP + C_XR + hc0 + cl; raw[u][k][0] = *(const u32x4*)src; raw[u][k][1] = *(const u32x4*)(src + 8); }
;             else { raw[u][k][0] = (u32x4){0u, 0u, 0u, 0u}; raw[u][k][1] = (u32x4){0u, 0u, 0u, 0u}; } } }
;     LDS_WAIT();
; #pragma unroll
;     for (int u = 0; u < NT; ++u) { const int m = m0 + 16 * u + rr, t = m - b * TP; LAS float* XC = XCb + u * (16 * 68);
;         float xv[4][16];
; #pragma unroll
;         for (int k = 0; k < 4; ++k) { float f0[8], f1[8]; unpack8(raw[u][k][0], f0); unpack8(raw[u][k][1], f1);
; #pragma unroll
;             for (int e = 0; e < 8; ++e) { xv[k][e] = f0[e]; xv[k][8 + e] = f1[e]; } }
;         if (t >= TP - 3) { float* o = p->out + O_PCB + ((size_t)(l * NB + b) * 3 + (t - (TP - 3))) * D + hc0 + cl;
; #pragma unroll
;             for (int e = 0; e < 16; e += 4) *(f32x4*)(o + e) = (f32x4){xv[3][e], xv[3][e + 1], xv[3][e + 2], xv[3][e + 3]}; }
; #pragma unroll
;         for (int e = 0; e < 16; e += 4) {
;             const f32x4 w0 = *(const LAS f32x4*)(CST + 0 * 64 + cl + e), w1 = *(const LAS f32x4*)(CST + 1 * 64 + cl + e), w2 = *(const LAS f32x4*)(CST + 2 * 64 + cl + e),
;                         w3 = *(const LAS f32x4*)(CST + 3 * 64 + cl + e), bb = *(const LAS f32x4*)(CST + 4 * 64 + cl + e);
;             f32x4 r;
; #pragma unroll
;             for (int q = 0; q < 4; ++q) r[q] = w0[q] * xv[0][e + q] + w1[q] * xv[1][e + q] + w2[q] * xv[2][e + q] + w3[q] * xv[3][e + q] + bb[q];
;             *(LAS f32x4*)(XC + rr * 68 + cl + e) = r;
;         } }
.LBB0_335:
	s_or_b64 exec, exec, s[10:11]
	v_mov_b64_e32 v[84:85], s[60:61]
	v_mad_i64_i32 v[86:87], s[10:11], v82, s33, v[84:85]
	s_lshl_b32 s16, s75, 1
	v_lshl_add_u64 v[86:87], v[86:87], 0, s[16:17]
	v_lshl_add_u64 v[86:87], v[86:87], 0, v[0:1]
	v_add_co_u32_e32 v88, vcc, s38, v86
	v_add_u32_e32 v83, 13, v82
	s_nop 0
	v_addc_co_u32_e32 v89, vcc, 0, v87, vcc
	global_load_dwordx4 v[170:173], v[88:89], off
	v_lshl_add_u64 v[86:87], v[86:87], 0, s[28:29]
	global_load_dwordx4 v[136:139], v[86:87], off offset:16
	v_add_u32_e32 v92, 16, v82
	v_add_u32_e32 v88, 14, v82
	v_add_u32_e32 v90, 15, v82
	v_mad_i64_i32 v[82:83], s[10:11], v83, s33, v[84:85]
	v_lshl_add_u64 v[82:83], v[82:83], 0, s[16:17]
	v_mad_i64_i32 v[88:89], s[10:11], v88, s33, v[84:85]
	v_lshl_add_u64 v[82:83], v[82:83], 0, v[0:1]
	v_mad_i64_i32 v[90:91], s[10:11], v90, s33, v[84:85]
	v_mad_i64_i32 v[84:85], s[10:11], v92, s33, v[84:85]
	v_lshl_add_u64 v[88:89], v[88:89], 0, s[16:17]
	v_lshl_add_u64 v[92:93], v[82:83], 0, s[28:29]
	v_add_co_u32_e32 v82, vcc, s38, v82
	v_lshl_add_u64 v[88:89], v[88:89], 0, v[0:1]
	s_nop 0
	v_addc_co_u32_e32 v83, vcc, 0, v83, vcc
	v_lshl_add_u64 v[90:91], v[90:91], 0, s[16:17]
	v_add_co_u32_e32 v86, vcc, s38, v88
	v_lshl_add_u64 v[90:91], v[90:91], 0, v[0:1]
	s_nop 0
	v_addc_co_u32_e32 v87, vcc, 0, v89, vcc
	v_lshl_add_u64 v[84:85], v[84:85], 0, s[16:17]
	v_lshl_add_u64 v[96:97], v[90:91], 0, s[28:29]
	v_add_co_u32_e32 v90, vcc, s38, v90
	v_lshl_add_u64 v[84:85], v[84:85], 0, v[0:1]
	s_nop 0
	v_addc_co_u32_e32 v91, vcc, 0, v91, vcc
	v_add_co_u32_e32 v118, vcc, s38, v84
	v_lshl_add_u64 v[94:95], v[88:89], 0, s[28:29]
	s_nop 0
	v_addc_co_u32_e32 v119, vcc, 0, v85, vcc
	s_waitcnt vmcnt(3)
	v_lshlrev_b32_e32 v154, 16, v120
	v_and_b32_e32 v155, 0xffff0000, v120
	v_lshlrev_b32_e32 v158, 16, v121
	v_and_b32_e32 v159, 0xffff0000, v121
	v_lshl_add_u64 v[128:129], v[84:85], 0, s[28:29]
	global_load_dwordx4 v[106:109], v[82:83], off
	s_nop 0
	global_load_dwordx4 v[82:85], v[92:93], off offset:16
	global_load_dwordx4 v[110:113], v[86:87], off
	s_nop 0
	global_load_dwordx4 v[86:89], v[94:95], off offset:16
	global_load_dwordx4 v[114:117], v[90:91], off
	s_nop 0
	global_load_dwordx4 v[90:93], v[96:97], off offset:16
	s_nop 0
	global_load_dwordx4 v[118:121], v[118:119], off
	s_nop 0
	global_load_dwordx4 v[94:97], v[128:129], off offset:16
	s_waitcnt lgkmcnt(0)
	ds_read_b128 v[128:131], v227 offset:8704
	ds_read_b128 v[132:135], v227 offset:8960
	ds_read_b128 v[140:143], v227 offset:9216
	ds_read_b128 v[144:147], v227 offset:9472
	ds_read_b128 v[148:151], v227 offset:9728
	v_lshlrev_b32_e32 v156, 16, v102
	v_and_b32_e32 v157, 0xffff0000, v102
	v_lshlrev_b32_e32 v152, 16, v124
	s_waitcnt lgkmcnt(3)
	v_pk_mul_f32 v[154:155], v[132:133], v[154:155]
	v_and_b32_e32 v153, 0xffff0000, v124
	v_pk_fma_f32 v[154:155], v[128:129], v[156:157], v[154:155]
	v_lshlrev_b32_e32 v102, 16, v103
	s_waitcnt lgkmcnt(2)
	v_pk_fma_f32 v[152:153], v[140:141], v[152:153], v[154:155]
	v_and_b32_e32 v103, 0xffff0000, v103
	v_lshlrev_b32_e32 v124, 16, v125
	v_and_b32_e32 v125, 0xffff0000, v125
	v_lshlrev_b32_e32 v174, 16, v122
	v_and_b32_e32 v175, 0xffff0000, v122
	v_lshlrev_b32_e32 v176, 16, v104
	v_and_b32_e32 v177, 0xffff0000, v104
	v_lshlrev_b32_e32 v122, 16, v123
	v_and_b32_e32 v123, 0xffff0000, v123
	v_lshlrev_b32_e32 v104, 16, v105
	v_and_b32_e32 v105, 0xffff0000, v105
	s_waitcnt vmcnt(10)
	v_lshlrev_b32_e32 v186, 16, v78
	v_and_b32_e32 v187, 0xffff0000, v78
	v_lshlrev_b32_e32 v188, 16, v74
	v_and_b32_e32 v189, 0xffff0000, v74
	v_lshlrev_b32_e32 v184, 16, v98
	v_and_b32_e32 v185, 0xffff0000, v98
	v_lshlrev_b32_e32 v78, 16, v79
	v_and_b32_e32 v79, 0xffff0000, v79
	v_lshlrev_b32_e32 v74, 16, v75
	v_and_b32_e32 v75, 0xffff0000, v75
	v_lshlrev_b32_e32 v98, 16, v99
	s_waitcnt vmcnt(9)
	v_lshlrev_b32_e32 v154, 16, v170
	v_and_b32_e32 v155, 0xffff0000, v170
	s_waitcnt lgkmcnt(1)
	v_pk_fma_f32 v[152:153], v[144:145], v[154:155], v[152:153]
	v_pk_mul_f32 v[154:155], v[134:135], v[158:159]
	v_lshlrev_b32_e32 v156, 16, v171
	v_pk_fma_f32 v[102:103], v[130:131], v[102:103], v[154:155]
	v_and_b32_e32 v157, 0xffff0000, v171
	v_pk_fma_f32 v[102:103], v[142:143], v[124:125], v[102:103]
	s_waitcnt lgkmcnt(0)
	v_pk_add_f32 v[152:153], v[148:149], v[152:153]
	v_pk_fma_f32 v[102:103], v[146:147], v[156:157], v[102:103]
	v_lshlrev_b32_e32 v124, 16, v126
	v_pk_add_f32 v[154:155], v[150:151], v[102:103]
	ds_write_b128 v240, v[152:155]
	ds_read_b128 v[152:155], v227 offset:8720
	ds_read_b128 v[168:171], v227 offset:8976
	ds_read_b128 v[156:159], v227 offset:9232
	ds_read_b128 v[160:163], v227 offset:9488
	ds_read_b128 v[164:167], v227 offset:9744
	v_and_b32_e32 v125, 0xffff0000, v126
	s_waitcnt lgkmcnt(3)
	v_pk_mul_f32 v[174:175], v[168:169], v[174:175]
	v_pk_mul_f32 v[122:123], v[170:171], v[122:123]
	v_pk_fma_f32 v[174:175], v[152:153], v[176:177], v[174:175]
	v_lshlrev_b32_e32 v102, 16, v172
	v_and_b32_e32 v103, 0xffff0000, v172
	s_waitcnt lgkmcnt(2)
	v_pk_fma_f32 v[124:125], v[156:157], v[124:125], v[174:175]
	v_lshlrev_b32_e32 v126, 16, v127
	v_and_b32_e32 v127, 0xffff0000, v127
	v_pk_fma_f32 v[104:105], v[154:155], v[104:105], v[122:123]
	s_waitcnt lgkmcnt(1)
	v_pk_fma_f32 v[102:103], v[160:161], v[102:103], v[124:125]
	v_lshlrev_b32_e32 v124, 16, v173
	v_and_b32_e32 v125, 0xffff0000, v173
	v_pk_fma_f32 v[104:105], v[158:159], v[126:127], v[104:105]
	s_waitcnt lgkmcnt(0)
	v_pk_add_f32 v[102:103], v[164:165], v[102:103]
	v_pk_fma_f32 v[104:105], v[162:163], v[124:125], v[104:105]
	s_waitcnt vmcnt(8)
; #define LAS __attribute__((address_space(3)))
; template <int NT> ...
;     ...
;     for (int u = 0; u < NT; ++u) { const int m = m0 + 16 * u + rr, t = m - b * TP; LAS float* XC = XCb + u * (16 * 68);
;         float xv[4][16];
; #pragma unroll
;         for (int k = 0; k < 4; ++k) { float f0[8], f1[8]; unpack8(raw[u][k][0], f0); unpack8(raw[u][k][1], f1);
; #pragma unroll
;             for (int e = 0; e < 8; ++e) { xv[k][e] = f0[e]; xv[k][8 + e] = f1[e]; } }
;         if (t >= TP - 3) { float* o = p->out + O_PCB + ((size_t)(l * NB + b) * 3 + (t - (TP - 3))) * D + hc0 + cl;
; #pragma unroll
;             for (int e = 0; e < 16; e += 4) *(f32x4*)(o + e) = (f32x4){xv[3][e], xv[3][e + 1], xv[3][e + 2], xv[3][e + 3]}; }
; #pragma unroll
;         for (int e = 0; e < 16; e += 4) {
;             const f32x4 w0 = *(const LAS f32x4*)(CST + 0 * 64 + cl + e), w1 = *(const LAS f32x4*)(CST + 1 * 64 + cl + e), w2 = *(const LAS f32x4*)(CST + 2 * 64 + cl + e),
;                         w3 = *(const LAS f32x4*)(CST + 3 * 64 + cl + e), bb = *(const LAS f32x4*)(CST + 4 * 64 + cl + e);
;             f32x4 r;
; #pragma unroll
;             for (int q = 0; q < 4; ++q) r[q] = w0[q] * xv[0][e + q] + w1[q] * xv[1][e + q] + w2[q] * xv[2][e + q] + w3[q] * xv[3][e + q] + bb[q];
;             *(LAS f32x4*)(XC + rr * 68 + cl + e) = r;
;         } }
	v_lshlrev_b32_e32 v126, 16, v136
	v_pk_add_f32 v[104:105], v[166:167], v[104:105]
	ds_write_b128 v240, v[102:105] offset:16
	ds_read_b128 v[102:105], v227 offset:8736
	ds_read_b128 v[180:183], v227 offset:8992
	ds_read_b128 v[122:125], v227 offset:9248
	ds_read_b128 v[172:175], v227 offset:9504
	ds_read_b128 v[176:179], v227 offset:9760
	v_and_b32_e32 v127, 0xffff0000, v136
	s_waitcnt lgkmcnt(3)
	v_pk_mul_f32 v[186:187], v[180:181], v[186:187]
	v_pk_mul_f32 v[78:79], v[182:183], v[78:79]
	v_pk_fma_f32 v[186:187], v[102:103], v[188:189], v[186:187]
	v_and_b32_e32 v99, 0xffff0000, v99
	s_waitcnt lgkmcnt(2)
	v_pk_fma_f32 v[184:185], v[122:123], v[184:185], v[186:187]
	v_pk_fma_f32 v[74:75], v[104:105], v[74:75], v[78:79]
	s_waitcnt lgkmcnt(1)
	v_pk_fma_f32 v[126:127], v[172:173], v[126:127], v[184:185]
	v_pk_fma_f32 v[74:75], v[124:125], v[98:99], v[74:75]
	s_waitcnt lgkmcnt(0)
	v_pk_add_f32 v[184:185], v[176:177], v[126:127]
	v_lshlrev_b32_e32 v126, 16, v137
	v_and_b32_e32 v127, 0xffff0000, v137
	v_pk_fma_f32 v[74:75], v[174:175], v[126:127], v[74:75]
	v_lshlrev_b32_e32 v78, 16, v76
	v_pk_add_f32 v[186:187], v[178:179], v[74:75]
	ds_write_b128 v240, v[184:187] offset:32
	ds_read_b128 v[184:187], v227 offset:8752
	ds_read_b128 v[200:203], v227 offset:9008
	ds_read_b128 v[188:191], v227 offset:9264
	ds_read_b128 v[192:195], v227 offset:9520
	ds_read_b128 v[196:199], v227 offset:9776
	v_lshlrev_b32_e32 v74, 16, v80
	v_and_b32_e32 v75, 0xffff0000, v80
	v_and_b32_e32 v79, 0xffff0000, v76
	s_waitcnt lgkmcnt(3)
	v_pk_mul_f32 v[74:75], v[200:201], v[74:75]
	v_lshlrev_b32_e32 v80, 16, v81
	v_and_b32_e32 v81, 0xffff0000, v81
	v_pk_fma_f32 v[74:75], v[184:185], v[78:79], v[74:75]
	v_lshlrev_b32_e32 v78, 16, v100
	v_and_b32_e32 v79, 0xffff0000, v100
	v_lshlrev_b32_e32 v76, 16, v77
	v_and_b32_e32 v77, 0xffff0000, v77
	v_pk_mul_f32 v[80:81], v[202:203], v[80:81]
	s_waitcnt lgkmcnt(2)
	v_pk_fma_f32 v[74:75], v[188:189], v[78:79], v[74:75]
	v_lshlrev_b32_e32 v78, 16, v138
	v_and_b32_e32 v79, 0xffff0000, v138
	v_lshlrev_b32_e32 v98, 16, v101
	v_and_b32_e32 v99, 0xffff0000, v101
	v_pk_fma_f32 v[76:77], v[186:187], v[76:77], v[80:81]
	s_waitcnt lgkmcnt(1)
	v_pk_fma_f32 v[74:75], v[192:193], v[78:79], v[74:75]
	v_lshlrev_b32_e32 v78, 16, v139
	v_and_b32_e32 v79, 0xffff0000, v139
	v_pk_fma_f32 v[76:77], v[190:191], v[98:99], v[76:77]
	s_waitcnt vmcnt(7)
	v_lshlrev_b32_e32 v80, 16, v106
	v_pk_fma_f32 v[76:77], v[194:195], v[78:79], v[76:77]
	s_waitcnt vmcnt(5)
	v_lshlrev_b32_e32 v78, 16, v110
	v_and_b32_e32 v79, 0xffff0000, v110
	v_and_b32_e32 v81, 0xffff0000, v106
	v_pk_mul_f32 v[78:79], v[132:133], v[78:79]
	s_waitcnt lgkmcnt(0)
	v_pk_add_f32 v[74:75], v[196:197], v[74:75]
	v_pk_add_f32 v[76:77], v[198:199], v[76:77]
	v_pk_fma_f32 v[78:79], v[128:129], v[80:81], v[78:79]
	v_lshlrev_b32_e32 v80, 16, v111
	v_and_b32_e32 v81, 0xffff0000, v111
	ds_write_b128 v240, v[74:77] offset:48
	s_waitcnt vmcnt(3)
	v_lshlrev_b32_e32 v76, 16, v114
	v_and_b32_e32 v77, 0xffff0000, v114
	v_lshlrev_b32_e32 v98, 16, v107
	v_and_b32_e32 v99, 0xffff0000, v107
	v_pk_mul_f32 v[80:81], v[134:135], v[80:81]
	s_waitcnt vmcnt(1)
	v_lshlrev_b32_e32 v74, 16, v118
	v_and_b32_e32 v75, 0xffff0000, v118
	v_pk_fma_f32 v[76:77], v[140:141], v[76:77], v[78:79]
	v_lshlrev_b32_e32 v78, 16, v115
	v_and_b32_e32 v79, 0xffff0000, v115
	v_pk_fma_f32 v[80:81], v[130:131], v[98:99], v[80:81]
	v_pk_fma_f32 v[74:75], v[144:145], v[74:75], v[76:77]
	v_lshlrev_b32_e32 v76, 16, v119
	v_and_b32_e32 v77, 0xffff0000, v119
	v_pk_fma_f32 v[78:79], v[142:143], v[78:79], v[80:81]
	v_lshlrev_b32_e32 v80, 16, v108
	v_pk_fma_f32 v[76:77], v[146:147], v[76:77], v[78:79]
	v_lshlrev_b32_e32 v78, 16, v112
	v_and_b32_e32 v79, 0xffff0000, v112
	v_and_b32_e32 v81, 0xffff0000, v108
	v_pk_mul_f32 v[78:79], v[168:169], v[78:79]
	v_pk_add_f32 v[74:75], v[148:149], v[74:75]
	v_pk_add_f32 v[76:77], v[150:151], v[76:77]
	v_pk_fma_f32 v[78:79], v[152:153], v[80:81], v[78:79]
	v_lshlrev_b32_e32 v80, 16, v113
	v_and_b32_e32 v81, 0xffff0000, v113
	ds_write_b128 v240, v[74:77] offset:4352
	v_lshlrev_b32_e32 v76, 16, v116
	v_and_b32_e32 v77, 0xffff0000, v116
	v_lshlrev_b32_e32 v98, 16, v109
	v_and_b32_e32 v99, 0xffff0000, v109
	v_pk_mul_f32 v[80:81], v[170:171], v[80:81]
	v_lshlrev_b32_e32 v74, 16, v120
	v_and_b32_e32 v75, 0xffff0000, v120
	v_pk_fma_f32 v[76:77], v[156:157], v[76:77], v[78:79]
	v_lshlrev_b32_e32 v78, 16, v117
	v_and_b32_e32 v79, 0xffff0000, v117
	v_pk_fma_f32 v[80:81], v[154:155], v[98:99], v[80:81]
	v_pk_fma_f32 v[74:75], v[160:161], v[74:75], v[76:77]
	v_lshlrev_b32_e32 v76, 16, v121
	v_and_b32_e32 v77, 0xffff0000, v121
	v_pk_fma_f32 v[78:79], v[158:159], v[78:79], v[80:81]
	v_lshlrev_b32_e32 v80, 16, v82
	v_pk_fma_f32 v[76:77], v[162:163], v[76:77], v[78:79]
	v_lshlrev_b32_e32 v78, 16, v86
	v_and_b32_e32 v79, 0xffff0000, v86
	v_and_b32_e32 v81, 0xffff0000, v82
	v_pk_mul_f32 v[78:79], v[180:181], v[78:79]
	v_pk_add_f32 v[74:75], v[164:165], v[74:75]
	v_pk_add_f32 v[76:77], v[166:167], v[76:77]
	v_pk_fma_f32 v[78:79], v[102:103], v[80:81], v[78:79]
	v_lshlrev_b32_e32 v80, 16, v87
	v_and_b32_e32 v81, 0xffff0000, v87
	ds_write_b128 v240, v[74:77] offset:4368
	v_lshlrev_b32_e32 v76, 16, v90
	v_and_b32_e32 v77, 0xffff0000, v90
	v_lshlrev_b32_e32 v82, 16, v83
	v_and_b32_e32 v83, 0xffff0000, v83
	v_pk_mul_f32 v[80:81], v[182:183], v[80:81]
	s_waitcnt vmcnt(0)
; #define LAS __attribute__((address_space(3)))
; __device__ __forceinline__ unsigned cvt_pk_bf16(float lo, float hi) { unsigned r; asm volatile("v_cvt_pk_bf16_f32 %0, %1, %2" : "=v"(r) : "v"(lo), "v"(hi)); return r; }
; __device__ __forceinline__ float sigmoidf_(float x) { return __builtin_amdgcn_rcpf(1.0f + __expf(-x)); }
; #define LDS_WAIT() asm volatile("s_waitcnt lgkmcnt(0)" ::: "memory")
; template <int NT> ...
;     ...
;             for (int q = 0; q < 4; ++q) r[q] = w0[q] * xv[0][e + q] + w1[q] * xv[1][e + q] + w2[q] * xv[2][e + q] + w3[q] * xv[3][e + q] + bb[q];
;             *(LAS f32x4*)(XC + rr * 68 + cl + e) = r;
;         } }
;     LDS_WAIT();
;     f32x4 ar[NT][4], ai[NT][4];
; #pragma unroll
;     for (int u = 0; u < NT; ++u) { const LAS float* XC = XCb + u * (16 * 68);
; #pragma unroll
;         for (int n = 0; n < 4; ++n) { ar[u][n] = (f32x4){0.f, 0.f, 0.f, 0.f}; ai[u][n] = (f32x4){0.f, 0.f, 0.f, 0.f}; }
; #pragma unroll
;         for (int s = 0; s < 2; ++s) {
;             const f32x4 x0 = *(const LAS f32x4*)(XC + fr * 68 + 32 * s + 8 * fq), x1 = *(const LAS f32x4*)(XC + fr * 68 + 32 * s + 8 * fq + 4);
;             u32x4 aw; aw.x = cvt_pk_bf16(x0[0], x0[1]); aw.y = cvt_pk_bf16(x0[2], x0[3]); aw.z = cvt_pk_bf16(x1[0], x1[1]); aw.w = cvt_pk_bf16(x1[2], x1[3]);
;             const bf16x8 af = __builtin_bit_cast(bf16x8, aw);
; #pragma unroll
;             for (int n = 0; n < 4; ++n) { ar[u][n] = __builtin_amdgcn_mfma_f32_16x16x32_bf16(af, Wa[n][s], ar[u][n], 0, 0, 0); ai[u][n] = __builtin_amdgcn_mfma_f32_16x16x32_bf16(af, Wx[n][s], ai[u][n], 0, 0, 0); }
;         } }
;     float av[NT][4][4], bv[NT][4][4];
; #pragma unroll
;     for (int u = 0; u < NT; ++u) { const LAS float* XC = XCb + u * (16 * 68); const int t0 = m0 + 16 * u - b * TP;
; #pragma unroll
;         for (int n = 0; n < 4; ++n) { const int cc = 16 * n + fr;
;             const float ba = CST[5 * 64 + cc], bx = CST[6 * 64 + cc], sp = CST[7 * 64 + cc];
; #pragma unroll
;             for (int j = 0; j < 4; ++j) {
;                 const float xc = XC[(4 * fq + j) * 68 + cc];
;                 const float r = sigmoidf_(ar[u][n][j] + ba), ig = sigmoidf_(ai[u][n][j] + bx);
;                 const float a = __expf(-8.0f * r * sp);
	v_lshlrev_b32_e32 v74, 16, v94
	v_and_b32_e32 v75, 0xffff0000, v94
	v_pk_fma_f32 v[76:77], v[122:123], v[76:77], v[78:79]
	v_lshlrev_b32_e32 v78, 16, v91
	v_and_b32_e32 v79, 0xffff0000, v91
	v_pk_fma_f32 v[80:81], v[104:105], v[82:83], v[80:81]
	v_pk_fma_f32 v[74:75], v[172:173], v[74:75], v[76:77]
	v_lshlrev_b32_e32 v76, 16, v95
	v_and_b32_e32 v77, 0xffff0000, v95
	v_pk_fma_f32 v[78:79], v[124:125], v[78:79], v[80:81]
	v_lshlrev_b32_e32 v80, 16, v84
	v_pk_fma_f32 v[76:77], v[174:175], v[76:77], v[78:79]
	v_lshlrev_b32_e32 v78, 16, v88
	v_and_b32_e32 v79, 0xffff0000, v88
	v_and_b32_e32 v81, 0xffff0000, v84
	v_pk_mul_f32 v[78:79], v[200:201], v[78:79]
	v_pk_add_f32 v[74:75], v[176:177], v[74:75]
	v_pk_add_f32 v[76:77], v[178:179], v[76:77]
	v_pk_fma_f32 v[78:79], v[184:185], v[80:81], v[78:79]
	v_lshlrev_b32_e32 v80, 16, v89
	v_and_b32_e32 v81, 0xffff0000, v89
	ds_write_b128 v240, v[74:77] offset:4384
	v_lshlrev_b32_e32 v76, 16, v92
	v_and_b32_e32 v77, 0xffff0000, v92
	v_lshlrev_b32_e32 v82, 16, v85
	v_and_b32_e32 v83, 0xffff0000, v85
	v_pk_mul_f32 v[80:81], v[202:203], v[80:81]
	v_lshlrev_b32_e32 v74, 16, v96
	v_and_b32_e32 v75, 0xffff0000, v96
	v_pk_fma_f32 v[76:77], v[188:189], v[76:77], v[78:79]
	v_lshlrev_b32_e32 v78, 16, v93
	v_and_b32_e32 v79, 0xffff0000, v93
	v_pk_fma_f32 v[80:81], v[186:187], v[82:83], v[80:81]
	v_pk_fma_f32 v[74:75], v[192:193], v[74:75], v[76:77]
	v_lshlrev_b32_e32 v76, 16, v97
	v_and_b32_e32 v77, 0xffff0000, v97
	v_pk_fma_f32 v[78:79], v[190:191], v[78:79], v[80:81]
	v_pk_add_f32 v[74:75], v[196:197], v[74:75]
	v_pk_fma_f32 v[76:77], v[194:195], v[76:77], v[78:79]
	v_add_u32_e32 v177, 0x2400, v232
	v_pk_add_f32 v[76:77], v[198:199], v[76:77]
	ds_write_b128 v240, v[74:77] offset:4400
	s_waitcnt lgkmcnt(0)
	ds_read_b128 v[74:77], v239
	ds_read_b128 v[78:81], v239 offset:16
	s_waitcnt lgkmcnt(1)
	v_cvt_pk_bf16_f32 v74, v74, v75
	v_cvt_pk_bf16_f32 v75, v76, v77
	s_waitcnt lgkmcnt(0)
	v_cvt_pk_bf16_f32 v76, v78, v79
	v_cvt_pk_bf16_f32 v77, v80, v81
	ds_read_b128 v[106:109], v239 offset:128
	ds_read_b128 v[110:113], v239 offset:144
	v_mfma_f32_16x16x32_bf16 v[78:81], v[74:77], v[34:37], 0
	s_waitcnt lgkmcnt(1)
	v_cvt_pk_bf16_f32 v106, v106, v107
	v_mfma_f32_16x16x32_bf16 v[82:85], v[74:77], v[38:41], 0
	v_cvt_pk_bf16_f32 v107, v108, v109
	s_waitcnt lgkmcnt(0)
	v_cvt_pk_bf16_f32 v108, v110, v111
	v_cvt_pk_bf16_f32 v109, v112, v113
	v_mfma_f32_16x16x32_bf16 v[86:89], v[74:77], v[42:45], 0
	v_add_u32_e32 v176, 0x2800, v232
	s_add_i32 s21, s21, 2
	v_add_u32_e32 v243, 32, v243
	v_mfma_f32_16x16x32_bf16 v[132:135], v[106:109], v[10:13], v[78:81]
	s_cmp_gt_u32 s21, 5
	v_subrev_u32_e32 v244, 32, v244
	v_mfma_f32_16x16x32_bf16 v[140:143], v[106:109], v[14:17], v[82:85]
	ds_read_b128 v[78:81], v239 offset:4352
	s_nop 1
	ds_read_b128 v[82:85], v239 offset:4368
	v_mfma_f32_16x16x32_bf16 v[90:93], v[74:77], v[46:49], 0
	v_mfma_f32_16x16x32_bf16 v[94:97], v[74:77], v[50:53], 0
	v_mfma_f32_16x16x32_bf16 v[98:101], v[74:77], v[54:57], 0
	v_mfma_f32_16x16x32_bf16 v[102:105], v[74:77], v[62:65], 0
	v_mfma_f32_16x16x32_bf16 v[74:77], v[74:77], v[58:61], 0
	v_mfma_f32_16x16x32_bf16 v[126:129], v[106:109], v[22:25], v[86:89]
	v_mfma_f32_16x16x32_bf16 v[122:125], v[106:109], v[26:29], v[90:93]
	v_mfma_f32_16x16x32_bf16 v[118:121], v[106:109], v[30:33], v[94:97]
	v_mfma_f32_16x16x32_bf16 v[114:117], v[106:109], v[18:21], v[98:101]
	v_mfma_f32_16x16x32_bf16 v[110:113], v[106:109], v[6:9], v[102:105]
	v_mfma_f32_16x16x32_bf16 v[106:109], v[106:109], v[2:5], v[74:77]
	s_waitcnt lgkmcnt(1)
	v_cvt_pk_bf16_f32 v74, v78, v79
	v_cvt_pk_bf16_f32 v75, v80, v81
	s_waitcnt lgkmcnt(0)
	v_cvt_pk_bf16_f32 v76, v82, v83
	v_cvt_pk_bf16_f32 v77, v84, v85
	ds_read_b128 v[94:97], v239 offset:4480
	ds_read_b128 v[98:101], v239 offset:4496
	s_waitcnt lgkmcnt(1)
	v_cvt_pk_bf16_f32 v152, v94, v95
	v_cvt_pk_bf16_f32 v153, v96, v97
	s_waitcnt lgkmcnt(0)
	v_cvt_pk_bf16_f32 v154, v98, v99
	v_cvt_pk_bf16_f32 v155, v100, v101
	ds_read2_b32 v[168:169], v177 offset0:192 offset1:208
	v_mfma_f32_16x16x32_bf16 v[78:81], v[74:77], v[34:37], 0
	ds_read2_b32 v[164:165], v176 offset0:64 offset1:80
	ds_read2_b32 v[166:167], v176 offset1:16
	ds_read2_b32 v[156:157], v177 offset0:224 offset1:240
	v_mfma_f32_16x16x32_bf16 v[102:105], v[152:155], v[10:13], v[78:81]
	s_waitcnt lgkmcnt(3)
	v_add_f32_e32 v133, v133, v168
	v_mul_f32_e32 v133, 0xbfb8aa3b, v133
	v_exp_f32_e32 v133, v133
	v_add_f32_e32 v78, v132, v168
	v_mul_f32_e32 v78, 0xbfb8aa3b, v78
	v_exp_f32_e32 v130, v78
	v_mfma_f32_16x16x32_bf16 v[82:85], v[74:77], v[38:41], 0
	v_add_f32_e32 v133, 1.0, v133
	v_add_f32_e32 v134, v134, v168
	v_add_f32_e32 v130, 1.0, v130
	v_rcp_f32_e32 v130, v130
	v_mfma_f32_16x16x32_bf16 v[144:147], v[74:77], v[54:57], 0
	v_mul_f32_e32 v134, 0xbfb8aa3b, v134
	v_exp_f32_e32 v134, v134
	v_mul_f32_e32 v130, 0xc1000000, v130
	s_waitcnt lgkmcnt(2)
	v_mul_f32_e32 v130, v164, v130
	v_mul_f32_e32 v130, 0x3fb8aa3b, v130
	v_mfma_f32_16x16x32_bf16 v[98:101], v[152:155], v[14:17], v[82:85]
	v_add_f32_e32 v135, v135, v168
	v_mul_f32_e32 v135, 0xbfb8aa3b, v135
	v_exp_f32_e32 v135, v135
	v_mfma_f32_16x16x32_bf16 v[82:85], v[152:155], v[18:21], v[144:147]
	v_add_f32_e32 v126, v126, v169
	v_mul_f32_e32 v126, 0xbfb8aa3b, v126
	v_add_f32_e32 v135, 1.0, v135
	v_exp_f32_e32 v146, v130
	v_mfma_f32_16x16x32_bf16 v[86:89], v[74:77], v[42:45], 0
	s_waitcnt lgkmcnt(1)
; #define LAS __attribute__((address_space(3)))
; __device__ __forceinline__ float sigmoidf_(float x) { return __builtin_amdgcn_rcpf(1.0f + __expf(-x)); }
; template <int NT> ...
;     ...
;     for (int u = 0; u < NT; ++u) { const LAS float* XC = XCb + u * (16 * 68); const int t0 = m0 + 16 * u - b * TP;
; #pragma unroll
;         for (int n = 0; n < 4; ++n) { const int cc = 16 * n + fr;
;             const float ba = CST[5 * 64 + cc], bx = CST[6 * 64 + cc], sp = CST[7 * 64 + cc];
; #pragma unroll
;             for (int j = 0; j < 4; ++j) {
;                 const float xc = XC[(4 * fq + j) * 68 + cc];
;                 const float r = sigmoidf_(ar[u][n][j] + ba), ig = sigmoidf_(ai[u][n][j] + bx);
;                 const float a = __expf(-8.0f * r * sp);
;                 float mult = sqrtf(fmaxf(1.0f - a * a, 0.f));
;                 if (t0 + 4 * fq + j == 0) mult = 1.0f;
;                 av[u][n][j] = a; bv[u][n][j] = mult * ig * xc; } } }
	v_add_f32_e32 v130, v140, v166
	v_mul_f32_e32 v130, 0xbfb8aa3b, v130
	v_fma_f32 v131, -v146, v146, 1.0
	v_mfma_f32_16x16x32_bf16 v[136:139], v[74:77], v[50:53], 0
	v_max_f32_e32 v131, 0, v131
	s_nop 0
	s_nop 0
	v_exp_f32_e32 v130, v130
	v_mfma_f32_16x16x32_bf16 v[94:97], v[152:155], v[22:25], v[86:89]
	v_mov_b32_e32 v132, v131
	ds_read2_b32 v[144:145], v241 offset1:16
	v_add_f32_e32 v130, 1.0, v130
	v_mfma_f32_16x16x32_bf16 v[86:89], v[152:155], v[30:33], v[136:139]
	v_rcp_f32_e32 v131, v130
	v_rcp_f32_e32 v135, v135
	v_exp_f32_e32 v126, v126
	s_nop 0
	v_mfma_f32_16x16x32_bf16 v[148:151], v[74:77], v[62:65], 0
	v_add_f32_e32 v122, v122, v167
	v_add_f32_e32 v126, 1.0, v126
	s_nop 0
	s_nop 0
	s_nop 0
	s_nop 0
	v_rcp_f32_e32 v126, v126
	s_nop 0
	s_nop 0
	s_nop 0
	v_mul_f32_e32 v126, 0xc1000000, v126
	v_mul_f32_e32 v126, v165, v126
	s_nop 0
	s_nop 0
	s_nop 0
	v_rcp_f32_e32 v136, v133
	s_nop 0
	v_mul_f32_e32 v126, 0x3fb8aa3b, v126
	v_mfma_f32_16x16x32_bf16 v[78:81], v[152:155], v[6:9], v[148:151]
	v_sqrt_f32_e32 v130, v132
	s_nop 0
	v_cmp_eq_u32_e32 vcc, s19, v245
	v_mul_f32_e32 v122, 0xbfb8aa3b, v122
	v_exp_f32_e32 v148, v126
	v_cndmask_b32_e64 v133, v130, 1.0, vcc
	v_mul_f32_e32 v130, 0xc1000000, v136
	v_mul_f32_e32 v130, v164, v130
	v_mul_f32_e32 v130, 0x3fb8aa3b, v130
	v_exp_f32_e32 v138, v130
	v_add_f32_e32 v130, v141, v166
	v_mul_f32_e32 v130, 0xbfb8aa3b, v130
	v_exp_f32_e32 v130, v130
	v_fma_f32 v132, -v138, v138, 1.0
	v_max_f32_e32 v132, 0, v132
	s_nop 0
	s_nop 0
	v_add_f32_e32 v130, 1.0, v130
	v_rcp_f32_e32 v130, v130
	s_nop 0
	s_nop 0
	ds_read2_b32 v[136:137], v241 offset0:68 offset1:84
	v_fma_f32 v126, -v148, v148, 1.0
	v_max_f32_e32 v126, 0, v126
	s_nop 0
	s_nop 0
	s_nop 0
	s_nop 0
	v_exp_f32_e32 v122, v122
	s_nop 0
	s_nop 0
	s_nop 0
	v_add_f32_e32 v127, v127, v169
	v_mul_f32_e32 v127, 0xbfb8aa3b, v127
	s_nop 0
	s_nop 0
	s_nop 0
	s_nop 0
	v_add_f32_e32 v122, 1.0, v122
	v_exp_f32_e32 v127, v127
	v_sqrt_f32_e32 v132, v132
	s_nop 0
	v_pk_mul_f32 v[130:131], v[130:131], v[132:133]
	v_add_f32_e32 v132, 1.0, v134
	v_rcp_f32_e32 v134, v132
	s_waitcnt lgkmcnt(0)
	v_mov_b32_e32 v132, v136
	v_mov_b32_e32 v133, v144
	v_pk_mul_f32 v[132:133], v[132:133], v[130:131]
	v_mul_f32_e32 v130, 0xc1000000, v134
	v_mul_f32_e32 v130, v164, v130
	v_mul_f32_e32 v130, 0x3fb8aa3b, v130
	v_exp_f32_e32 v139, v130
	v_add_f32_e32 v130, v142, v166
	v_mul_f32_e32 v130, 0xbfb8aa3b, v130
	v_exp_f32_e32 v134, v130
	v_fma_f32 v130, -v139, v139, 1.0
	v_max_f32_e32 v130, 0, v130
	s_nop 0
	s_nop 0
	v_add_f32_e32 v134, 1.0, v134
	v_rcp_f32_e32 v134, v134
	v_mov_b32_e32 v136, v130
	s_nop 0
	v_rcp_f32_e32 v151, v122
	v_add_f32_e32 v127, 1.0, v127
	v_rcp_f32_e32 v127, v127
	s_nop 0
	s_nop 0
	s_nop 0
	s_nop 0
	v_add_f32_e32 v123, v123, v167
	s_nop 0
	s_nop 0
	s_nop 0
	v_mul_f32_e32 v123, 0xbfb8aa3b, v123
	v_add_f32_e32 v128, v128, v169
	s_nop 0
	s_nop 0
	s_nop 0
	s_nop 0
	v_mul_f32_e32 v128, 0xbfb8aa3b, v128
	v_exp_f32_e32 v128, v128
	v_sqrt_f32_e32 v136, v136
	s_nop 0
	v_mul_f32_e32 v136, v134, v136
	v_mul_f32_e32 v134, 0xc1000000, v135
	v_mul_f32_e32 v134, v164, v134
	v_mul_f32_e32 v134, 0x3fb8aa3b, v134
	v_exp_f32_e32 v141, v134
	v_add_f32_e32 v134, v143, v166
	v_mul_f32_e32 v134, 0xbfb8aa3b, v134
	v_exp_f32_e32 v140, v134
	v_fma_f32 v134, -v141, v141, 1.0
	v_max_f32_e32 v134, 0, v134
	s_nop 0
	s_nop 0
	v_add_f32_e32 v140, 1.0, v140
	v_rcp_f32_e32 v140, v140
	v_mov_b32_e32 v142, v134
	s_nop 0
	v_add_f32_e32 v129, v129, v169
	v_mul_f32_e32 v129, 0xbfb8aa3b, v129
	v_exp_f32_e32 v129, v129
	s_nop 0
	s_nop 0
	s_nop 0
	s_nop 0
	v_add_f32_e32 v129, 1.0, v129
	s_nop 0
	s_nop 0
	s_nop 0
	v_rcp_f32_e32 v129, v129
	v_add_f32_e32 v124, v124, v167
	s_nop 0
	s_nop 0
	s_nop 0
	s_nop 0
	v_mov_b32_e32 v144, v137
	v_mul_f32_e32 v129, 0xc1000000, v129
	v_sqrt_f32_e32 v142, v142
	s_nop 0
	s_nop 0
	s_nop 0
	v_mul_f32_e32 v142, v140, v142
	v_mul_f32_e32 v129, v165, v129
	s_nop 0
	s_nop 0
	v_mul_f32_e32 v129, 0x3fb8aa3b, v129
	v_exp_f32_e32 v129, v129
	v_add_f32_e32 v118, v118, v156
	s_nop 0
	s_nop 0
	s_nop 0
	s_nop 0
	v_mul_f32_e32 v124, 0xbfb8aa3b, v124
	s_nop 0
	s_nop 0
	s_nop 0
	v_mul_f32_e32 v118, 0xbfb8aa3b, v118
	v_exp_f32_e32 v124, v124
	s_nop 0
	s_nop 0
	s_nop 0
	s_nop 0
	v_exp_f32_e32 v118, v118
	v_mfma_f32_16x16x32_bf16 v[90:93], v[74:77], v[46:49], 0
	v_sqrt_f32_e32 v122, v126
	s_nop 0
	v_mul_f32_e32 v126, 0xc1000000, v127
	v_mul_f32_e32 v126, v165, v126
	v_mul_f32_e32 v126, 0x3fb8aa3b, v126
	v_exp_f32_e32 v126, v126
	v_exp_f32_e32 v127, v123
	v_mfma_f32_16x16x32_bf16 v[74:77], v[74:77], v[58:61], 0
	v_add_f32_e32 v124, 1.0, v124
	v_fma_f32 v123, -v126, v126, 1.0
	v_max_f32_e32 v123, 0, v123
	s_nop 0
	s_nop 0
	v_add_f32_e32 v118, 1.0, v118
	v_mfma_f32_16x16x32_bf16 v[90:93], v[152:155], v[26:29], v[90:93]
	v_mov_b32_e32 v140, v123
	s_nop 0
	v_cndmask_b32_e64 v123, v122, 1.0, vcc
	v_add_f32_e32 v122, 1.0, v127
	v_rcp_f32_e32 v150, v122
	s_nop 0
	s_nop 0
	s_nop 0
	s_nop 0
	v_mfma_f32_16x16x32_bf16 v[74:77], v[152:155], v[2:5], v[74:77]
	s_nop 0
	s_nop 0
	s_nop 0
	v_rcp_f32_e32 v124, v124
	ds_read2_b32 v[152:153], v176 offset0:96 offset1:112
	s_nop 0
	s_nop 0
	s_nop 0
	v_add_f32_e32 v127, 1.0, v128
	v_rcp_f32_e32 v127, v127
	s_nop 0
	v_rcp_f32_e32 v118, v118
	v_add_f32_e32 v125, v125, v167
	v_mul_f32_e32 v127, 0xc1000000, v127
	v_mul_f32_e32 v127, v165, v127
	v_mul_f32_e32 v127, 0x3fb8aa3b, v127
	v_exp_f32_e32 v127, v127
	v_sqrt_f32_e32 v122, v140
	s_nop 0
	v_mul_f32_e32 v125, 0xbfb8aa3b, v125
	v_exp_f32_e32 v125, v125
	v_fma_f32 v128, -v127, v127, 1.0
	v_max_f32_e32 v128, 0, v128
	s_nop 0
	s_nop 0
	v_mul_f32_e32 v118, 0xc1000000, v118
	s_waitcnt lgkmcnt(0)
; #define LAS __attribute__((address_space(3)))
; __device__ __forceinline__ float sigmoidf_(float x) { return __builtin_amdgcn_rcpf(1.0f + __expf(-x)); }
; template <int NT> ...
;     ...
;     for (int u = 0; u < NT; ++u) { const LAS float* XC = XCb + u * (16 * 68); const int t0 = m0 + 16 * u - b * TP;
; #pragma unroll
;         for (int n = 0; n < 4; ++n) { const int cc = 16 * n + fr;
;             const float ba = CST[5 * 64 + cc], bx = CST[6 * 64 + cc], sp = CST[7 * 64 + cc];
; #pragma unroll
;             for (int j = 0; j < 4; ++j) {
;                 const float xc = XC[(4 * fq + j) * 68 + cc];
;                 const float r = sigmoidf_(ar[u][n][j] + ba), ig = sigmoidf_(ai[u][n][j] + bx);
;                 const float a = __expf(-8.0f * r * sp);
;                 float mult = sqrtf(fmaxf(1.0f - a * a, 0.f));
;                 if (t0 + 4 * fq + j == 0) mult = 1.0f;
;                 av[u][n][j] = a; bv[u][n][j] = mult * ig * xc; } } }
	v_mul_f32_e32 v118, v152, v118
	s_nop 0
	s_nop 0
	v_mul_f32_e32 v118, 0x3fb8aa3b, v118
	ds_read2_b32 v[154:155], v176 offset0:32 offset1:48
	v_exp_f32_e32 v160, v118
	s_nop 0
	s_nop 0
	s_nop 0
	s_nop 0
	v_add_f32_e32 v125, 1.0, v125
	s_nop 0
	s_nop 0
	s_nop 0
	v_rcp_f32_e32 v125, v125
	v_fma_f32 v118, -v160, v160, 1.0
	s_nop 0
	s_nop 0
	s_nop 0
	s_nop 0
	v_pk_mul_f32 v[122:123], v[150:151], v[122:123]
	s_waitcnt lgkmcnt(0)
	v_add_f32_e32 v114, v114, v154
	v_sqrt_f32_e32 v128, v128
	s_nop 0
	v_fma_f32 v137, -v129, v129, 1.0
	v_max_f32_e32 v137, 0, v137
	s_nop 0
	s_nop 0
	v_mul_f32_e32 v124, v124, v128
	v_max_f32_e32 v118, 0, v118
	s_nop 0
	s_nop 0
	v_pk_mul_f32 v[122:123], v[144:145], v[122:123]
	v_mul_f32_e32 v114, 0xbfb8aa3b, v114
	v_exp_f32_e32 v114, v114
	s_nop 0
	s_nop 0
	s_nop 0
	s_nop 0
	v_add_f32_e32 v114, 1.0, v114
	s_nop 0
	s_nop 0
	s_nop 0
	v_rcp_f32_e32 v163, v114
	v_add_f32_e32 v119, v119, v156
	s_nop 0
	s_nop 0
	s_nop 0
	s_nop 0
	v_mul_f32_e32 v119, 0xbfb8aa3b, v119
	v_exp_f32_e32 v119, v119
	v_sqrt_f32_e32 v128, v137
	s_nop 0
	v_mul_f32_e32 v144, v125, v128
	s_nop 0
	s_nop 0
	v_add_f32_e32 v119, 1.0, v119
	ds_read2_b32 v[158:159], v241 offset0:32 offset1:48
	s_nop 0
	s_nop 0
	ds_read2_b32 v[170:171], v241 offset0:100 offset1:116
	v_add_f32_e32 v121, v121, v156
	v_mul_f32_e32 v121, 0xbfb8aa3b, v121
	s_nop 0
	s_nop 0
	s_nop 0
	s_nop 0
	v_exp_f32_e32 v121, v121
	s_nop 0
	s_nop 0
	s_nop 0
	v_add_f32_e32 v121, 1.0, v121
	v_rcp_f32_e32 v121, v121
	s_nop 0
	s_nop 0
	s_nop 0
	v_rcp_f32_e32 v125, v119
	s_nop 0
	v_add_f32_e32 v110, v110, v157
	v_mul_f32_e32 v110, 0xbfb8aa3b, v110
	v_sqrt_f32_e32 v114, v118
	s_nop 0
	v_cndmask_b32_e64 v119, v114, 1.0, vcc
	v_mul_f32_e32 v114, 0xc1000000, v125
	v_mul_f32_e32 v114, v152, v114
	v_mul_f32_e32 v114, 0x3fb8aa3b, v114
	v_exp_f32_e32 v151, v114
	v_add_f32_e32 v114, v115, v154
	v_mul_f32_e32 v114, 0xbfb8aa3b, v114
	v_exp_f32_e32 v114, v114
	v_fma_f32 v115, -v151, v151, 1.0
	v_max_f32_e32 v115, 0, v115
	s_nop 0
	s_nop 0
	v_add_f32_e32 v114, 1.0, v114
	v_rcp_f32_e32 v162, v114
	s_nop 0
	s_nop 0
	v_exp_f32_e32 v110, v110
	v_add_f32_e32 v106, v106, v155
	v_mul_f32_e32 v106, 0xbfb8aa3b, v106
	s_nop 0
	s_nop 0
	s_nop 0
	s_nop 0
	v_add_f32_e32 v110, 1.0, v110
	s_nop 0
	s_nop 0
	s_nop 0
	v_rcp_f32_e32 v110, v110
	v_exp_f32_e32 v106, v106
	s_nop 0
	s_nop 0
	s_nop 0
	v_add_f32_e32 v118, v120, v156
	v_mul_f32_e32 v118, 0xbfb8aa3b, v118
	v_exp_f32_e32 v120, v118
	s_nop 0
	v_mul_f32_e32 v110, 0xc1000000, v110
	v_mul_f32_e32 v110, v153, v110
	v_sqrt_f32_e32 v118, v115
	s_nop 0
	v_pk_mul_f32 v[114:115], v[162:163], v[118:119]
	v_add_f32_e32 v118, 1.0, v120
	v_rcp_f32_e32 v120, v118
	s_waitcnt lgkmcnt(0)
	v_mov_b32_e32 v118, v170
	v_mov_b32_e32 v119, v158
	v_pk_mul_f32 v[118:119], v[118:119], v[114:115]
	v_mul_f32_e32 v114, 0xc1000000, v120
	v_mul_f32_e32 v114, v152, v114
	v_mul_f32_e32 v114, 0x3fb8aa3b, v114
	v_exp_f32_e32 v147, v114
	v_add_f32_e32 v114, v116, v154
	v_mul_f32_e32 v114, 0xbfb8aa3b, v114
	v_exp_f32_e32 v116, v114
	v_fma_f32 v114, -v147, v147, 1.0
	v_max_f32_e32 v114, 0, v114
	s_nop 0
	s_nop 0
	v_add_f32_e32 v116, 1.0, v116
	v_rcp_f32_e32 v116, v116
	v_mov_b32_e32 v120, v114
	s_nop 0
	v_mul_f32_e32 v110, 0x3fb8aa3b, v110
	v_exp_f32_e32 v162, v110
	v_add_f32_e32 v111, v111, v157
	s_nop 0
	s_nop 0
	s_nop 0
	s_nop 0
	v_fma_f32 v110, -v162, v162, 1.0
	s_nop 0
	s_nop 0
	s_nop 0
	v_max_f32_e32 v110, 0, v110
	v_mul_f32_e32 v111, 0xbfb8aa3b, v111
	s_nop 0
	s_nop 0
	s_nop 0
	s_nop 0
	v_add_f32_e32 v106, 1.0, v106
	v_exp_f32_e32 v111, v111
	v_sqrt_f32_e32 v120, v120
	s_nop 0
	v_mul_f32_e32 v120, v116, v120
	v_mul_f32_e32 v116, 0xc1000000, v121
	v_mul_f32_e32 v116, v152, v116
	v_mul_f32_e32 v116, 0x3fb8aa3b, v116
	v_exp_f32_e32 v149, v116
	v_add_f32_e32 v116, v117, v154
	v_mul_f32_e32 v116, 0xbfb8aa3b, v116
	v_exp_f32_e32 v121, v116
	v_fma_f32 v116, -v149, v149, 1.0
	v_max_f32_e32 v116, 0, v116
	s_nop 0
	s_nop 0
	v_add_f32_e32 v121, 1.0, v121
	v_rcp_f32_e32 v121, v121
	v_mov_b32_e32 v125, v116
	s_nop 0
	v_rcp_f32_e32 v173, v106
	v_add_f32_e32 v111, 1.0, v111
	v_rcp_f32_e32 v111, v111
	s_nop 0
	s_nop 0
	s_nop 0
	s_nop 0
	v_add_f32_e32 v107, v107, v155
	s_nop 0
	s_nop 0
	s_nop 0
	v_mul_f32_e32 v107, 0xbfb8aa3b, v107
	v_add_f32_e32 v112, v112, v157
	s_nop 0
	s_nop 0
	s_nop 0
	s_nop 0
	v_mul_f32_e32 v112, 0xbfb8aa3b, v112
	v_exp_f32_e32 v112, v112
	v_sqrt_f32_e32 v125, v125
	s_nop 0
	s_nop 0
	s_nop 0
	v_mul_f32_e32 v150, v121, v125
	v_add_f32_e32 v113, v113, v157
	s_nop 0
	s_nop 0
	v_mul_f32_e32 v113, 0xbfb8aa3b, v113
	v_exp_f32_e32 v113, v113
	v_add_f32_e32 v108, v108, v155
	s_nop 0
	s_nop 0
	s_nop 0
	s_nop 0
	s_nop 0
	s_nop 0
	s_nop 0
	v_add_f32_e32 v113, 1.0, v113
	v_rcp_f32_e32 v113, v113
	s_nop 0
	s_nop 0
	s_nop 0
	s_nop 0
	v_mul_f32_e32 v113, 0xc1000000, v113
	v_mul_f32_e32 v113, v153, v113
	v_sqrt_f32_e32 v106, v110
	s_nop 0
	v_mul_f32_e32 v110, 0xc1000000, v111
	v_mul_f32_e32 v110, v153, v110
	v_mul_f32_e32 v110, 0x3fb8aa3b, v110
	v_exp_f32_e32 v110, v110
	v_exp_f32_e32 v111, v107
	v_mul_f32_e32 v113, 0x3fb8aa3b, v113
	v_exp_f32_e32 v113, v113
	v_fma_f32 v107, -v110, v110, 1.0
	v_max_f32_e32 v107, 0, v107
	s_nop 0
	s_nop 0
	v_add_f32_e32 v102, v102, v168
	v_mul_f32_e32 v108, 0xbfb8aa3b, v108
	v_mov_b32_e32 v121, v107
	s_nop 0
	v_cndmask_b32_e64 v107, v106, 1.0, vcc
	v_add_f32_e32 v106, 1.0, v111
	v_rcp_f32_e32 v172, v106
	s_nop 0
	s_nop 0
	s_nop 0
	s_nop 0
	v_mul_f32_e32 v102, 0xbfb8aa3b, v102
	s_nop 0
	s_nop 0
	s_nop 0
	v_exp_f32_e32 v108, v108
	v_exp_f32_e32 v102, v102
	s_nop 0
	s_nop 0
	s_nop 0
	v_add_f32_e32 v111, 1.0, v112
	v_rcp_f32_e32 v111, v111
	s_nop 0
	v_add_f32_e32 v108, 1.0, v108
; #define LAS __attribute__((address_space(3)))
; __device__ __forceinline__ float sigmoidf_(float x) { return __builtin_amdgcn_rcpf(1.0f + __expf(-x)); }
; template <int NT> ...
;     ...
;     for (int u = 0; u < NT; ++u) { const LAS float* XC = XCb + u * (16 * 68); const int t0 = m0 + 16 * u - b * TP;
; #pragma unroll
;         for (int n = 0; n < 4; ++n) { const int cc = 16 * n + fr;
;             const float ba = CST[5 * 64 + cc], bx = CST[6 * 64 + cc], sp = CST[7 * 64 + cc];
; #pragma unroll
;             for (int j = 0; j < 4; ++j) {
;                 const float xc = XC[(4 * fq + j) * 68 + cc];
;                 const float r = sigmoidf_(ar[u][n][j] + ba), ig = sigmoidf_(ai[u][n][j] + bx);
;                 const float a = __expf(-8.0f * r * sp);
;                 float mult = sqrtf(fmaxf(1.0f - a * a, 0.f));
;                 if (t0 + 4 * fq + j == 0) mult = 1.0f;
;                 av[u][n][j] = a; bv[u][n][j] = mult * ig * xc; } } }
	v_add_f32_e32 v102, 1.0, v102
	v_mul_f32_e32 v111, 0xc1000000, v111
	v_mul_f32_e32 v111, v153, v111
	v_mul_f32_e32 v111, 0x3fb8aa3b, v111
	v_exp_f32_e32 v111, v111
	v_sqrt_f32_e32 v106, v121
	s_nop 0
	v_rcp_f32_e32 v108, v108
	v_rcp_f32_e32 v102, v102
	v_fma_f32 v112, -v111, v111, 1.0
	v_max_f32_e32 v112, 0, v112
	s_nop 0
	s_nop 0
	v_add_f32_e32 v109, v109, v155
	v_mul_f32_e32 v109, 0xbfb8aa3b, v109
	s_nop 0
	s_nop 0
	v_exp_f32_e32 v109, v109
	v_mul_f32_e32 v102, 0xc1000000, v102
	v_mul_f32_e32 v102, v164, v102
	s_nop 0
	s_nop 0
	s_nop 0
	s_nop 0
	v_mul_f32_e32 v102, 0x3fb8aa3b, v102
	s_nop 0
	s_nop 0
	s_nop 0
	v_exp_f32_e32 v178, v102
	v_add_f32_e32 v103, v103, v168
	s_nop 0
	s_nop 0
	s_nop 0
	s_nop 0
	v_add_f32_e32 v109, 1.0, v109
	v_mul_f32_e32 v103, 0xbfb8aa3b, v103
	v_sqrt_f32_e32 v112, v112
	s_nop 0
	v_fma_f32 v121, -v113, v113, 1.0
	v_max_f32_e32 v121, 0, v121
	s_nop 0
	s_nop 0
	v_mul_f32_e32 v108, v108, v112
	v_rcp_f32_e32 v109, v109
	s_nop 0
	s_nop 0
	v_exp_f32_e32 v103, v103
	v_fma_f32 v102, -v178, v178, 1.0
	v_pk_mul_f32 v[106:107], v[172:173], v[106:107]
	s_nop 0
	s_nop 0
	s_nop 0
	s_nop 0
	v_mov_b32_e32 v158, v171
	s_nop 0
	s_nop 0
	s_nop 0
	v_max_f32_e32 v102, 0, v102
	v_pk_mul_f32 v[106:107], v[158:159], v[106:107]
	s_nop 0
	s_nop 0
	s_nop 0
	s_nop 0
	v_add_f32_e32 v103, 1.0, v103
	v_rcp_f32_e32 v103, v103
	v_sqrt_f32_e32 v112, v121
	s_nop 0
	v_mul_f32_e32 v158, v109, v112
	s_nop 0
	s_nop 0
	v_mul_f32_e32 v103, 0xc1000000, v103
	v_mul_f32_e32 v103, v164, v103
	s_nop 0
	s_nop 0
	v_mul_f32_e32 v103, 0x3fb8aa3b, v103
	v_exp_f32_e32 v179, v103
	v_add_f32_e32 v98, v98, v166
	s_nop 0
	s_nop 0
	s_nop 0
	s_nop 0
	v_fma_f32 v103, -v179, v179, 1.0
	s_nop 0
	s_nop 0
	s_nop 0
	v_max_f32_e32 v103, 0, v103
	v_add_f32_e32 v99, v99, v166
	s_nop 0
	s_nop 0
	s_nop 0
	s_nop 0
	v_mul_f32_e32 v98, 0xbfb8aa3b, v98
	v_mul_f32_e32 v99, 0xbfb8aa3b, v99
	v_sqrt_f32_e32 v102, v102
	s_nop 0
	s_nop 0
	s_nop 0
	v_exp_f32_e32 v98, v98
	v_exp_f32_e32 v99, v99
	s_nop 0
	s_nop 0
	v_add_f32_e32 v104, v104, v168
	v_add_f32_e32 v98, 1.0, v98
	v_add_f32_e32 v99, 1.0, v99
	s_nop 0
	s_nop 0
	s_nop 0
	s_nop 0
	v_mul_f32_e32 v104, 0xbfb8aa3b, v104
	s_nop 0
	s_nop 0
	s_nop 0
	v_rcp_f32_e32 v98, v98
	v_rcp_f32_e32 v99, v99
	s_nop 0
	v_exp_f32_e32 v104, v104
	s_nop 0
	v_add_u32_e32 v109, 0x1000, v241
	s_nop 0
	s_nop 0
	ds_read2_b32 v[170:171], v109 offset0:64 offset1:80
	ds_read2_b32 v[172:173], v109 offset0:132 offset1:148
	v_sqrt_f32_e32 v103, v103
	s_nop 0
	v_pk_mul_f32 v[98:99], v[98:99], v[102:103]
	v_add_f32_e32 v102, 1.0, v104
	v_rcp_f32_e32 v104, v102
	s_waitcnt lgkmcnt(1)
	v_mov_b32_e32 v102, v170
	s_waitcnt lgkmcnt(0)
	v_mov_b32_e32 v103, v172
	v_pk_mul_f32 v[102:103], v[98:99], v[102:103]
	v_mul_f32_e32 v98, 0xc1000000, v104
	v_mul_f32_e32 v98, v164, v98
	v_mul_f32_e32 v98, 0x3fb8aa3b, v98
	v_exp_f32_e32 v161, v98
	v_add_f32_e32 v98, v100, v166
	v_mul_f32_e32 v98, 0xbfb8aa3b, v98
	v_exp_f32_e32 v100, v98
	v_fma_f32 v98, -v161, v161, 1.0
	v_max_f32_e32 v98, 0, v98
	s_nop 0
	s_nop 0
	v_add_f32_e32 v105, v105, v168
	v_mul_f32_e32 v105, 0xbfb8aa3b, v105
	v_mov_b32_e32 v104, v98
	s_nop 0
	v_exp_f32_e32 v105, v105
	v_add_f32_e32 v100, 1.0, v100
	v_rcp_f32_e32 v100, v100
	s_nop 0
	s_nop 0
	s_nop 0
	s_nop 0
	v_add_f32_e32 v105, 1.0, v105
	s_nop 0
	s_nop 0
	s_nop 0
	v_rcp_f32_e32 v105, v105
	v_add_f32_e32 v94, v94, v169
	s_nop 0
	s_nop 0
	s_nop 0
	s_nop 0
	v_mul_f32_e32 v94, 0xbfb8aa3b, v94
	v_exp_f32_e32 v94, v94
	v_sqrt_f32_e32 v104, v104
	s_nop 0
	v_mul_f32_e32 v104, v100, v104
	v_mul_f32_e32 v100, 0xc1000000, v105
	v_mul_f32_e32 v100, v164, v100
	v_mul_f32_e32 v100, 0x3fb8aa3b, v100
	v_exp_f32_e32 v163, v100
	v_add_f32_e32 v100, v101, v166
	v_mul_f32_e32 v100, 0xbfb8aa3b, v100
	v_exp_f32_e32 v105, v100
	v_fma_f32 v100, -v163, v163, 1.0
	v_max_f32_e32 v100, 0, v100
	s_nop 0
	s_nop 0
	v_add_f32_e32 v94, 1.0, v94
	v_rcp_f32_e32 v94, v94
	v_mov_b32_e32 v121, v100
	s_nop 0
	v_add_f32_e32 v105, 1.0, v105
	v_mul_f32_e32 v94, 0xc1000000, v94
	v_mul_f32_e32 v94, v165, v94
	s_nop 0
	s_nop 0
	v_mul_f32_e32 v94, 0x3fb8aa3b, v94
	s_nop 0
	s_nop 0
	v_exp_f32_e32 v168, v94
	s_nop 0
	s_nop 0
	s_nop 0
	v_fma_f32 v94, -v168, v168, 1.0
	v_max_f32_e32 v94, 0, v94
	s_nop 0
	s_nop 0
	s_nop 0
	s_nop 0
	v_rcp_f32_e32 v105, v105
	v_add_f32_e32 v95, v95, v169
	v_sqrt_f32_e32 v121, v121
	s_nop 0
	v_mul_f32_e32 v125, 0x4f800000, v94
	v_cmp_gt_f32_e32 vcc, s47, v94
	v_mul_f32_e32 v95, 0xbfb8aa3b, v95
	v_exp_f32_e32 v95, v95
	v_cndmask_b32_e32 v125, v94, v125, vcc
	v_sqrt_f32_e32 v94, v125
	v_mul_f32_e32 v164, v105, v121
	v_add_f32_e32 v95, 1.0, v95
	v_rcp_f32_e32 v95, v95
	v_add_u32_e32 v105, -1, v94
	v_fma_f32 v121, -v105, v94, v125
	v_cmp_ge_f32_e64 s[10:11], 0, v121
	v_add_u32_e32 v121, 1, v94
	v_add_f32_e32 v96, v96, v169
	v_cndmask_b32_e64 v105, v94, v105, s[10:11]
	v_fma_f32 v94, -v121, v94, v125
	v_cmp_lt_f32_e64 s[10:11], 0, v94
	v_mul_f32_e32 v96, 0xbfb8aa3b, v96
	v_exp_f32_e32 v96, v96
	v_cndmask_b32_e64 v94, v105, v121, s[10:11]
	v_mul_f32_e32 v105, 0x37800000, v94
	v_cndmask_b32_e32 v105, v94, v105, vcc
	v_mul_f32_e32 v94, 0xc1000000, v95
	v_mul_f32_e32 v94, v165, v94
	v_mul_f32_e32 v94, 0x3fb8aa3b, v94
	v_exp_f32_e32 v94, v94
	v_cmp_class_f32_e64 s[10:11], v125, v219
	v_add_f32_e32 v96, 1.0, v96
	v_rcp_f32_e32 v96, v96
	v_fma_f32 v95, -v94, v94, 1.0
	v_max_f32_e32 v95, 0, v95
	s_nop 0
	s_nop 0
	v_cndmask_b32_e64 v174, v105, v125, s[10:11]
	v_add_f32_e32 v97, v97, v169
	s_nop 0
	s_nop 0
	v_mul_f32_e32 v97, 0xbfb8aa3b, v97
	v_exp_f32_e32 v97, v97
	v_add_f32_e32 v92, v92, v167
	s_nop 0
	s_nop 0
	s_nop 0
	s_nop 0
	v_add_f32_e32 v97, 1.0, v97
	s_nop 0
	s_nop 0
	s_nop 0
; #define LAS __attribute__((address_space(3)))
; __device__ __forceinline__ float sigmoidf_(float x) { return __builtin_amdgcn_rcpf(1.0f + __expf(-x)); }
; template <int NT> ...
;     ...
;     for (int u = 0; u < NT; ++u) { const LAS float* XC = XCb + u * (16 * 68); const int t0 = m0 + 16 * u - b * TP;
; #pragma unroll
;         for (int n = 0; n < 4; ++n) { const int cc = 16 * n + fr;
;             const float ba = CST[5 * 64 + cc], bx = CST[6 * 64 + cc], sp = CST[7 * 64 + cc];
; #pragma unroll
;             for (int j = 0; j < 4; ++j) {
;                 const float xc = XC[(4 * fq + j) * 68 + cc];
;                 const float r = sigmoidf_(ar[u][n][j] + ba), ig = sigmoidf_(ai[u][n][j] + bx);
;                 const float a = __expf(-8.0f * r * sp);
;                 float mult = sqrtf(fmaxf(1.0f - a * a, 0.f));
;                 if (t0 + 4 * fq + j == 0) mult = 1.0f;
;                 av[u][n][j] = a; bv[u][n][j] = mult * ig * xc; } } }
	v_rcp_f32_e32 v97, v97
	v_add_f32_e32 v86, v86, v156
	s_nop 0
	s_nop 0
	s_nop 0
	s_nop 0
	v_mul_f32_e32 v97, 0xc1000000, v97
	v_mul_f32_e32 v97, v165, v97
	v_sqrt_f32_e32 v175, v95
	s_nop 0
	v_mul_f32_e32 v95, 0xc1000000, v96
	v_mul_f32_e32 v95, v165, v95
	v_mul_f32_e32 v95, 0x3fb8aa3b, v95
	v_exp_f32_e32 v95, v95
	v_mul_f32_e32 v97, 0x3fb8aa3b, v97
	v_exp_f32_e32 v97, v97
	v_mul_f32_e32 v92, 0xbfb8aa3b, v92
	v_fma_f32 v96, -v95, v95, 1.0
	v_max_f32_e32 v96, 0, v96
	s_nop 0
	s_nop 0
	v_mul_f32_e32 v86, 0xbfb8aa3b, v86
	v_exp_f32_e32 v92, v92
	s_nop 0
	s_nop 0
	v_exp_f32_e32 v86, v86
	v_add_f32_e32 v92, 1.0, v92
	v_rcp_f32_e32 v92, v92
	s_nop 0
	s_nop 0
	s_nop 0
	s_nop 0
	v_add_f32_e32 v86, 1.0, v86
	s_nop 0
	s_nop 0
	s_nop 0
	v_rcp_f32_e32 v86, v86
	v_add_f32_e32 v93, v93, v167
	s_nop 0
	s_nop 0
	s_nop 0
	s_nop 0
	v_mul_f32_e32 v93, 0xbfb8aa3b, v93
	v_exp_f32_e32 v93, v93
	v_sqrt_f32_e32 v96, v96
	s_nop 0
	v_fma_f32 v105, -v97, v97, 1.0
	v_max_f32_e32 v105, 0, v105
	s_nop 0
	s_nop 0
	v_mul_f32_e32 v92, v92, v96
	v_mul_f32_e32 v86, 0xc1000000, v86
	s_nop 0
	s_nop 0
	v_mul_f32_e32 v86, v152, v86
	v_mul_f32_e32 v86, 0x3fb8aa3b, v86
	v_exp_f32_e32 v180, v86
	s_nop 0
	s_nop 0
	s_nop 0
	s_nop 0
	v_add_f32_e32 v87, v87, v156
	s_nop 0
	s_nop 0
	v_add_f32_e32 v93, 1.0, v93
	s_nop 0
	v_mul_f32_e32 v87, 0xbfb8aa3b, v87
	v_rcp_f32_e32 v93, v93
	s_nop 0
	v_exp_f32_e32 v87, v87
	s_nop 0
	s_nop 0
	s_nop 0
	v_fma_f32 v86, -v180, v180, 1.0
	v_max_f32_e32 v86, 0, v86
	v_sqrt_f32_e32 v96, v105
	s_nop 0
	v_mul_f32_e32 v166, v93, v96
	s_nop 0
	s_nop 0
	v_add_f32_e32 v87, 1.0, v87
	v_rcp_f32_e32 v87, v87
	s_nop 0
	s_nop 0
	v_add_f32_e32 v90, v90, v167
	v_mul_f32_e32 v87, 0xc1000000, v87
	v_mul_f32_e32 v87, v152, v87
	s_nop 0
	s_nop 0
	v_mul_f32_e32 v87, 0x3fb8aa3b, v87
	s_nop 0
	s_nop 0
	v_exp_f32_e32 v170, v87
	s_nop 0
	s_nop 0
	s_nop 0
	v_fma_f32 v87, -v170, v170, 1.0
	v_max_f32_e32 v87, 0, v87
	s_nop 0
	s_nop 0
	s_nop 0
	s_nop 0
	v_add_f32_e32 v91, v91, v167
	v_mul_f32_e32 v90, 0xbfb8aa3b, v90
	v_sqrt_f32_e32 v86, v86
	s_nop 0
	s_nop 0
	s_nop 0
	v_mul_f32_e32 v91, 0xbfb8aa3b, v91
	v_exp_f32_e32 v90, v90
	s_nop 0
	s_nop 0
	v_exp_f32_e32 v91, v91
	v_add_f32_e32 v82, v82, v154
	v_add_f32_e32 v83, v83, v154
	v_mul_f32_e32 v82, 0xbfb8aa3b, v82
	v_mul_f32_e32 v83, 0xbfb8aa3b, v83
	v_exp_f32_e32 v82, v82
	v_exp_f32_e32 v83, v83
	s_nop 0
	s_nop 0
	v_add_f32_e32 v90, 1.0, v90
	v_add_f32_e32 v91, 1.0, v91
	s_nop 0
	s_nop 0
	v_rcp_f32_e32 v90, v90
	v_rcp_f32_e32 v91, v91
	s_nop 0
	s_nop 0
	v_add_f32_e32 v88, v88, v156
	v_add_f32_e32 v82, 1.0, v82
	v_add_f32_e32 v83, 1.0, v83
	s_nop 0
	v_mul_f32_e32 v88, 0xbfb8aa3b, v88
	v_rcp_f32_e32 v82, v82
	v_rcp_f32_e32 v83, v83
	s_nop 0
	v_exp_f32_e32 v88, v88
	s_nop 0
	v_pk_mul_f32 v[90:91], v[90:91], v[174:175]
	v_mov_b32_e32 v172, v171
	s_nop 0
	s_nop 0
	v_pk_mul_f32 v[90:91], v[90:91], v[172:173]
	ds_read2_b32 v[172:173], v109 offset0:96 offset1:112
	ds_read2_b32 v[174:175], v109 offset0:164 offset1:180
	v_sqrt_f32_e32 v87, v87
	s_nop 0
	v_pk_mul_f32 v[82:83], v[82:83], v[86:87]
	v_add_f32_e32 v86, 1.0, v88
	v_rcp_f32_e32 v88, v86
	s_waitcnt lgkmcnt(1)
	v_mov_b32_e32 v86, v172
	s_waitcnt lgkmcnt(0)
	v_mov_b32_e32 v87, v174
	v_pk_mul_f32 v[86:87], v[82:83], v[86:87]
	v_mul_f32_e32 v82, 0xc1000000, v88
	v_mul_f32_e32 v82, v152, v82
	v_mul_f32_e32 v82, 0x3fb8aa3b, v82
	v_exp_f32_e32 v169, v82
	v_add_f32_e32 v82, v84, v154
	v_mul_f32_e32 v82, 0xbfb8aa3b, v82
	v_exp_f32_e32 v84, v82
	v_fma_f32 v82, -v169, v169, 1.0
	v_max_f32_e32 v82, 0, v82
	s_nop 0
	s_nop 0
	v_add_f32_e32 v89, v89, v156
	v_mul_f32_e32 v89, 0xbfb8aa3b, v89
	v_mov_b32_e32 v88, v82
	s_nop 0
	v_exp_f32_e32 v89, v89
	v_add_f32_e32 v84, 1.0, v84
	v_rcp_f32_e32 v84, v84
	s_nop 0
	s_nop 0
	s_nop 0
	s_nop 0
	v_add_f32_e32 v89, 1.0, v89
	s_nop 0
	s_nop 0
	s_nop 0
	v_rcp_f32_e32 v89, v89
	v_add_f32_e32 v78, v78, v157
	s_nop 0
	s_nop 0
	s_nop 0
	s_nop 0
	v_mul_f32_e32 v78, 0xbfb8aa3b, v78
	v_exp_f32_e32 v78, v78
	v_sqrt_f32_e32 v88, v88
	s_nop 0
	v_mul_f32_e32 v88, v84, v88
	v_mul_f32_e32 v84, 0xc1000000, v89
	v_mul_f32_e32 v84, v152, v84
	v_mul_f32_e32 v84, 0x3fb8aa3b, v84
	v_exp_f32_e32 v171, v84
	v_add_f32_e32 v84, v85, v154
	v_mul_f32_e32 v84, 0xbfb8aa3b, v84
	v_exp_f32_e32 v89, v84
	v_fma_f32 v84, -v171, v171, 1.0
	v_max_f32_e32 v84, 0, v84
	s_nop 0
	s_nop 0
	v_add_f32_e32 v78, 1.0, v78
	v_rcp_f32_e32 v78, v78
	v_mov_b32_e32 v93, v84
	s_nop 0
	ds_read2_b32 v[98:99], v109 offset0:200 offset1:216
	v_mul_f32_e32 v78, 0xc1000000, v78
	v_mul_f32_e32 v78, v153, v78
	s_nop 0
	ds_read2_b32 v[82:83], v109 offset0:232 offset1:248
	s_nop 0
	v_mul_f32_e32 v78, 0x3fb8aa3b, v78
	v_add_f32_e32 v79, v79, v157
	s_nop 0
	s_nop 0
	v_exp_f32_e32 v152, v78
	v_mul_f32_e32 v79, 0xbfb8aa3b, v79
	s_nop 0
	s_nop 0
	v_exp_f32_e32 v79, v79
	s_nop 0
	v_add_f32_e32 v74, v74, v155
	v_mul_f32_e32 v74, 0xbfb8aa3b, v74
	s_nop 0
	s_nop 0
	v_exp_f32_e32 v78, v74
	v_fma_f32 v74, -v152, v152, 1.0
	s_nop 0
	s_nop 0
	v_max_f32_e32 v74, 0, v74
	v_add_f32_e32 v79, 1.0, v79
	v_sqrt_f32_e32 v93, v93
	s_nop 0
	v_mul_f32_e32 v96, 0x4f800000, v74
	v_cmp_gt_f32_e32 vcc, s47, v74
	v_rcp_f32_e32 v79, v79
	v_add_f32_e32 v89, 1.0, v89
	v_cndmask_b32_e32 v96, v74, v96, vcc
	v_rcp_f32_e32 v89, v89
	v_sqrt_f32_e32 v105, v96
	v_mul_f32_e32 v79, 0xc1000000, v79
	v_mul_f32_e32 v79, v153, v79
	v_mul_f32_e32 v74, v89, v93
	v_add_u32_e32 v89, -1, v105
	v_mul_f32_e32 v79, 0x3fb8aa3b, v79
	v_fma_f32 v93, -v89, v105, v96
	v_exp_f32_e32 v154, v79
	v_cmp_ge_f32_e64 s[10:11], 0, v93
	v_add_u32_e32 v93, 1, v105
	v_add_f32_e32 v75, v75, v155
	v_cndmask_b32_e64 v89, v105, v89, s[10:11]
	v_fma_f32 v105, -v93, v105, v96
; #define LAS __attribute__((address_space(3)))
; __device__ __forceinline__ unsigned cvt_pk_bf16(float lo, float hi) { unsigned r; asm volatile("v_cvt_pk_bf16_f32 %0, %1, %2" : "=v"(r) : "v"(lo), "v"(hi)); return r; }
; __device__ __forceinline__ float sigmoidf_(float x) { return __builtin_amdgcn_rcpf(1.0f + __expf(-x)); }
; template <int NT> ...
;     ...
;     for (int u = 0; u < NT; ++u) { const LAS float* XC = XCb + u * (16 * 68); const int t0 = m0 + 16 * u - b * TP;
; #pragma unroll
;         for (int n = 0; n < 4; ++n) { const int cc = 16 * n + fr;
;             const float ba = CST[5 * 64 + cc], bx = CST[6 * 64 + cc], sp = CST[7 * 64 + cc];
; #pragma unroll
;             for (int j = 0; j < 4; ++j) {
;                 const float xc = XC[(4 * fq + j) * 68 + cc];
;                 const float r = sigmoidf_(ar[u][n][j] + ba), ig = sigmoidf_(ai[u][n][j] + bx);
;                 const float a = __expf(-8.0f * r * sp);
;                 float mult = sqrtf(fmaxf(1.0f - a * a, 0.f));
;                 if (t0 + 4 * fq + j == 0) mult = 1.0f;
;                 av[u][n][j] = a; bv[u][n][j] = mult * ig * xc; } } }
; #pragma unroll
;     for (int u = 0; u < NT; ++u) {
; #pragma unroll
;         for (int n = 0; n < 4; ++n) { const int ch = hc0 + 16 * n + fr;
;             float hl[4], pl[4];
;             hl[0] = bv[u][n][0]; pl[0] = av[u][n][0];
; #pragma unroll
;             for (int j = 1; j < 4; ++j) { hl[j] = av[u][n][j] * hl[j - 1] + bv[u][n][j]; pl[j] = av[u][n][j] * pl[j - 1]; }
;             float He = 0.f, Pe = 1.f;
; #pragma unroll
;             for (int g = 0; g < 3; ++g) { const float Pg = __shfl(pl[3], fr + 16 * g), Hg = __shfl(hl[3], fr + 16 * g); if (g < fq) { He = Pg * He + Hg; Pe = Pg * Pe; } }
;             const float Hin = Pe * Hc[n] + He, Pin = Pe * Pc[n];
;             float hf[4], pf[4];
; #pragma unroll
;             for (int j = 0; j < 4; ++j) { hf[j] = hl[j] + pl[j] * Hin; pf[j] = pl[j] * Pin; }
; #pragma unroll
;             for (int j = 0; j < 4; ++j) { const size_t o = (size_t)(m0 + 16 * u + 4 * fq + j) * D + ch; HLOC[o] = (bf16_t)(cvt_pk_bf16(hf[j], 0.f) & 0xffffu); PCUM[o] = (bf16_t)(cvt_pk_bf16(pf[j], 0.f) & 0xffffu); }
;             Hc[n] = __shfl(hf[3], fr + 48); Pc[n] = __shfl(pf[3], fr + 48);
;         } }
	v_cmp_lt_f32_e64 s[10:11], 0, v105
	v_fma_f32 v79, -v154, v154, 1.0
	v_max_f32_e32 v79, 0, v79
	v_cndmask_b32_e64 v89, v89, v93, s[10:11]
	v_mul_f32_e32 v93, 0x37800000, v89
	v_cndmask_b32_e32 v89, v89, v93, vcc
	v_mul_f32_e32 v75, 0xbfb8aa3b, v75
	s_nop 0
	s_nop 0
	v_exp_f32_e32 v75, v75
	v_add_f32_e32 v80, v80, v157
	v_mov_b32_e32 v93, v79
	s_nop 0
	v_mul_f32_e32 v80, 0xbfb8aa3b, v80
	v_add_f32_e32 v75, 1.0, v75
	v_exp_f32_e32 v80, v80
	v_cmp_class_f32_e64 s[10:11], v96, v219
	v_rcp_f32_e32 v79, v75
	s_nop 0
	v_cndmask_b32_e64 v182, v89, v96, s[10:11]
	s_nop 0
	s_nop 0
	s_nop 0
	s_nop 0
	v_add_f32_e32 v80, 1.0, v80
	s_nop 0
	s_nop 0
	v_rcp_f32_e32 v80, v80
	v_mov_b32_e32 v174, v173
	s_nop 0
	s_nop 0
	s_nop 0
	s_nop 0
	v_add_f32_e32 v81, v81, v157
	v_mul_f32_e32 v81, 0xbfb8aa3b, v81
	v_sqrt_f32_e32 v183, v93
	s_nop 0
	v_mul_f32_e32 v75, 0xc1000000, v80
	v_mul_f32_e32 v75, v153, v75
	v_mul_f32_e32 v75, 0x3fb8aa3b, v75
	v_exp_f32_e32 v173, v75
	v_add_f32_e32 v75, v76, v155
	v_exp_f32_e32 v81, v81
	v_mul_f32_e32 v75, 0xbfb8aa3b, v75
	v_fma_f32 v76, -v173, v173, 1.0
	v_max_f32_e32 v76, 0, v76
	s_nop 0
	s_nop 0
	v_add_f32_e32 v81, 1.0, v81
	v_rcp_f32_e32 v81, v81
	s_nop 0
	s_nop 0
	v_exp_f32_e32 v75, v75
	v_add_f32_e32 v77, v77, v155
	v_mul_f32_e32 v77, 0xbfb8aa3b, v77
	s_nop 0
	s_nop 0
	s_nop 0
	s_nop 0
	v_add_f32_e32 v75, 1.0, v75
	s_nop 0
	s_nop 0
	s_nop 0
	v_rcp_f32_e32 v75, v75
	v_exp_f32_e32 v77, v77
	s_nop 0
	s_nop 0
	s_nop 0
	s_nop 0
	ds_read2_b32 v[130:131], v241 offset0:136 offset1:152
	ds_read2_b32 v[134:135], v241 offset0:204 offset1:220
	v_sqrt_f32_e32 v76, v76
	s_nop 0
	v_mul_f32_e32 v80, 0xc1000000, v81
	v_mul_f32_e32 v80, v153, v80
	v_mul_f32_e32 v80, 0x3fb8aa3b, v80
	v_exp_f32_e32 v81, v80
	v_mul_f32_e32 v76, v75, v76
	v_add_f32_e32 v75, 1.0, v77
	v_fma_f32 v137, v138, v133, v132
	v_fma_f32 v80, -v81, v81, 1.0
	v_max_f32_e32 v80, 0, v80
	s_nop 0
	s_nop 0
	s_waitcnt lgkmcnt(0)
	v_mov_b32_e32 v140, v134
	v_rcp_f32_e32 v75, v75
	s_nop 0
	s_nop 0
	v_add_u32_e32 v112, 0x1400, v241
	ds_read2_b32 v[100:101], v112 offset0:12 offset1:28
	ds_read2_b32 v[84:85], v112 offset0:44 offset1:60
	s_nop 0
	s_nop 0
	s_nop 0
	s_nop 0
	ds_read2_b32 v[114:115], v241 offset0:168 offset1:184
	s_nop 0
	s_nop 0
	s_nop 0
	ds_read2_b32 v[116:117], v241 offset0:236 offset1:252
	v_add_f32_e32 v78, 1.0, v78
	s_nop 0
	s_nop 0
	s_nop 0
	s_nop 0
	v_mul_f32_e32 v93, v138, v146
	v_mov_b32_e32 v138, v130
	v_sqrt_f32_e32 v77, v80
	s_nop 0
	v_mul_f32_e32 v80, v139, v137
	v_pk_fma_f32 v[156:157], v[138:139], v[136:137], v[80:81] op_sel_hi:[1,1,0]
	v_and_or_b32 v89, v207, 64, v223
	v_mov_b32_e32 v143, v156
	v_mul_f32_e32 v80, v139, v93
	v_pk_mul_f32 v[138:139], v[140:141], v[142:143]
	v_mul_f32_e32 v105, v141, v80
	v_add_f32_e32 v96, v138, v139
	v_lshlrev_b32_e32 v134, 2, v89
	ds_bpermute_b32 v89, v134, v105
	ds_bpermute_b32 v109, v134, v96
	v_mul_f32_e32 v130, v75, v77
	ds_bpermute_b32 v75, v134, v105 offset:64
	ds_bpermute_b32 v77, v134, v96 offset:64
	ds_bpermute_b32 v112, v134, v105 offset:128
	ds_bpermute_b32 v121, v134, v96 offset:128
	s_waitcnt lgkmcnt(4)
	v_fmac_f32_e32 v109, 0, v89
	v_cndmask_b32_e64 v109, v109, 0, s[8:9]
	v_cndmask_b32_e64 v89, v89, 1.0, s[8:9]
	s_waitcnt lgkmcnt(2)
	v_fmac_f32_e32 v77, v109, v75
	v_mul_f32_e32 v75, v89, v75
	v_cndmask_b32_e64 v77, v109, v77, s[4:5]
	v_cndmask_b32_e64 v75, v89, v75, s[4:5]
	v_add_u32_e32 v138, s19, v242
	s_waitcnt lgkmcnt(0)
	v_fmac_f32_e32 v121, v77, v112
	v_mul_f32_e32 v89, v75, v112
	v_ashrrev_i32_e32 v139, 31, v138
	v_cndmask_b32_e64 v77, v77, v121, s[6:7]
	v_cndmask_b32_e64 v75, v75, v89, s[6:7]
	v_lshlrev_b64 v[140:141], 10, v[138:139]
	v_fmac_f32_e32 v77, v70, v75
	v_mul_f32_e32 v70, v72, v75
	v_fmac_f32_e32 v133, v146, v77
	v_or_b32_e32 v142, v140, v208
	v_mov_b32_e32 v143, v141
	v_mul_f32_e32 v72, v146, v70
	v_fmac_f32_e32 v137, v93, v77
	v_mul_f32_e32 v75, v93, v70
	v_fmac_f32_e32 v156, v80, v77
	v_mul_f32_e32 v80, v80, v70
	v_fmac_f32_e32 v96, v105, v77
	v_mul_f32_e32 v77, v105, v70
	v_cvt_pk_bf16_f32 v70, v133, v1
	v_lshlrev_b64 v[132:133], 1, v[142:143]
	v_lshl_add_u64 v[142:143], s[62:63], 0, v[132:133]
	v_lshl_add_u64 v[132:133], s[64:65], 0, v[132:133]
	global_store_short v[142:143], v70, off
	v_cvt_pk_bf16_f32 v70, v72, v1
	global_store_short v[132:133], v70, off
	v_add_u32_e32 v132, 1, v138
	v_ashrrev_i32_e32 v133, 31, v132
	v_lshlrev_b64 v[132:133], 10, v[132:133]
	v_or_b32_e32 v142, v132, v208
	v_mov_b32_e32 v143, v133
	v_cvt_pk_bf16_f32 v70, v137, v1
	v_lshlrev_b64 v[136:137], 1, v[142:143]
	v_lshl_add_u64 v[142:143], s[62:63], 0, v[136:137]
	v_lshl_add_u64 v[136:137], s[64:65], 0, v[136:137]
	global_store_short v[142:143], v70, off
	v_cvt_pk_bf16_f32 v70, v75, v1
	global_store_short v[136:137], v70, off
	v_add_u32_e32 v136, 2, v138
	v_ashrrev_i32_e32 v137, 31, v136
	v_lshlrev_b64 v[136:137], 10, v[136:137]
	v_or_b32_e32 v142, v136, v208
	v_mov_b32_e32 v143, v137
	v_lshlrev_b64 v[142:143], 1, v[142:143]
	v_cvt_pk_bf16_f32 v70, v156, v1
	v_lshl_add_u64 v[156:157], s[62:63], 0, v[142:143]
	v_lshl_add_u64 v[142:143], s[64:65], 0, v[142:143]
	v_rcp_f32_e32 v78, v78
	global_store_short v[156:157], v70, off
	v_cvt_pk_bf16_f32 v70, v80, v1
	global_store_short v[142:143], v70, off
	v_add_u32_e32 v142, 3, v138
	v_ashrrev_i32_e32 v143, 31, v142
	v_lshlrev_b64 v[142:143], 10, v[142:143]
	v_or_b32_e32 v156, v142, v208
	v_mov_b32_e32 v157, v143
	v_pk_mul_f32 v[78:79], v[78:79], v[182:183]
	v_lshlrev_b64 v[156:157], 1, v[156:157]
	v_pk_mul_f32 v[78:79], v[78:79], v[174:175]
	v_cvt_pk_bf16_f32 v70, v96, v1
	v_lshl_add_u64 v[174:175], s[62:63], 0, v[156:157]
	v_fma_f32 v125, v126, v123, v122
	global_store_short v[174:175], v70, off
	v_mul_f32_e32 v75, v126, v148
	v_mov_b32_e32 v126, v131
	v_mul_f32_e32 v70, v127, v125
	v_pk_fma_f32 v[174:175], v[126:127], v[124:125], v[70:71] op_sel_hi:[1,1,0]
	v_mov_b32_e32 v128, v135
	v_mov_b32_e32 v145, v174
	v_mul_f32_e32 v70, v127, v75
	v_pk_mul_f32 v[126:127], v[128:129], v[144:145]
	v_mul_f32_e32 v89, v129, v70
	v_add_f32_e32 v80, v126, v127
	ds_bpermute_b32 v93, v134, v89
	ds_bpermute_b32 v105, v134, v80
	v_cvt_pk_bf16_f32 v72, v77, v1
	v_lshl_add_u64 v[126:127], s[64:65], 0, v[156:157]
	global_store_short v[126:127], v72, off
	ds_bpermute_b32 v72, v134, v89 offset:64
	ds_bpermute_b32 v109, v134, v80 offset:64
	ds_bpermute_b32 v112, v134, v89 offset:128
	ds_bpermute_b32 v121, v134, v80 offset:128
	s_waitcnt lgkmcnt(4)
; __device__ __forceinline__ unsigned cvt_pk_bf16(float lo, float hi) { unsigned r; asm volatile("v_cvt_pk_bf16_f32 %0, %1, %2" : "=v"(r) : "v"(lo), "v"(hi)); return r; }
; template <int NT> ...
;     ...
;     for (int u = 0; u < NT; ++u) {
; #pragma unroll
;         for (int n = 0; n < 4; ++n) { const int ch = hc0 + 16 * n + fr;
;             float hl[4], pl[4];
;             hl[0] = bv[u][n][0]; pl[0] = av[u][n][0];
; #pragma unroll
;             for (int j = 1; j < 4; ++j) { hl[j] = av[u][n][j] * hl[j - 1] + bv[u][n][j]; pl[j] = av[u][n][j] * pl[j - 1]; }
;             float He = 0.f, Pe = 1.f;
; #pragma unroll
;             for (int g = 0; g < 3; ++g) { const float Pg = __shfl(pl[3], fr + 16 * g), Hg = __shfl(hl[3], fr + 16 * g); if (g < fq) { He = Pg * He + Hg; Pe = Pg * Pe; } }
;             const float Hin = Pe * Hc[n] + He, Pin = Pe * Pc[n];
;             float hf[4], pf[4];
; #pragma unroll
;             for (int j = 0; j < 4; ++j) { hf[j] = hl[j] + pl[j] * Hin; pf[j] = pl[j] * Pin; }
; #pragma unroll
;             for (int j = 0; j < 4; ++j) { const size_t o = (size_t)(m0 + 16 * u + 4 * fq + j) * D + ch; HLOC[o] = (bf16_t)(cvt_pk_bf16(hf[j], 0.f) & 0xffffu); PCUM[o] = (bf16_t)(cvt_pk_bf16(pf[j], 0.f) & 0xffffu); }
;             Hc[n] = __shfl(hf[3], fr + 48); Pc[n] = __shfl(pf[3], fr + 48);
;         } }
	v_fmac_f32_e32 v105, 0, v93
	v_cndmask_b32_e64 v105, v105, 0, s[8:9]
	v_cndmask_b32_e64 v93, v93, 1.0, s[8:9]
	s_waitcnt lgkmcnt(2)
	v_fmac_f32_e32 v109, v105, v72
	v_mul_f32_e32 v72, v93, v72
	v_cndmask_b32_e64 v105, v105, v109, s[4:5]
	v_cndmask_b32_e64 v72, v93, v72, s[4:5]
	s_waitcnt lgkmcnt(0)
	v_fmac_f32_e32 v121, v105, v112
	v_mul_f32_e32 v93, v72, v112
	v_cndmask_b32_e64 v105, v105, v121, s[6:7]
	v_cndmask_b32_e64 v72, v72, v93, s[6:7]
	v_fmac_f32_e32 v105, v71, v72
	v_mul_f32_e32 v71, v73, v72
	v_mul_f32_e32 v93, v148, v71
	v_fmac_f32_e32 v125, v75, v105
	v_mul_f32_e32 v75, v75, v71
	v_fmac_f32_e32 v174, v70, v105
	v_mul_f32_e32 v109, v70, v71
	v_fmac_f32_e32 v80, v89, v105
	v_mul_f32_e32 v89, v89, v71
	v_or_b32_e32 v70, v140, v214
	v_mov_b32_e32 v71, v141
	v_lshlrev_b64 v[70:71], 1, v[70:71]
	v_lshl_add_u64 v[72:73], s[62:63], 0, v[70:71]
	v_lshl_add_u64 v[70:71], s[64:65], 0, v[70:71]
	v_fmac_f32_e32 v123, v148, v105
	v_cvt_pk_bf16_f32 v105, v123, v1
	global_store_short v[72:73], v105, off
	v_cvt_pk_bf16_f32 v72, v93, v1
	global_store_short v[70:71], v72, off
	v_or_b32_e32 v70, v132, v214
	v_mov_b32_e32 v71, v133
	v_lshlrev_b64 v[70:71], 1, v[70:71]
	v_lshl_add_u64 v[72:73], s[62:63], 0, v[70:71]
	v_lshl_add_u64 v[70:71], s[64:65], 0, v[70:71]
	v_cvt_pk_bf16_f32 v93, v125, v1
	global_store_short v[72:73], v93, off
	v_cvt_pk_bf16_f32 v72, v75, v1
	global_store_short v[70:71], v72, off
	v_or_b32_e32 v70, v136, v214
	v_mov_b32_e32 v71, v137
	v_lshlrev_b64 v[70:71], 1, v[70:71]
	v_lshl_add_u64 v[72:73], s[62:63], 0, v[70:71]
	v_lshl_add_u64 v[70:71], s[64:65], 0, v[70:71]
	v_cvt_pk_bf16_f32 v75, v174, v1
	global_store_short v[72:73], v75, off
	v_cvt_pk_bf16_f32 v72, v109, v1
	global_store_short v[70:71], v72, off
	v_or_b32_e32 v70, v142, v214
	v_mov_b32_e32 v71, v143
	v_lshlrev_b64 v[70:71], 1, v[70:71]
	v_lshl_add_u64 v[72:73], s[62:63], 0, v[70:71]
	v_fma_f32 v121, v151, v119, v118
	v_cvt_pk_bf16_f32 v75, v80, v1
	global_store_short v[72:73], v75, off
	v_mov_b32_e32 v146, v114
	v_mul_f32_e32 v72, v147, v121
	v_pk_fma_f32 v[72:73], v[146:147], v[120:121], v[72:73] op_sel_hi:[1,1,0]
	v_mul_f32_e32 v93, v151, v160
	v_mov_b32_e32 v148, v116
	v_mov_b32_e32 v151, v72
	v_mul_f32_e32 v73, v147, v93
	v_pk_mul_f32 v[122:123], v[148:149], v[150:151]
	v_mul_f32_e32 v109, v149, v73
	v_add_f32_e32 v105, v122, v123
	ds_bpermute_b32 v112, v134, v109
	ds_bpermute_b32 v114, v134, v105
	v_lshl_add_u64 v[70:71], s[64:65], 0, v[70:71]
	v_cvt_pk_bf16_f32 v75, v89, v1
	global_store_short v[70:71], v75, off
	ds_bpermute_b32 v70, v134, v109 offset:64
	ds_bpermute_b32 v71, v134, v105 offset:64
	s_waitcnt lgkmcnt(2)
	v_fmac_f32_e32 v114, 0, v112
	ds_bpermute_b32 v75, v134, v80 offset:192
	ds_bpermute_b32 v80, v134, v89 offset:192
	v_cndmask_b32_e64 v89, v114, 0, s[8:9]
	ds_bpermute_b32 v114, v134, v109 offset:128
	ds_bpermute_b32 v116, v134, v105 offset:128
	v_cndmask_b32_e64 v112, v112, 1.0, s[8:9]
	s_waitcnt lgkmcnt(4)
	v_fmac_f32_e32 v71, v89, v70
	v_mul_f32_e32 v70, v112, v70
	v_cndmask_b32_e64 v71, v89, v71, s[4:5]
	v_cndmask_b32_e64 v70, v112, v70, s[4:5]
	s_waitcnt lgkmcnt(0)
	v_fmac_f32_e32 v116, v71, v114
	v_mul_f32_e32 v89, v70, v114
	v_cndmask_b32_e64 v71, v71, v116, s[6:7]
	v_cndmask_b32_e64 v70, v70, v89, s[6:7]
	v_fmac_f32_e32 v71, v66, v70
	v_mul_f32_e32 v66, v68, v70
	v_fmac_f32_e32 v119, v160, v71
	v_fmac_f32_e32 v121, v93, v71
	v_fmac_f32_e32 v72, v73, v71
	v_fmac_f32_e32 v105, v109, v71
	v_or_b32_e32 v70, v140, v212
	v_mov_b32_e32 v71, v141
	v_lshlrev_b64 v[70:71], 1, v[70:71]
	v_mul_f32_e32 v68, v160, v66
	v_mul_f32_e32 v89, v93, v66
	v_mul_f32_e32 v93, v73, v66
	v_mul_f32_e32 v114, v109, v66
	v_cvt_pk_bf16_f32 v66, v119, v1
	v_lshl_add_u64 v[118:119], s[62:63], 0, v[70:71]
	v_lshl_add_u64 v[70:71], s[64:65], 0, v[70:71]
	global_store_short v[118:119], v66, off
	v_cvt_pk_bf16_f32 v66, v68, v1
	global_store_short v[70:71], v66, off
	v_or_b32_e32 v70, v132, v212
	v_mov_b32_e32 v71, v133
	v_lshlrev_b64 v[70:71], 1, v[70:71]
	v_cvt_pk_bf16_f32 v66, v121, v1
	v_lshl_add_u64 v[118:119], s[62:63], 0, v[70:71]
	v_lshl_add_u64 v[70:71], s[64:65], 0, v[70:71]
	global_store_short v[118:119], v66, off
	v_cvt_pk_bf16_f32 v66, v89, v1
	global_store_short v[70:71], v66, off
	v_or_b32_e32 v70, v136, v212
	v_mov_b32_e32 v71, v137
	v_lshlrev_b64 v[70:71], 1, v[70:71]
	v_cvt_pk_bf16_f32 v66, v72, v1
	v_lshl_add_u64 v[72:73], s[62:63], 0, v[70:71]
	v_lshl_add_u64 v[70:71], s[64:65], 0, v[70:71]
	global_store_short v[72:73], v66, off
	v_cvt_pk_bf16_f32 v66, v93, v1
	global_store_short v[70:71], v66, off
	v_or_b32_e32 v70, v142, v212
	v_mov_b32_e32 v71, v143
	v_lshlrev_b64 v[70:71], 1, v[70:71]
	v_cvt_pk_bf16_f32 v66, v105, v1
	v_lshl_add_u64 v[72:73], s[62:63], 0, v[70:71]
	v_fma_f32 v109, v110, v107, v106
	global_store_short v[72:73], v66, off
	v_mul_f32_e32 v89, v110, v162
	v_mov_b32_e32 v110, v115
	v_mul_f32_e32 v66, v111, v109
	v_pk_fma_f32 v[72:73], v[110:111], v[108:109], v[66:67] op_sel_hi:[1,1,0]
	v_mov_b32_e32 v112, v117
	v_mov_b32_e32 v159, v72
	v_mul_f32_e32 v66, v111, v89
	v_pk_mul_f32 v[110:111], v[112:113], v[158:159]
	v_mul_f32_e32 v93, v113, v66
	v_add_f32_e32 v73, v110, v111
	ds_bpermute_b32 v106, v134, v93
	ds_bpermute_b32 v108, v134, v73
	v_cvt_pk_bf16_f32 v68, v114, v1
	v_lshl_add_u64 v[70:71], s[64:65], 0, v[70:71]
	global_store_short v[70:71], v68, off
	ds_bpermute_b32 v68, v134, v93 offset:64
	ds_bpermute_b32 v70, v134, v73 offset:64
	s_waitcnt lgkmcnt(2)
	v_fmac_f32_e32 v108, 0, v106
	ds_bpermute_b32 v110, v134, v105 offset:192
	v_cndmask_b32_e64 v71, v108, 0, s[8:9]
	v_cndmask_b32_e64 v105, v106, 1.0, s[8:9]
	ds_bpermute_b32 v106, v134, v93 offset:128
	ds_bpermute_b32 v108, v134, v73 offset:128
	s_waitcnt lgkmcnt(3)
; __device__ __forceinline__ unsigned cvt_pk_bf16(float lo, float hi) { unsigned r; asm volatile("v_cvt_pk_bf16_f32 %0, %1, %2" : "=v"(r) : "v"(lo), "v"(hi)); return r; }
; template <int NT> ...
;     ...
;     for (int u = 0; u < NT; ++u) {
; #pragma unroll
;         for (int n = 0; n < 4; ++n) { const int ch = hc0 + 16 * n + fr;
;             float hl[4], pl[4];
;             hl[0] = bv[u][n][0]; pl[0] = av[u][n][0];
; #pragma unroll
;             for (int j = 1; j < 4; ++j) { hl[j] = av[u][n][j] * hl[j - 1] + bv[u][n][j]; pl[j] = av[u][n][j] * pl[j - 1]; }
;             float He = 0.f, Pe = 1.f;
; #pragma unroll
;             for (int g = 0; g < 3; ++g) { const float Pg = __shfl(pl[3], fr + 16 * g), Hg = __shfl(hl[3], fr + 16 * g); if (g < fq) { He = Pg * He + Hg; Pe = Pg * Pe; } }
;             const float Hin = Pe * Hc[n] + He, Pin = Pe * Pc[n];
;             float hf[4], pf[4];
; #pragma unroll
;             for (int j = 0; j < 4; ++j) { hf[j] = hl[j] + pl[j] * Hin; pf[j] = pl[j] * Pin; }
; #pragma unroll
;             for (int j = 0; j < 4; ++j) { const size_t o = (size_t)(m0 + 16 * u + 4 * fq + j) * D + ch; HLOC[o] = (bf16_t)(cvt_pk_bf16(hf[j], 0.f) & 0xffffu); PCUM[o] = (bf16_t)(cvt_pk_bf16(pf[j], 0.f) & 0xffffu); }
;             Hc[n] = __shfl(hf[3], fr + 48); Pc[n] = __shfl(pf[3], fr + 48);
;         } }
	v_fmac_f32_e32 v70, v71, v68
	v_mul_f32_e32 v68, v105, v68
	v_cndmask_b32_e64 v70, v71, v70, s[4:5]
	v_cndmask_b32_e64 v68, v105, v68, s[4:5]
	s_waitcnt lgkmcnt(0)
	v_fmac_f32_e32 v108, v70, v106
	v_mul_f32_e32 v71, v68, v106
	v_cndmask_b32_e64 v70, v70, v108, s[6:7]
	v_cndmask_b32_e64 v68, v68, v71, s[6:7]
	v_fmac_f32_e32 v70, v67, v68
	v_mul_f32_e32 v67, v69, v68
	v_or_b32_e32 v140, v140, v210
	v_fmac_f32_e32 v107, v162, v70
	v_mul_f32_e32 v71, v162, v67
	v_fmac_f32_e32 v109, v89, v70
	v_mul_f32_e32 v89, v89, v67
	v_fmac_f32_e32 v72, v66, v70
	v_mul_f32_e32 v105, v66, v67
	v_fmac_f32_e32 v73, v93, v70
	v_mul_f32_e32 v70, v93, v67
	v_lshlrev_b64 v[66:67], 1, v[140:141]
	v_lshl_add_u64 v[68:69], s[62:63], 0, v[66:67]
	v_lshl_add_u64 v[66:67], s[64:65], 0, v[66:67]
	v_or_b32_e32 v132, v132, v210
	v_cvt_pk_bf16_f32 v93, v107, v1
	global_store_short v[68:69], v93, off
	v_cvt_pk_bf16_f32 v68, v71, v1
	global_store_short v[66:67], v68, off
	v_lshlrev_b64 v[66:67], 1, v[132:133]
	v_lshl_add_u64 v[68:69], s[62:63], 0, v[66:67]
	v_lshl_add_u64 v[66:67], s[64:65], 0, v[66:67]
	v_or_b32_e32 v136, v136, v210
	v_cvt_pk_bf16_f32 v71, v109, v1
	global_store_short v[68:69], v71, off
	v_cvt_pk_bf16_f32 v68, v89, v1
	global_store_short v[66:67], v68, off
	v_lshlrev_b64 v[66:67], 1, v[136:137]
	v_lshl_add_u64 v[68:69], s[62:63], 0, v[66:67]
	v_lshl_add_u64 v[66:67], s[64:65], 0, v[66:67]
	v_or_b32_e32 v142, v142, v210
	v_cvt_pk_bf16_f32 v71, v72, v1
	global_store_short v[68:69], v71, off
	v_cvt_pk_bf16_f32 v68, v105, v1
	global_store_short v[66:67], v68, off
	v_lshlrev_b64 v[66:67], 1, v[142:143]
	v_lshl_add_u64 v[68:69], s[62:63], 0, v[66:67]
	v_lshl_add_u64 v[66:67], s[64:65], 0, v[66:67]
	v_fma_f32 v105, v179, v102, v103
	v_cvt_pk_bf16_f32 v71, v73, v1
	global_store_short v[68:69], v71, off
	v_cvt_pk_bf16_f32 v68, v70, v1
	global_store_short v[66:67], v68, off
	v_mov_b32_e32 v160, v98
	v_mul_f32_e32 v66, v105, v161
	v_pk_fma_f32 v[66:67], v[104:105], v[160:161], v[66:67] op_sel_hi:[1,1,0]
	v_mul_f32_e32 v71, v179, v178
	v_mov_b32_e32 v165, v66
	v_mov_b32_e32 v162, v100
	v_mul_f32_e32 v67, v161, v71
	v_pk_mul_f32 v[68:69], v[164:165], v[162:163]
	ds_bpermute_b32 v112, v134, v73 offset:192
	v_add_f32_e32 v72, v68, v69
	v_mul_f32_e32 v73, v163, v67
	ds_bpermute_b32 v89, v134, v73
	ds_bpermute_b32 v93, v134, v72
	v_add_u32_e32 v68, 16, v138
	v_ashrrev_i32_e32 v69, 31, v68
	v_lshlrev_b64 v[106:107], 10, v[68:69]
	ds_bpermute_b32 v68, v134, v73 offset:64
	ds_bpermute_b32 v69, v134, v72 offset:64
	s_waitcnt lgkmcnt(2)
	v_fmac_f32_e32 v93, 0, v89
	ds_bpermute_b32 v98, v134, v70 offset:192
	v_cndmask_b32_e64 v70, v93, 0, s[8:9]
	ds_bpermute_b32 v93, v134, v73 offset:128
	ds_bpermute_b32 v100, v134, v72 offset:128
	ds_bpermute_b32 v96, v134, v96 offset:192
	ds_bpermute_b32 v77, v134, v77 offset:192
	v_cndmask_b32_e64 v89, v89, 1.0, s[8:9]
	s_waitcnt lgkmcnt(5)
	v_fmac_f32_e32 v69, v70, v68
	v_mul_f32_e32 v68, v89, v68
	v_cndmask_b32_e64 v69, v70, v69, s[4:5]
	v_cndmask_b32_e64 v68, v89, v68, s[4:5]
	s_waitcnt lgkmcnt(2)
	v_fmac_f32_e32 v100, v69, v93
	v_mul_f32_e32 v70, v68, v93
	v_cndmask_b32_e64 v69, v69, v100, s[6:7]
	v_cndmask_b32_e64 v68, v68, v70, s[6:7]
	s_waitcnt lgkmcnt(1)
	v_fmac_f32_e32 v69, v68, v96
	s_waitcnt lgkmcnt(0)
	v_mul_f32_e32 v68, v68, v77
	v_fmac_f32_e32 v102, v178, v69
	v_mul_f32_e32 v77, v178, v68
	v_fmac_f32_e32 v105, v71, v69
	v_mul_f32_e32 v89, v71, v68
	v_fmac_f32_e32 v66, v67, v69
	v_mul_f32_e32 v93, v67, v68
	v_fmac_f32_e32 v72, v73, v69
	v_mul_f32_e32 v73, v73, v68
	v_or_b32_e32 v68, v106, v208
	v_mov_b32_e32 v69, v107
	v_lshlrev_b64 v[68:69], 1, v[68:69]
	v_cvt_pk_bf16_f32 v67, v102, v1
	v_lshl_add_u64 v[70:71], s[62:63], 0, v[68:69]
	v_lshl_add_u64 v[68:69], s[64:65], 0, v[68:69]
	global_store_short v[70:71], v67, off
	v_cvt_pk_bf16_f32 v67, v77, v1
	global_store_short v[68:69], v67, off
	v_add_u32_e32 v68, 17, v138
	v_ashrrev_i32_e32 v69, 31, v68
	v_lshlrev_b64 v[102:103], 10, v[68:69]
	v_or_b32_e32 v68, v102, v208
	v_mov_b32_e32 v69, v103
	v_lshlrev_b64 v[68:69], 1, v[68:69]
	v_cvt_pk_bf16_f32 v67, v105, v1
	v_lshl_add_u64 v[70:71], s[62:63], 0, v[68:69]
	v_lshl_add_u64 v[68:69], s[64:65], 0, v[68:69]
	global_store_short v[70:71], v67, off
	v_cvt_pk_bf16_f32 v67, v89, v1
	global_store_short v[68:69], v67, off
	v_add_u32_e32 v68, 18, v138
	v_ashrrev_i32_e32 v69, 31, v68
	v_lshlrev_b64 v[104:105], 10, v[68:69]
	v_or_b32_e32 v68, v104, v208
	v_mov_b32_e32 v69, v105
	v_cvt_pk_bf16_f32 v70, v66, v1
	v_lshlrev_b64 v[66:67], 1, v[68:69]
	v_lshl_add_u64 v[68:69], s[62:63], 0, v[66:67]
	v_lshl_add_u64 v[66:67], s[64:65], 0, v[66:67]
	global_store_short v[68:69], v70, off
	v_cvt_pk_bf16_f32 v68, v93, v1
	global_store_short v[66:67], v68, off
	v_add_u32_e32 v66, 19, v138
	v_ashrrev_i32_e32 v67, 31, v66
	v_lshlrev_b64 v[108:109], 10, v[66:67]
	v_or_b32_e32 v66, v108, v208
	v_mov_b32_e32 v67, v109
	v_lshlrev_b64 v[66:67], 1, v[66:67]
	v_lshl_add_u64 v[68:69], s[62:63], 0, v[66:67]
	v_fma_f32 v93, v94, v90, v91
	v_cvt_pk_bf16_f32 v70, v72, v1
	global_store_short v[68:69], v70, off
	v_mul_f32_e32 v89, v94, v168
	v_mov_b32_e32 v94, v99
	v_mul_f32_e32 v68, v93, v95
	v_pk_fma_f32 v[68:69], v[92:93], v[94:95], v[68:69] op_sel_hi:[1,1,0]
	v_mov_b32_e32 v96, v101
	v_mov_b32_e32 v167, v68
	v_mul_f32_e32 v69, v95, v89
	v_pk_mul_f32 v[70:71], v[166:167], v[96:97]
	v_mul_f32_e32 v91, v97, v69
	v_add_f32_e32 v71, v70, v71
	ds_bpermute_b32 v92, v134, v91
	ds_bpermute_b32 v94, v134, v71
	v_lshl_add_u64 v[66:67], s[64:65], 0, v[66:67]
	v_cvt_pk_bf16_f32 v77, v73, v1
	global_store_short v[66:67], v77, off
	ds_bpermute_b32 v66, v134, v91 offset:64
	ds_bpermute_b32 v67, v134, v71 offset:64
	s_waitcnt lgkmcnt(2)
; __device__ __forceinline__ unsigned cvt_pk_bf16(float lo, float hi) { unsigned r; asm volatile("v_cvt_pk_bf16_f32 %0, %1, %2" : "=v"(r) : "v"(lo), "v"(hi)); return r; }
; template <int NT> ...
;     ...
;     for (int u = 0; u < NT; ++u) {
; #pragma unroll
;         for (int n = 0; n < 4; ++n) { const int ch = hc0 + 16 * n + fr;
;             float hl[4], pl[4];
;             hl[0] = bv[u][n][0]; pl[0] = av[u][n][0];
; #pragma unroll
;             for (int j = 1; j < 4; ++j) { hl[j] = av[u][n][j] * hl[j - 1] + bv[u][n][j]; pl[j] = av[u][n][j] * pl[j - 1]; }
;             float He = 0.f, Pe = 1.f;
; #pragma unroll
;             for (int g = 0; g < 3; ++g) { const float Pg = __shfl(pl[3], fr + 16 * g), Hg = __shfl(hl[3], fr + 16 * g); if (g < fq) { He = Pg * He + Hg; Pe = Pg * Pe; } }
;             const float Hin = Pe * Hc[n] + He, Pin = Pe * Pc[n];
;             float hf[4], pf[4];
; #pragma unroll
;             for (int j = 0; j < 4; ++j) { hf[j] = hl[j] + pl[j] * Hin; pf[j] = pl[j] * Pin; }
; #pragma unroll
;             for (int j = 0; j < 4; ++j) { const size_t o = (size_t)(m0 + 16 * u + 4 * fq + j) * D + ch; HLOC[o] = (bf16_t)(cvt_pk_bf16(hf[j], 0.f) & 0xffffu); PCUM[o] = (bf16_t)(cvt_pk_bf16(pf[j], 0.f) & 0xffffu); }
;             Hc[n] = __shfl(hf[3], fr + 48); Pc[n] = __shfl(pf[3], fr + 48);
;         } }
	v_fmac_f32_e32 v94, 0, v92
	ds_bpermute_b32 v70, v134, v72 offset:192
	ds_bpermute_b32 v72, v134, v73 offset:192
	v_cndmask_b32_e64 v73, v94, 0, s[8:9]
	v_cndmask_b32_e64 v77, v92, 1.0, s[8:9]
	ds_bpermute_b32 v92, v134, v91 offset:128
	ds_bpermute_b32 v94, v134, v71 offset:128
	s_waitcnt lgkmcnt(4)
	v_fmac_f32_e32 v67, v73, v66
	v_mul_f32_e32 v66, v77, v66
	v_cndmask_b32_e64 v67, v73, v67, s[4:5]
	v_cndmask_b32_e64 v66, v77, v66, s[4:5]
	s_waitcnt lgkmcnt(0)
	v_fmac_f32_e32 v94, v67, v92
	v_mul_f32_e32 v73, v66, v92
	v_cndmask_b32_e64 v67, v67, v94, s[6:7]
	v_cndmask_b32_e64 v66, v66, v73, s[6:7]
	v_fmac_f32_e32 v67, v66, v75
	v_mul_f32_e32 v66, v66, v80
	v_fmac_f32_e32 v90, v168, v67
	v_mul_f32_e32 v73, v168, v66
	v_fmac_f32_e32 v93, v89, v67
	v_mul_f32_e32 v75, v89, v66
	v_fmac_f32_e32 v68, v69, v67
	v_mul_f32_e32 v77, v69, v66
	v_fmac_f32_e32 v71, v91, v67
	v_mul_f32_e32 v80, v91, v66
	v_or_b32_e32 v66, v106, v214
	v_mov_b32_e32 v67, v107
	v_lshlrev_b64 v[66:67], 1, v[66:67]
	v_cvt_pk_bf16_f32 v69, v90, v1
	v_lshl_add_u64 v[90:91], s[62:63], 0, v[66:67]
	v_lshl_add_u64 v[66:67], s[64:65], 0, v[66:67]
	global_store_short v[90:91], v69, off
	v_cvt_pk_bf16_f32 v69, v73, v1
	global_store_short v[66:67], v69, off
	v_or_b32_e32 v66, v102, v214
	v_mov_b32_e32 v67, v103
	v_lshlrev_b64 v[66:67], 1, v[66:67]
	v_cvt_pk_bf16_f32 v69, v93, v1
	v_lshl_add_u64 v[90:91], s[62:63], 0, v[66:67]
	v_lshl_add_u64 v[66:67], s[64:65], 0, v[66:67]
	global_store_short v[90:91], v69, off
	v_cvt_pk_bf16_f32 v69, v75, v1
	global_store_short v[66:67], v69, off
	v_or_b32_e32 v66, v104, v214
	v_mov_b32_e32 v67, v105
	v_lshlrev_b64 v[66:67], 1, v[66:67]
	v_cvt_pk_bf16_f32 v73, v68, v1
	v_lshl_add_u64 v[68:69], s[62:63], 0, v[66:67]
	v_lshl_add_u64 v[66:67], s[64:65], 0, v[66:67]
	global_store_short v[68:69], v73, off
	v_cvt_pk_bf16_f32 v68, v77, v1
	global_store_short v[66:67], v68, off
	v_or_b32_e32 v66, v108, v214
	v_mov_b32_e32 v67, v109
	v_lshlrev_b64 v[66:67], 1, v[66:67]
	v_lshl_add_u64 v[68:69], s[62:63], 0, v[66:67]
	v_fma_f32 v89, v170, v86, v87
	v_cvt_pk_bf16_f32 v73, v71, v1
	global_store_short v[68:69], v73, off
	v_mov_b32_e32 v168, v82
	v_mul_f32_e32 v68, v89, v169
	v_pk_fma_f32 v[68:69], v[88:89], v[168:169], v[68:69] op_sel_hi:[1,1,0]
	v_mul_f32_e32 v77, v170, v180
	v_mov_b32_e32 v75, v68
	v_mov_b32_e32 v170, v84
	v_mul_f32_e32 v69, v169, v77
	v_pk_mul_f32 v[74:75], v[74:75], v[170:171]
	v_lshl_add_u64 v[66:67], s[64:65], 0, v[66:67]
	v_add_f32_e32 v82, v74, v75
	v_mul_f32_e32 v74, v171, v69
	ds_bpermute_b32 v75, v134, v74
	ds_bpermute_b32 v84, v134, v82
	v_cvt_pk_bf16_f32 v73, v80, v1
	global_store_short v[66:67], v73, off
	ds_bpermute_b32 v66, v134, v74 offset:64
	ds_bpermute_b32 v67, v134, v82 offset:64
	s_waitcnt lgkmcnt(2)
	v_fmac_f32_e32 v84, 0, v75
	ds_bpermute_b32 v73, v134, v80 offset:192
	v_cndmask_b32_e64 v80, v84, 0, s[8:9]
	ds_bpermute_b32 v84, v134, v74 offset:128
	ds_bpermute_b32 v87, v134, v82 offset:128
	ds_bpermute_b32 v111, v134, v114 offset:192
	v_cndmask_b32_e64 v75, v75, 1.0, s[8:9]
	s_waitcnt lgkmcnt(4)
	v_fmac_f32_e32 v67, v80, v66
	v_mul_f32_e32 v66, v75, v66
	v_cndmask_b32_e64 v67, v80, v67, s[4:5]
	v_cndmask_b32_e64 v66, v75, v66, s[4:5]
	s_waitcnt lgkmcnt(1)
	v_fmac_f32_e32 v87, v67, v84
	v_mul_f32_e32 v75, v66, v84
	v_cndmask_b32_e64 v67, v67, v87, s[6:7]
	v_cndmask_b32_e64 v66, v66, v75, s[6:7]
	v_fmac_f32_e32 v67, v66, v110
	s_waitcnt lgkmcnt(0)
; __device__ __forceinline__ unsigned cvt_pk_bf16(float lo, float hi) { unsigned r; asm volatile("v_cvt_pk_bf16_f32 %0, %1, %2" : "=v"(r) : "v"(lo), "v"(hi)); return r; }
; template <int NT> ...
;     ...
;     for (int u = 0; u < NT; ++u) {
; #pragma unroll
;         for (int n = 0; n < 4; ++n) { const int ch = hc0 + 16 * n + fr;
;             float hl[4], pl[4];
;             hl[0] = bv[u][n][0]; pl[0] = av[u][n][0];
; #pragma unroll
;             for (int j = 1; j < 4; ++j) { hl[j] = av[u][n][j] * hl[j - 1] + bv[u][n][j]; pl[j] = av[u][n][j] * pl[j - 1]; }
;             float He = 0.f, Pe = 1.f;
; #pragma unroll
;             for (int g = 0; g < 3; ++g) { const float Pg = __shfl(pl[3], fr + 16 * g), Hg = __shfl(hl[3], fr + 16 * g); if (g < fq) { He = Pg * He + Hg; Pe = Pg * Pe; } }
;             const float Hin = Pe * Hc[n] + He, Pin = Pe * Pc[n];
;             float hf[4], pf[4];
; #pragma unroll
;             for (int j = 0; j < 4; ++j) { hf[j] = hl[j] + pl[j] * Hin; pf[j] = pl[j] * Pin; }
; #pragma unroll
;             for (int j = 0; j < 4; ++j) { const size_t o = (size_t)(m0 + 16 * u + 4 * fq + j) * D + ch; HLOC[o] = (bf16_t)(cvt_pk_bf16(hf[j], 0.f) & 0xffffu); PCUM[o] = (bf16_t)(cvt_pk_bf16(pf[j], 0.f) & 0xffffu); }
;             Hc[n] = __shfl(hf[3], fr + 48); Pc[n] = __shfl(pf[3], fr + 48);
;         } }
; __device__ __forceinline__ void scan_phase(KP p, int l, LAS unsigned char* lds) {
;     ...
;             for (int tt = 0; tt < 8; tt += 2) scan_tiles<2>(p, l, P, HLOC, PCUM, XC, CST, Wa, Wx, b, hc0, (tile0 + tt) * 16, lane, fr, fq, Hc, Pc);
	v_mul_f32_e32 v66, v66, v111
	v_fmac_f32_e32 v86, v180, v67
	v_mul_f32_e32 v80, v180, v66
	v_fmac_f32_e32 v89, v77, v67
	v_mul_f32_e32 v77, v77, v66
	v_fmac_f32_e32 v68, v69, v67
	v_mul_f32_e32 v84, v69, v66
	v_fmac_f32_e32 v82, v74, v67
	v_mul_f32_e32 v87, v74, v66
	v_or_b32_e32 v66, v106, v212
	v_mov_b32_e32 v67, v107
	v_lshlrev_b64 v[66:67], 1, v[66:67]
	v_cvt_pk_bf16_f32 v69, v86, v1
	v_lshl_add_u64 v[74:75], s[62:63], 0, v[66:67]
	v_lshl_add_u64 v[66:67], s[64:65], 0, v[66:67]
	global_store_short v[74:75], v69, off
	v_cvt_pk_bf16_f32 v69, v80, v1
	global_store_short v[66:67], v69, off
	v_or_b32_e32 v66, v102, v212
	v_mov_b32_e32 v67, v103
	v_lshlrev_b64 v[66:67], 1, v[66:67]
	v_cvt_pk_bf16_f32 v69, v89, v1
	v_lshl_add_u64 v[74:75], s[62:63], 0, v[66:67]
	v_lshl_add_u64 v[66:67], s[64:65], 0, v[66:67]
	global_store_short v[74:75], v69, off
	v_cvt_pk_bf16_f32 v69, v77, v1
	global_store_short v[66:67], v69, off
	v_or_b32_e32 v66, v104, v212
	v_mov_b32_e32 v67, v105
	v_lshlrev_b64 v[66:67], 1, v[66:67]
	v_cvt_pk_bf16_f32 v74, v68, v1
	v_lshl_add_u64 v[68:69], s[62:63], 0, v[66:67]
	v_lshl_add_u64 v[66:67], s[64:65], 0, v[66:67]
	global_store_short v[68:69], v74, off
	v_cvt_pk_bf16_f32 v68, v84, v1
	global_store_short v[66:67], v68, off
	v_or_b32_e32 v66, v108, v212
	v_mov_b32_e32 v67, v109
	v_lshlrev_b64 v[66:67], 1, v[66:67]
	v_lshl_add_u64 v[68:69], s[62:63], 0, v[66:67]
	v_fma_f32 v77, v154, v78, v79
	v_cvt_pk_bf16_f32 v74, v82, v1
	global_store_short v[68:69], v74, off
	v_mov_b32_e32 v172, v83
	v_mul_f32_e32 v68, v77, v173
	v_pk_fma_f32 v[74:75], v[76:77], v[172:173], v[68:69] op_sel_hi:[1,1,0]
	v_mul_f32_e32 v79, v154, v152
	v_mov_b32_e32 v131, v74
	v_mov_b32_e32 v80, v85
	v_mul_f32_e32 v75, v173, v79
	v_pk_mul_f32 v[68:69], v[130:131], v[80:81]
	v_mul_f32_e32 v76, v81, v75
	v_add_f32_e32 v69, v68, v69
	ds_bpermute_b32 v80, v134, v76
	ds_bpermute_b32 v81, v134, v69
	v_lshl_add_u64 v[66:67], s[64:65], 0, v[66:67]
	v_cvt_pk_bf16_f32 v84, v87, v1
	global_store_short v[66:67], v84, off
	ds_bpermute_b32 v66, v134, v82 offset:192
	ds_bpermute_b32 v67, v134, v76 offset:64
	ds_bpermute_b32 v82, v134, v69 offset:64
	ds_bpermute_b32 v83, v134, v76 offset:128
	ds_bpermute_b32 v84, v134, v69 offset:128
	s_waitcnt lgkmcnt(5)
	v_fmac_f32_e32 v81, 0, v80
	v_cndmask_b32_e64 v81, v81, 0, s[8:9]
	v_cndmask_b32_e64 v80, v80, 1.0, s[8:9]
	s_waitcnt lgkmcnt(2)
	v_fmac_f32_e32 v82, v81, v67
	v_mul_f32_e32 v67, v80, v67
	v_cndmask_b32_e64 v81, v81, v82, s[4:5]
	v_cndmask_b32_e64 v67, v80, v67, s[4:5]
	s_waitcnt lgkmcnt(0)
	v_fmac_f32_e32 v84, v81, v83
	v_mul_f32_e32 v80, v67, v83
	v_cndmask_b32_e64 v81, v81, v84, s[6:7]
	v_cndmask_b32_e64 v67, v67, v80, s[6:7]
	v_fmac_f32_e32 v81, v67, v112
	v_mul_f32_e32 v67, v67, v98
	v_fmac_f32_e32 v78, v152, v81
	v_or_b32_e32 v106, v106, v210
	v_mul_f32_e32 v82, v152, v67
	v_fmac_f32_e32 v77, v79, v81
	v_mul_f32_e32 v83, v79, v67
	v_mul_f32_e32 v84, v75, v67
	v_mul_f32_e32 v85, v76, v67
	v_cvt_pk_bf16_f32 v67, v78, v1
	v_lshlrev_b64 v[78:79], 1, v[106:107]
	v_fmac_f32_e32 v74, v75, v81
	v_fmac_f32_e32 v69, v76, v81
	v_lshl_add_u64 v[80:81], s[62:63], 0, v[78:79]
	global_store_short v[80:81], v67, off
	v_cvt_pk_bf16_f32 v67, v82, v1
	v_lshl_add_u64 v[78:79], s[64:65], 0, v[78:79]
	v_or_b32_e32 v102, v102, v210
	global_store_short v[78:79], v67, off
	v_cvt_pk_bf16_f32 v67, v77, v1
	v_lshlrev_b64 v[76:77], 1, v[102:103]
	v_lshl_add_u64 v[78:79], s[62:63], 0, v[76:77]
	global_store_short v[78:79], v67, off
	v_cvt_pk_bf16_f32 v67, v83, v1
	v_lshl_add_u64 v[76:77], s[64:65], 0, v[76:77]
	v_or_b32_e32 v104, v104, v210
	global_store_short v[76:77], v67, off
	v_cvt_pk_bf16_f32 v67, v74, v1
	v_lshlrev_b64 v[74:75], 1, v[104:105]
	v_lshl_add_u64 v[76:77], s[62:63], 0, v[74:75]
	v_lshl_add_u64 v[74:75], s[64:65], 0, v[74:75]
	v_or_b32_e32 v108, v108, v210
	global_store_short v[76:77], v67, off
	v_cvt_pk_bf16_f32 v67, v84, v1
	global_store_short v[74:75], v67, off
	v_lshlrev_b64 v[74:75], 1, v[108:109]
	v_cvt_pk_bf16_f32 v67, v69, v1
	v_lshl_add_u64 v[76:77], s[62:63], 0, v[74:75]
	global_store_short v[76:77], v67, off
	v_cvt_pk_bf16_f32 v67, v85, v1
	v_lshl_add_u64 v[74:75], s[64:65], 0, v[74:75]
	ds_bpermute_b32 v71, v134, v71 offset:192
	ds_bpermute_b32 v68, v134, v87 offset:192
	global_store_short v[74:75], v67, off
	ds_bpermute_b32 v67, v134, v69 offset:192
	ds_bpermute_b32 v69, v134, v85 offset:192
	v_add_u32_e32 v242, 32, v242
	v_subrev_u32_e32 v245, 32, v245
	s_cbranch_scc1 .LBB0_342

; #define LAS __attribute__((address_space(3)))
; __device__ __forceinline__ unsigned cvt_pk_bf16(float lo, float hi) { unsigned r; asm volatile("v_cvt_pk_bf16_f32 %0, %1, %2" : "=v"(r) : "v"(lo), "v"(hi)); return r; }
; #define LDS_WAIT() asm volatile("s_waitcnt lgkmcnt(0)" ::: "memory")
; template <int NT> ...
;     ...
;     for (int u = 0; u < NT; ++u) { const int m = m0 + 16 * u + rr, t = m - b * TP; LAS float* XC = XCb + u * (16 * 68);
;         float xv[4][16];
; #pragma unroll
;         for (int k = 0; k < 4; ++k) { float f0[8], f1[8]; unpack8(raw[u][k][0], f0); unpack8(raw[u][k][1], f1);
; #pragma unroll
;             for (int e = 0; e < 8; ++e) { xv[k][e] = f0[e]; xv[k][8 + e] = f1[e]; } }
;         if (t >= TP - 3) { float* o = p->out + O_PCB + ((size_t)(l * NB + b) * 3 + (t - (TP - 3))) * D + hc0 + cl;
; #pragma unroll
;             for (int e = 0; e < 16; e += 4) *(f32x4*)(o + e) = (f32x4){xv[3][e], xv[3][e + 1], xv[3][e + 2], xv[3][e + 3]}; }
; #pragma unroll
;         for (int e = 0; e < 16; e += 4) {
;             const f32x4 w0 = *(const LAS f32x4*)(CST + 0 * 64 + cl + e), w1 = *(const LAS f32x4*)(CST + 1 * 64 + cl + e), w2 = *(const LAS f32x4*)(CST + 2 * 64 + cl + e),
;                         w3 = *(const LAS f32x4*)(CST + 3 * 64 + cl + e), bb = *(const LAS f32x4*)(CST + 4 * 64 + cl + e);
;             f32x4 r;
; #pragma unroll
;             for (int q = 0; q < 4; ++q) r[q] = w0[q] * xv[0][e + q] + w1[q] * xv[1][e + q] + w2[q] * xv[2][e + q] + w3[q] * xv[3][e + q] + bb[q];
;             *(LAS f32x4*)(XC + rr * 68 + cl + e) = r;
;         } }
;     LDS_WAIT();
;     f32x4 ar[NT][4], ai[NT][4];
; #pragma unroll
;     for (int u = 0; u < NT; ++u) { const LAS float* XC = XCb + u * (16 * 68);
; #pragma unroll
;         for (int n = 0; n < 4; ++n) { ar[u][n] = (f32x4){0.f, 0.f, 0.f, 0.f}; ai[u][n] = (f32x4){0.f, 0.f, 0.f, 0.f}; }
; #pragma unroll
;         for (int s = 0; s < 2; ++s) {
;             const f32x4 x0 = *(const LAS f32x4*)(XC + fr * 68 + 32 * s + 8 * fq), x1 = *(const LAS f32x4*)(XC + fr * 68 + 32 * s + 8 * fq + 4);
;             u32x4 aw; aw.x = cvt_pk_bf16(x0[0], x0[1]); aw.y = cvt_pk_bf16(x0[2], x0[3]); aw.z = cvt_pk_bf16(x1[0], x1[1]); aw.w = cvt_pk_bf16(x1[2], x1[3]);
;             const bf16x8 af = __builtin_bit_cast(bf16x8, aw);
.LBB0_353:
	s_or_b64 exec, exec, s[10:11]
	ds_read_b128 v[114:117], v227 offset:8704
	ds_read_b128 v[118:121], v227 offset:8960
	ds_read_b128 v[122:125], v227 offset:9216
	ds_read_b128 v[126:129], v227 offset:9472
	ds_read_b128 v[130:133], v227 offset:9728
	v_lshlrev_b32_e32 v138, 16, v86
	v_and_b32_e32 v139, 0xffff0000, v86
	v_lshlrev_b32_e32 v86, 16, v87
	v_and_b32_e32 v87, 0xffff0000, v87
	v_lshlrev_b32_e32 v140, 16, v82
	v_and_b32_e32 v141, 0xffff0000, v82
	s_waitcnt lgkmcnt(3)
	v_pk_mul_f32 v[118:119], v[118:119], v[138:139]
	v_lshlrev_b32_e32 v82, 16, v83
	v_and_b32_e32 v83, 0xffff0000, v83
	v_pk_mul_f32 v[86:87], v[120:121], v[86:87]
	v_lshlrev_b32_e32 v136, 16, v98
	v_and_b32_e32 v137, 0xffff0000, v98
	v_pk_fma_f32 v[114:115], v[114:115], v[140:141], v[118:119]
	v_lshlrev_b32_e32 v98, 16, v99
	v_and_b32_e32 v99, 0xffff0000, v99
	v_pk_fma_f32 v[82:83], v[116:117], v[82:83], v[86:87]
	s_waitcnt lgkmcnt(2)
	v_pk_fma_f32 v[114:115], v[122:123], v[136:137], v[114:115]
	v_pk_fma_f32 v[82:83], v[124:125], v[98:99], v[82:83]
	s_waitcnt lgkmcnt(1)
	v_pk_fma_f32 v[110:111], v[126:127], v[110:111], v[114:115]
	v_pk_fma_f32 v[82:83], v[128:129], v[112:113], v[82:83]
	s_waitcnt lgkmcnt(0)
	v_pk_add_f32 v[110:111], v[130:131], v[110:111]
	v_pk_add_f32 v[112:113], v[132:133], v[82:83]
	ds_write_b128 v240, v[110:113]
	ds_read_b128 v[110:113], v227 offset:8720
	ds_read_b128 v[114:117], v227 offset:8976
	ds_read_b128 v[118:121], v227 offset:9232
	ds_read_b128 v[122:125], v227 offset:9488
	ds_read_b128 v[126:129], v227 offset:9744
	v_lshlrev_b32_e32 v86, 16, v88
	v_and_b32_e32 v87, 0xffff0000, v88
	v_lshlrev_b32_e32 v98, 16, v84
	v_and_b32_e32 v99, 0xffff0000, v84
	s_waitcnt lgkmcnt(3)
	v_pk_mul_f32 v[86:87], v[114:115], v[86:87]
	v_lshlrev_b32_e32 v88, 16, v89
	v_and_b32_e32 v89, 0xffff0000, v89
	v_lshlrev_b32_e32 v82, 16, v100
	v_and_b32_e32 v83, 0xffff0000, v100
	v_pk_fma_f32 v[86:87], v[110:111], v[98:99], v[86:87]
	v_lshlrev_b32_e32 v84, 16, v85
	v_and_b32_e32 v85, 0xffff0000, v85
	v_pk_mul_f32 v[88:89], v[116:117], v[88:89]
	s_waitcnt lgkmcnt(2)
	v_pk_fma_f32 v[82:83], v[118:119], v[82:83], v[86:87]
	v_lshlrev_b32_e32 v86, 16, v101
	v_and_b32_e32 v87, 0xffff0000, v101
	v_pk_fma_f32 v[84:85], v[112:113], v[84:85], v[88:89]
	s_waitcnt lgkmcnt(1)
	v_pk_fma_f32 v[82:83], v[122:123], v[106:107], v[82:83]
	v_pk_fma_f32 v[84:85], v[120:121], v[86:87], v[84:85]
	s_waitcnt lgkmcnt(0)
	v_pk_add_f32 v[82:83], v[126:127], v[82:83]
	v_pk_fma_f32 v[84:85], v[124:125], v[108:109], v[84:85]
	v_lshlrev_b32_e32 v116, 16, v78
	v_pk_add_f32 v[84:85], v[128:129], v[84:85]
	ds_write_b128 v240, v[82:85] offset:16
	ds_read_b128 v[82:85], v227 offset:8736
	ds_read_b128 v[86:89], v227 offset:8992
	ds_read_b128 v[98:101], v227 offset:9248
	ds_read_b128 v[106:109], v227 offset:9504
	ds_read_b128 v[110:113], v227 offset:9760
	v_and_b32_e32 v117, 0xffff0000, v78
	v_lshlrev_b32_e32 v78, 16, v79
	v_and_b32_e32 v79, 0xffff0000, v79
	v_lshlrev_b32_e32 v118, 16, v74
	v_and_b32_e32 v119, 0xffff0000, v74
	s_waitcnt lgkmcnt(3)
	v_pk_mul_f32 v[86:87], v[86:87], v[116:117]
	v_lshlrev_b32_e32 v74, 16, v75
	v_and_b32_e32 v75, 0xffff0000, v75
	v_pk_mul_f32 v[78:79], v[88:89], v[78:79]
	v_lshlrev_b32_e32 v114, 16, v90
	v_and_b32_e32 v115, 0xffff0000, v90
	v_pk_fma_f32 v[82:83], v[82:83], v[118:119], v[86:87]
	v_lshlrev_b32_e32 v86, 16, v91
	v_and_b32_e32 v87, 0xffff0000, v91
	v_pk_fma_f32 v[74:75], v[84:85], v[74:75], v[78:79]
	s_waitcnt lgkmcnt(2)
	v_pk_fma_f32 v[82:83], v[98:99], v[114:115], v[82:83]
	v_pk_fma_f32 v[74:75], v[100:101], v[86:87], v[74:75]
	s_waitcnt lgkmcnt(1)
	v_pk_fma_f32 v[82:83], v[106:107], v[102:103], v[82:83]
	v_pk_fma_f32 v[74:75], v[108:109], v[104:105], v[74:75]
	s_waitcnt lgkmcnt(0)
	v_pk_add_f32 v[82:83], v[110:111], v[82:83]
	v_pk_add_f32 v[84:85], v[112:113], v[74:75]
	ds_write_b128 v240, v[82:85] offset:32
	ds_read_b128 v[82:85], v227 offset:8752
	ds_read_b128 v[86:89], v227 offset:9008
	ds_read_b128 v[98:101], v227 offset:9264
	ds_read_b128 v[102:105], v227 offset:9520
	ds_read_b128 v[106:109], v227 offset:9776
	v_lshlrev_b32_e32 v78, 16, v80
	v_and_b32_e32 v79, 0xffff0000, v80
	v_lshlrev_b32_e32 v90, 16, v76
	v_and_b32_e32 v91, 0xffff0000, v76
	s_waitcnt lgkmcnt(3)
	v_pk_mul_f32 v[78:79], v[86:87], v[78:79]
	v_lshlrev_b32_e32 v80, 16, v81
	v_and_b32_e32 v81, 0xffff0000, v81
	v_lshlrev_b32_e32 v74, 16, v92
	v_and_b32_e32 v75, 0xffff0000, v92
	v_pk_fma_f32 v[78:79], v[82:83], v[90:91], v[78:79]
	v_lshlrev_b32_e32 v76, 16, v77
	v_and_b32_e32 v77, 0xffff0000, v77
	v_pk_mul_f32 v[80:81], v[88:89], v[80:81]
	s_waitcnt lgkmcnt(2)
	v_pk_fma_f32 v[74:75], v[98:99], v[74:75], v[78:79]
	v_lshlrev_b32_e32 v78, 16, v93
	v_and_b32_e32 v79, 0xffff0000, v93
	v_pk_fma_f32 v[76:77], v[84:85], v[76:77], v[80:81]
	s_waitcnt lgkmcnt(1)
	v_pk_fma_f32 v[74:75], v[102:103], v[94:95], v[74:75]
	v_pk_fma_f32 v[76:77], v[100:101], v[78:79], v[76:77]
	s_waitcnt lgkmcnt(0)
	v_pk_add_f32 v[74:75], v[106:107], v[74:75]
	v_pk_fma_f32 v[76:77], v[104:105], v[96:97], v[76:77]
	s_add_i32 s12, s18, s12
	v_pk_add_f32 v[76:77], v[108:109], v[76:77]
	ds_write_b128 v240, v[74:77] offset:48
	s_waitcnt lgkmcnt(0)
	ds_read_b128 v[74:77], v239
	ds_read_b128 v[78:81], v239 offset:16
	s_waitcnt lgkmcnt(1)
	v_cvt_pk_bf16_f32 v74, v74, v75
	v_cvt_pk_bf16_f32 v75, v76, v77
	s_waitcnt lgkmcnt(0)
; #define LAS __attribute__((address_space(3)))
; __device__ __forceinline__ unsigned cvt_pk_bf16(float lo, float hi) { unsigned r; asm volatile("v_cvt_pk_bf16_f32 %0, %1, %2" : "=v"(r) : "v"(lo), "v"(hi)); return r; }
; __device__ __forceinline__ float sigmoidf_(float x) { return __builtin_amdgcn_rcpf(1.0f + __expf(-x)); }
; template <int NT> ...
;     ...
;     for (int u = 0; u < NT; ++u) { const LAS float* XC = XCb + u * (16 * 68);
; #pragma unroll
;         for (int n = 0; n < 4; ++n) { ar[u][n] = (f32x4){0.f, 0.f, 0.f, 0.f}; ai[u][n] = (f32x4){0.f, 0.f, 0.f, 0.f}; }
; #pragma unroll
;         for (int s = 0; s < 2; ++s) {
;             const f32x4 x0 = *(const LAS f32x4*)(XC + fr * 68 + 32 * s + 8 * fq), x1 = *(const LAS f32x4*)(XC + fr * 68 + 32 * s + 8 * fq + 4);
;             u32x4 aw; aw.x = cvt_pk_bf16(x0[0], x0[1]); aw.y = cvt_pk_bf16(x0[2], x0[3]); aw.z = cvt_pk_bf16(x1[0], x1[1]); aw.w = cvt_pk_bf16(x1[2], x1[3]);
;             const bf16x8 af = __builtin_bit_cast(bf16x8, aw);
; #pragma unroll
;             for (int n = 0; n < 4; ++n) { ar[u][n] = __builtin_amdgcn_mfma_f32_16x16x32_bf16(af, Wa[n][s], ar[u][n], 0, 0, 0); ai[u][n] = __builtin_amdgcn_mfma_f32_16x16x32_bf16(af, Wx[n][s], ai[u][n], 0, 0, 0); }
;         } }
;     float av[NT][4][4], bv[NT][4][4];
; #pragma unroll
;     for (int u = 0; u < NT; ++u) { const LAS float* XC = XCb + u * (16 * 68); const int t0 = m0 + 16 * u - b * TP;
; #pragma unroll
;         for (int n = 0; n < 4; ++n) { const int cc = 16 * n + fr;
;             const float ba = CST[5 * 64 + cc], bx = CST[6 * 64 + cc], sp = CST[7 * 64 + cc];
; #pragma unroll
;             for (int j = 0; j < 4; ++j) {
;                 const float xc = XC[(4 * fq + j) * 68 + cc];
;                 const float r = sigmoidf_(ar[u][n][j] + ba), ig = sigmoidf_(ai[u][n][j] + bx);
;                 const float a = __expf(-8.0f * r * sp);
;                 float mult = sqrtf(fmaxf(1.0f - a * a, 0.f));
;                 if (t0 + 4 * fq + j == 0) mult = 1.0f;
;                 av[u][n][j] = a; bv[u][n][j] = mult * ig * xc; } } }
	v_cvt_pk_bf16_f32 v76, v78, v79
	v_cvt_pk_bf16_f32 v77, v80, v81
	s_nop 0
	v_mfma_f32_16x16x32_bf16 v[78:81], v[74:77], v[54:57], 0
	ds_read_b128 v[54:57], v239 offset:128
	ds_read_b128 v[82:85], v239 offset:144
	v_mfma_f32_16x16x32_bf16 v[34:37], v[74:77], v[34:37], 0
	v_mfma_f32_16x16x32_bf16 v[42:45], v[74:77], v[42:45], 0
	v_mfma_f32_16x16x32_bf16 v[46:49], v[74:77], v[46:49], 0
	v_mfma_f32_16x16x32_bf16 v[38:41], v[74:77], v[38:41], 0
	v_mfma_f32_16x16x32_bf16 v[50:53], v[74:77], v[50:53], 0
	v_mfma_f32_16x16x32_bf16 v[62:65], v[74:77], v[62:65], 0
	v_mfma_f32_16x16x32_bf16 v[58:61], v[74:77], v[58:61], 0
	s_waitcnt lgkmcnt(1)
	v_cvt_pk_bf16_f32 v74, v54, v55
	v_cvt_pk_bf16_f32 v75, v56, v57
	s_waitcnt lgkmcnt(0)
	v_cvt_pk_bf16_f32 v76, v82, v83
	v_cvt_pk_bf16_f32 v77, v84, v85
	v_or_b32_e32 v55, 64, v134
	v_mfma_f32_16x16x32_bf16 v[82:85], v[74:77], v[10:13], v[34:37]
	v_or_b32_e32 v54, 0x80, v134
	v_mfma_f32_16x16x32_bf16 v[34:37], v[74:77], v[22:25], v[42:45]
	v_mfma_f32_16x16x32_bf16 v[22:25], v[74:77], v[26:29], v[46:49]
	ds_read2_b32 v[28:29], v177 offset0:192 offset1:208
	s_nop 0
	ds_read2_b32 v[42:43], v241 offset1:16
	s_waitcnt lgkmcnt(1)
	s_nop 0
	v_add_f32_e32 v0, v82, v28
	v_mul_f32_e32 v0, 0xbfb8aa3b, v0
	v_mfma_f32_16x16x32_bf16 v[10:13], v[74:77], v[18:21], v[78:81]
	v_exp_f32_e32 v18, v0
	ds_read2_b32 v[46:47], v241 offset0:68 offset1:84
	v_add_f32_e32 v34, v34, v29
	v_mfma_f32_16x16x32_bf16 v[86:89], v[74:77], v[14:17], v[38:41]
	v_add_f32_e32 v18, 1.0, v18
	v_rcp_f32_e32 v18, v18
	v_mul_f32_e32 v34, 0xbfb8aa3b, v34
	ds_read2_b32 v[38:39], v176 offset0:64 offset1:80
	ds_read2_b32 v[40:41], v176 offset1:16
	v_mul_f32_e32 v18, 0xc1000000, v18
	v_mfma_f32_16x16x32_bf16 v[14:17], v[74:77], v[30:33], v[50:53]
	v_exp_f32_e32 v34, v34
	s_waitcnt lgkmcnt(1)
	v_mul_f32_e32 v18, v38, v18
	v_mul_f32_e32 v18, 0x3fb8aa3b, v18
	v_exp_f32_e32 v44, v18
	s_waitcnt lgkmcnt(0)
	v_add_f32_e32 v18, v86, v40
	v_mul_f32_e32 v18, 0xbfb8aa3b, v18
	v_exp_f32_e32 v18, v18
	v_fma_f32 v19, -v44, v44, 1.0
	v_max_f32_e32 v19, 0, v19
	s_nop 0
	s_nop 0
	v_add_f32_e32 v18, 1.0, v18
	v_add_f32_e32 v34, 1.0, v34
	v_mov_b32_e32 v20, v19
	s_nop 0
	v_rcp_f32_e32 v19, v18
	v_rcp_f32_e32 v34, v34
	v_add_f32_e32 v22, v22, v41
	s_nop 0
	s_nop 0
	s_nop 0
	s_nop 0
	v_mul_f32_e32 v34, 0xc1000000, v34
	s_nop 0
	s_nop 0
	s_nop 0
	v_mul_f32_e32 v34, v39, v34
	v_mul_f32_e32 v34, 0x3fb8aa3b, v34
	s_nop 0
	v_add_f32_e32 v26, v83, v28
	v_mul_f32_e32 v26, 0xbfb8aa3b, v26
	v_exp_f32_e32 v26, v26
	s_nop 0
	s_nop 0
	s_nop 0
	v_or_b32_e32 v21, s12, v224
	v_exp_f32_e32 v56, v34
	v_sqrt_f32_e32 v18, v20
	s_nop 0
	v_add_f32_e32 v20, 1.0, v26
	v_rcp_f32_e32 v20, v20
	v_cmp_eq_u32_e32 vcc, 0, v21
	v_fma_f32 v34, -v56, v56, 1.0
	v_max_f32_e32 v34, 0, v34
	v_cndmask_b32_e64 v21, v18, 1.0, vcc
	v_mul_f32_e32 v18, 0xc1000000, v20
	v_mul_f32_e32 v18, v38, v18
	v_mul_f32_e32 v18, 0x3fb8aa3b, v18
	v_exp_f32_e32 v30, v18
	v_add_f32_e32 v18, v87, v40
	v_mul_f32_e32 v18, 0xbfb8aa3b, v18
	v_exp_f32_e32 v18, v18
	v_fma_f32 v20, -v30, v30, 1.0
	v_max_f32_e32 v20, 0, v20
	s_nop 0
	s_nop 0
	v_add_f32_e32 v18, 1.0, v18
	v_rcp_f32_e32 v18, v18
	s_nop 0
	s_nop 0
	v_mul_f32_e32 v22, 0xbfb8aa3b, v22
	v_exp_f32_e32 v22, v22
	v_add_f32_e32 v35, v35, v29
	s_nop 0
	s_nop 0
	s_nop 0
	s_nop 0
	v_mul_f32_e32 v35, 0xbfb8aa3b, v35
	s_nop 0
	s_nop 0
	s_nop 0
	v_exp_f32_e32 v35, v35
	v_add_f32_e32 v22, 1.0, v22
	s_nop 0
	s_nop 0
	s_nop 0
	v_add_f32_e32 v27, v84, v28
	v_mul_f32_e32 v27, 0xbfb8aa3b, v27
	v_exp_f32_e32 v27, v27
	s_nop 0
	v_add_f32_e32 v28, v85, v28
	v_mul_f32_e32 v28, 0xbfb8aa3b, v28
	v_sqrt_f32_e32 v20, v20
	s_nop 0
	v_pk_mul_f32 v[18:19], v[18:19], v[20:21]
	v_add_f32_e32 v20, 1.0, v27
	v_rcp_f32_e32 v26, v20
	v_mov_b32_e32 v20, v46
	v_mov_b32_e32 v21, v42
	v_pk_mul_f32 v[20:21], v[20:21], v[18:19]
	v_mul_f32_e32 v18, 0xc1000000, v26
	v_mul_f32_e32 v18, v38, v18
	v_mul_f32_e32 v18, 0x3fb8aa3b, v18
	v_exp_f32_e32 v31, v18
	v_add_f32_e32 v18, v88, v40
	v_mul_f32_e32 v18, 0xbfb8aa3b, v18
	v_exp_f32_e32 v26, v18
	v_fma_f32 v18, -v31, v31, 1.0
	v_max_f32_e32 v18, 0, v18
	s_nop 0
	s_nop 0
	v_exp_f32_e32 v28, v28
	v_add_f32_e32 v26, 1.0, v26
	v_mov_b32_e32 v27, v18
	s_nop 0
	v_add_f32_e32 v28, 1.0, v28
	v_rcp_f32_e32 v26, v26
	v_rcp_f32_e32 v49, v22
	s_nop 0
	s_nop 0
	s_nop 0
	s_nop 0
	v_add_f32_e32 v35, 1.0, v35
	s_nop 0
	s_nop 0
	s_nop 0
	v_rcp_f32_e32 v35, v35
	v_add_f32_e32 v23, v23, v41
	s_nop 0
	s_nop 0
	s_nop 0
	v_rcp_f32_e32 v33, v28
	s_nop 0
	v_mul_f32_e32 v23, 0xbfb8aa3b, v23
	v_add_f32_e32 v36, v36, v29
	v_sqrt_f32_e32 v27, v27
	s_nop 0
	v_mul_f32_e32 v28, v26, v27
	v_mul_f32_e32 v26, 0xc1000000, v33
	v_mul_f32_e32 v26, v38, v26
	v_mul_f32_e32 v26, 0x3fb8aa3b, v26
	v_exp_f32_e32 v33, v26
	v_add_f32_e32 v26, v89, v40
	v_mul_f32_e32 v26, 0xbfb8aa3b, v26
	v_exp_f32_e32 v32, v26
	v_fma_f32 v26, -v33, v33, 1.0
	v_max_f32_e32 v26, 0, v26
	s_nop 0
	s_nop 0
	v_add_f32_e32 v32, 1.0, v32
	v_rcp_f32_e32 v32, v32
	v_mov_b32_e32 v38, v26
	s_nop 0
	v_mul_f32_e32 v36, 0xbfb8aa3b, v36
	v_exp_f32_e32 v36, v36
	v_add_f32_e32 v29, v37, v29
	s_nop 0
	s_nop 0
	s_nop 0
	s_nop 0
	v_mul_f32_e32 v29, 0xbfb8aa3b, v29
	s_nop 0
	s_nop 0
	s_nop 0
	v_exp_f32_e32 v29, v29
	v_add_f32_e32 v24, v24, v41
	s_nop 0
	s_nop 0
	s_nop 0
	s_nop 0
	v_add_f32_e32 v29, 1.0, v29
	v_mov_b32_e32 v42, v47
	v_sqrt_f32_e32 v38, v38
	s_nop 0
	s_nop 0
	s_nop 0
	v_mul_f32_e32 v38, v32, v38
	v_rcp_f32_e32 v29, v29
	s_nop 0
	s_nop 0
	v_mul_f32_e32 v24, 0xbfb8aa3b, v24
	v_mul_f32_e32 v29, 0xc1000000, v29
	v_mul_f32_e32 v29, v39, v29
	s_nop 0
	s_nop 0
	s_nop 0
	s_nop 0
	v_mul_f32_e32 v29, 0x3fb8aa3b, v29
	s_nop 0
	s_nop 0
	s_nop 0
	v_exp_f32_e32 v24, v24
	ds_read2_b32 v[46:47], v176 offset0:96 offset1:112
	s_nop 0
	s_nop 0
	s_nop 0
	v_mul_f32_e32 v32, 0xc1000000, v35
	v_mul_f32_e32 v32, v39, v32
	s_nop 0
	v_mul_f32_e32 v32, 0x3fb8aa3b, v32
	v_add_f32_e32 v24, 1.0, v24
	v_sqrt_f32_e32 v22, v34
	s_nop 0
	v_exp_f32_e32 v34, v32
	v_exp_f32_e32 v32, v23
	v_rcp_f32_e32 v24, v24
	v_add_f32_e32 v25, v25, v41
	v_fma_f32 v23, -v34, v34, 1.0
	v_max_f32_e32 v23, 0, v23
	s_nop 0
	s_nop 0
	v_mul_f32_e32 v25, 0xbfb8aa3b, v25
	v_exp_f32_e32 v25, v25
	v_mov_b32_e32 v35, v23
	s_nop 0
	v_cndmask_b32_e64 v23, v22, 1.0, vcc
	v_add_f32_e32 v22, 1.0, v32
	v_rcp_f32_e32 v48, v22
	s_nop 0
	s_nop 0
	s_nop 0
	s_nop 0
	ds_read2_b32 v[50:51], v176 offset0:32 offset1:48
	s_nop 0
	s_nop 0
	s_nop 0
	v_add_f32_e32 v25, 1.0, v25
	v_rcp_f32_e32 v25, v25
	s_nop 0
	s_nop 0
	s_nop 0
	v_add_f32_e32 v32, 1.0, v36
	v_rcp_f32_e32 v32, v32
	s_nop 0
	s_waitcnt lgkmcnt(0)
; #define LAS __attribute__((address_space(3)))
; __device__ __forceinline__ float sigmoidf_(float x) { return __builtin_amdgcn_rcpf(1.0f + __expf(-x)); }
; template <int NT> ...
;     ...
;     for (int u = 0; u < NT; ++u) { const LAS float* XC = XCb + u * (16 * 68); const int t0 = m0 + 16 * u - b * TP;
; #pragma unroll
;         for (int n = 0; n < 4; ++n) { const int cc = 16 * n + fr;
;             const float ba = CST[5 * 64 + cc], bx = CST[6 * 64 + cc], sp = CST[7 * 64 + cc];
; #pragma unroll
;             for (int j = 0; j < 4; ++j) {
;                 const float xc = XC[(4 * fq + j) * 68 + cc];
;                 const float r = sigmoidf_(ar[u][n][j] + ba), ig = sigmoidf_(ai[u][n][j] + bx);
;                 const float a = __expf(-8.0f * r * sp);
;                 float mult = sqrtf(fmaxf(1.0f - a * a, 0.f));
;                 if (t0 + 4 * fq + j == 0) mult = 1.0f;
;                 av[u][n][j] = a; bv[u][n][j] = mult * ig * xc; } } }
	v_add_f32_e32 v10, v10, v50
	v_mul_f32_e32 v10, 0xbfb8aa3b, v10
	v_mul_f32_e32 v32, 0xc1000000, v32
	v_mul_f32_e32 v32, v39, v32
	v_mul_f32_e32 v32, 0x3fb8aa3b, v32
	v_sqrt_f32_e32 v22, v35
	s_nop 0
	v_exp_f32_e32 v35, v32
	v_pk_mul_f32 v[22:23], v[48:49], v[22:23]
	ds_read2_b32 v[48:49], v177 offset0:224 offset1:240
	v_pk_mul_f32 v[22:23], v[42:43], v[22:23]
	v_fma_f32 v32, -v35, v35, 1.0
	v_max_f32_e32 v32, 0, v32
	s_nop 0
	s_nop 0
	s_waitcnt lgkmcnt(0)
	v_add_f32_e32 v14, v14, v48
	v_mul_f32_e32 v14, 0xbfb8aa3b, v14
	s_nop 0
	s_nop 0
	v_exp_f32_e32 v14, v14
	v_exp_f32_e32 v10, v10
	v_mfma_f32_16x16x32_bf16 v[2:5], v[74:77], v[2:5], v[58:61]
	s_nop 0
	s_nop 0
	s_nop 0
	s_nop 0
	v_add_f32_e32 v14, 1.0, v14
	s_nop 0
	s_nop 0
	s_nop 0
	v_rcp_f32_e32 v14, v14
	v_add_f32_e32 v10, 1.0, v10
	s_nop 0
	s_nop 0
	s_nop 0
	v_exp_f32_e32 v37, v29
	s_nop 0
	v_mul_f32_e32 v14, 0xc1000000, v14
	v_mul_f32_e32 v14, v46, v14
	v_fma_f32 v29, -v37, v37, 1.0
	v_max_f32_e32 v29, 0, v29
	v_sqrt_f32_e32 v32, v32
	s_nop 0
	s_nop 0
	s_nop 0
	v_mul_f32_e32 v24, v24, v32
	v_mul_f32_e32 v14, 0x3fb8aa3b, v14
	s_nop 0
	s_nop 0
	v_exp_f32_e32 v57, v14
	v_rcp_f32_e32 v59, v10
	v_add_f32_e32 v15, v15, v48
	s_nop 0
	s_nop 0
	s_nop 0
	s_nop 0
	v_fma_f32 v14, -v57, v57, 1.0
	s_nop 0
	s_nop 0
	s_nop 0
	v_max_f32_e32 v14, 0, v14
	v_mul_f32_e32 v15, 0xbfb8aa3b, v15
	s_nop 0
	s_nop 0
	s_nop 0
	s_nop 0
	v_exp_f32_e32 v15, v15
	ds_read2_b32 v[52:53], v241 offset0:32 offset1:48
	v_sqrt_f32_e32 v29, v29
	s_nop 0
	v_mul_f32_e32 v40, v25, v29
	s_nop 0
	s_nop 0
	v_add_f32_e32 v15, 1.0, v15
	ds_read2_b32 v[60:61], v241 offset0:100 offset1:116
	s_nop 0
	s_nop 0
	v_add_f32_e32 v17, v17, v48
	v_mul_f32_e32 v17, 0xbfb8aa3b, v17
	v_exp_f32_e32 v17, v17
	s_nop 0
	s_nop 0
	s_nop 0
	s_nop 0
	v_add_f32_e32 v17, 1.0, v17
	s_nop 0
	s_nop 0
	s_nop 0
	v_rcp_f32_e32 v17, v17
	v_mfma_f32_16x16x32_bf16 v[6:9], v[74:77], v[6:9], v[62:65]
	s_nop 0
	s_nop 0
	s_nop 0
	v_rcp_f32_e32 v25, v15
	s_nop 0
	s_nop 2
	v_add_f32_e32 v6, v6, v49
	v_mul_f32_e32 v6, 0xbfb8aa3b, v6
	v_sqrt_f32_e32 v10, v14
	s_nop 0
	v_cndmask_b32_e64 v15, v10, 1.0, vcc
	v_mul_f32_e32 v10, 0xc1000000, v25
	v_mul_f32_e32 v10, v46, v10
	v_mul_f32_e32 v10, 0x3fb8aa3b, v10
	v_exp_f32_e32 v42, v10
	v_add_f32_e32 v10, v11, v50
	v_mul_f32_e32 v10, 0xbfb8aa3b, v10
	v_exp_f32_e32 v10, v10
	v_fma_f32 v11, -v42, v42, 1.0
	v_max_f32_e32 v11, 0, v11
	s_nop 0
	s_nop 0
	v_add_f32_e32 v10, 1.0, v10
	v_rcp_f32_e32 v58, v10
	s_nop 0
	s_nop 0
	v_exp_f32_e32 v6, v6
	v_add_f32_e32 v2, v2, v51
	v_mul_f32_e32 v2, 0xbfb8aa3b, v2
	s_nop 0
	s_nop 0
	s_nop 0
	s_nop 0
	v_add_f32_e32 v6, 1.0, v6
	s_nop 0
	s_nop 0
	s_nop 0
	v_rcp_f32_e32 v6, v6
	v_exp_f32_e32 v2, v2
	s_nop 0
	s_nop 0
	s_nop 0
	v_add_f32_e32 v14, v16, v48
	v_mul_f32_e32 v14, 0xbfb8aa3b, v14
	v_exp_f32_e32 v16, v14
	s_nop 0
	v_mul_f32_e32 v6, 0xc1000000, v6
	v_mul_f32_e32 v6, v47, v6
	v_sqrt_f32_e32 v14, v11
	s_nop 0
	v_pk_mul_f32 v[10:11], v[58:59], v[14:15]
	v_add_f32_e32 v14, 1.0, v16
	v_rcp_f32_e32 v16, v14
	s_waitcnt lgkmcnt(0)
	v_mov_b32_e32 v14, v60
	v_mov_b32_e32 v15, v52
	v_pk_mul_f32 v[14:15], v[14:15], v[10:11]
	v_mul_f32_e32 v10, 0xc1000000, v16
	v_mul_f32_e32 v10, v46, v10
	v_mul_f32_e32 v10, 0x3fb8aa3b, v10
	v_exp_f32_e32 v43, v10
	v_add_f32_e32 v10, v12, v50
	v_mul_f32_e32 v10, 0xbfb8aa3b, v10
	v_exp_f32_e32 v12, v10
	v_fma_f32 v10, -v43, v43, 1.0
	v_max_f32_e32 v10, 0, v10
	s_nop 0
	s_nop 0
	v_add_f32_e32 v12, 1.0, v12
	v_rcp_f32_e32 v12, v12
	v_mov_b32_e32 v16, v10
	s_nop 0
	v_mul_f32_e32 v6, 0x3fb8aa3b, v6
	v_exp_f32_e32 v48, v6
	v_add_f32_e32 v7, v7, v49
	s_nop 0
	s_nop 0
	s_nop 0
	s_nop 0
	v_fma_f32 v6, -v48, v48, 1.0
	s_nop 0
	s_nop 0
	s_nop 0
	v_max_f32_e32 v6, 0, v6
	v_mul_f32_e32 v7, 0xbfb8aa3b, v7
	s_nop 0
	s_nop 0
	s_nop 0
	s_nop 0
	v_add_f32_e32 v2, 1.0, v2
	v_exp_f32_e32 v7, v7
	v_sqrt_f32_e32 v16, v16
	s_nop 0
	v_mul_f32_e32 v16, v12, v16
	v_mul_f32_e32 v12, 0xc1000000, v17
	v_mul_f32_e32 v12, v46, v12
	v_mul_f32_e32 v12, 0x3fb8aa3b, v12
	v_exp_f32_e32 v45, v12
	v_add_f32_e32 v12, v13, v50
	v_mul_f32_e32 v12, 0xbfb8aa3b, v12
	v_exp_f32_e32 v17, v12
	v_fma_f32 v12, -v45, v45, 1.0
	v_max_f32_e32 v12, 0, v12
	s_nop 0
	s_nop 0
	v_add_f32_e32 v17, 1.0, v17
	v_rcp_f32_e32 v17, v17
	v_mov_b32_e32 v25, v12
	s_nop 0
	v_rcp_f32_e32 v59, v2
	v_add_f32_e32 v7, 1.0, v7
	v_rcp_f32_e32 v7, v7
	s_nop 0
	s_nop 0
	s_nop 0
	s_nop 0
	v_add_f32_e32 v3, v3, v51
	s_nop 0
	s_nop 0
	s_nop 0
	v_mul_f32_e32 v3, 0xbfb8aa3b, v3
	v_add_f32_e32 v8, v8, v49
	s_nop 0
	s_nop 0
	s_nop 0
	s_nop 0
	v_mul_f32_e32 v8, 0xbfb8aa3b, v8
	v_exp_f32_e32 v8, v8
	v_sqrt_f32_e32 v25, v25
	s_nop 0
	s_nop 0
	s_nop 0
	v_mul_f32_e32 v46, v17, v25
	v_add_f32_e32 v9, v9, v49
	s_nop 0
	s_nop 0
	v_mul_f32_e32 v9, 0xbfb8aa3b, v9
	v_exp_f32_e32 v9, v9
	v_add_f32_e32 v4, v4, v51
	s_nop 0
	s_nop 0
	s_nop 0
	s_nop 0
	s_nop 0
	s_nop 0
	s_nop 0
	v_add_f32_e32 v9, 1.0, v9
	v_rcp_f32_e32 v9, v9
	s_nop 0
	s_nop 0
	s_nop 0
	s_nop 0
	v_mul_f32_e32 v4, 0xbfb8aa3b, v4
	v_exp_f32_e32 v4, v4
	v_sqrt_f32_e32 v2, v6
	s_nop 0
	v_mul_f32_e32 v6, 0xc1000000, v7
	v_mul_f32_e32 v6, v47, v6
	v_mul_f32_e32 v6, 0x3fb8aa3b, v6
	v_exp_f32_e32 v60, v6
	v_exp_f32_e32 v6, v3
	v_add_f32_e32 v4, 1.0, v4
	v_rcp_f32_e32 v4, v4
	v_fma_f32 v3, -v60, v60, 1.0
	v_max_f32_e32 v3, 0, v3
	s_nop 0
	s_nop 0
	ds_read2_b32 v[18:19], v241 offset0:136 offset1:152
	v_add_f32_e32 v5, v5, v51
	v_mov_b32_e32 v7, v3
	s_nop 0
	v_cndmask_b32_e64 v3, v2, 1.0, vcc
	v_add_f32_e32 v2, 1.0, v6
	v_rcp_f32_e32 v58, v2
	s_nop 0
	s_nop 0
	s_nop 0
	s_nop 0
	ds_read2_b32 v[26:27], v241 offset0:204 offset1:220
	s_nop 0
	s_nop 0
	s_nop 0
	v_mul_f32_e32 v5, 0xbfb8aa3b, v5
	v_exp_f32_e32 v5, v5
	s_nop 0
	s_nop 0
	s_nop 0
	v_add_f32_e32 v6, 1.0, v8
	v_rcp_f32_e32 v6, v6
	s_nop 0
	v_fma_f32 v29, v30, v21, v20
	v_add_f32_e32 v5, 1.0, v5
	v_mul_f32_e32 v6, 0xc1000000, v6
	v_mul_f32_e32 v6, v47, v6
	v_mul_f32_e32 v6, 0x3fb8aa3b, v6
	v_sqrt_f32_e32 v2, v7
	s_nop 0
	v_exp_f32_e32 v7, v6
	s_waitcnt lgkmcnt(0)
; #define LAS __attribute__((address_space(3)))
; __device__ __forceinline__ unsigned cvt_pk_bf16(float lo, float hi) { unsigned r; asm volatile("v_cvt_pk_bf16_f32 %0, %1, %2" : "=v"(r) : "v"(lo), "v"(hi)); return r; }
; __device__ __forceinline__ float sigmoidf_(float x) { return __builtin_amdgcn_rcpf(1.0f + __expf(-x)); }
; template <int NT> ...
;     ...
;     for (int u = 0; u < NT; ++u) { const LAS float* XC = XCb + u * (16 * 68); const int t0 = m0 + 16 * u - b * TP;
; #pragma unroll
;         for (int n = 0; n < 4; ++n) { const int cc = 16 * n + fr;
;             const float ba = CST[5 * 64 + cc], bx = CST[6 * 64 + cc], sp = CST[7 * 64 + cc];
; #pragma unroll
;             for (int j = 0; j < 4; ++j) {
;                 const float xc = XC[(4 * fq + j) * 68 + cc];
;                 const float r = sigmoidf_(ar[u][n][j] + ba), ig = sigmoidf_(ai[u][n][j] + bx);
;                 const float a = __expf(-8.0f * r * sp);
;                 float mult = sqrtf(fmaxf(1.0f - a * a, 0.f));
;                 if (t0 + 4 * fq + j == 0) mult = 1.0f;
;                 av[u][n][j] = a; bv[u][n][j] = mult * ig * xc; } } }
; #pragma unroll
;     for (int u = 0; u < NT; ++u) {
; #pragma unroll
;         for (int n = 0; n < 4; ++n) { const int ch = hc0 + 16 * n + fr;
;             float hl[4], pl[4];
;             hl[0] = bv[u][n][0]; pl[0] = av[u][n][0];
; #pragma unroll
;             for (int j = 1; j < 4; ++j) { hl[j] = av[u][n][j] * hl[j - 1] + bv[u][n][j]; pl[j] = av[u][n][j] * pl[j - 1]; }
;             float He = 0.f, Pe = 1.f;
; #pragma unroll
;             for (int g = 0; g < 3; ++g) { const float Pg = __shfl(pl[3], fr + 16 * g), Hg = __shfl(hl[3], fr + 16 * g); if (g < fq) { He = Pg * He + Hg; Pe = Pg * Pe; } }
;             const float Hin = Pe * Hc[n] + He, Pin = Pe * Pc[n];
;             float hf[4], pf[4];
; #pragma unroll
;             for (int j = 0; j < 4; ++j) { hf[j] = hl[j] + pl[j] * Hin; pf[j] = pl[j] * Pin; }
; #pragma unroll
;             for (int j = 0; j < 4; ++j) { const size_t o = (size_t)(m0 + 16 * u + 4 * fq + j) * D + ch; HLOC[o] = (bf16_t)(cvt_pk_bf16(hf[j], 0.f) & 0xffffu); PCUM[o] = (bf16_t)(cvt_pk_bf16(pf[j], 0.f) & 0xffffu); }
;             Hc[n] = __shfl(hf[3], fr + 48); Pc[n] = __shfl(pf[3], fr + 48);
;         } }
	v_mov_b32_e32 v32, v26
	v_rcp_f32_e32 v5, v5
	ds_read2_b32 v[10:11], v241 offset0:168 offset1:184
	v_fma_f32 v6, -v7, v7, 1.0
	v_max_f32_e32 v6, 0, v6
	s_nop 0
	s_nop 0
	ds_read2_b32 v[12:13], v241 offset0:236 offset1:252
	v_mov_b32_e32 v36, v27
	s_nop 0
	s_nop 0
	v_or_b32_e32 v0, 0xc0, v134
	v_pk_mul_f32 v[2:3], v[58:59], v[2:3]
	v_mov_b32_e32 v52, v61
	s_nop 0
	s_nop 0
	s_nop 0
	s_nop 0
	v_pk_mul_f32 v[2:3], v[52:53], v[2:3]
	s_nop 0
	s_nop 0
	s_nop 0
	s_nop 1
	s_nop 0
	s_nop 0
	s_nop 0
	s_nop 0
	s_nop 1
	v_sqrt_f32_e32 v6, v6
	s_nop 0
	v_mul_f32_e32 v8, 0xc1000000, v9
	v_mul_f32_e32 v8, v47, v8
	v_mul_f32_e32 v8, 0x3fb8aa3b, v8
	v_exp_f32_e32 v9, v8
	v_mul_f32_e32 v4, v4, v6
	v_fma_f32 v8, -v9, v9, 1.0
	v_max_f32_e32 v8, 0, v8
	s_nop 0
	s_nop 0
	s_nop 1
	s_nop 0
	s_nop 0
	s_nop 0
	s_nop 0
	s_nop 0
	s_nop 0
	s_nop 0
	s_nop 0
	s_nop 0
	s_nop 0
	s_nop 0
	s_nop 1
	s_nop 0
	s_nop 0
	s_nop 0
	s_nop 0
	v_mul_f32_e32 v17, v30, v44
	v_mov_b32_e32 v30, v18
	v_sqrt_f32_e32 v8, v8
	s_nop 0
	v_mul_f32_e32 v6, v31, v29
	v_pk_fma_f32 v[50:51], v[30:31], v[28:29], v[6:7] op_sel_hi:[1,1,0]
	v_mul_f32_e32 v6, v31, v17
	v_mov_b32_e32 v39, v50
	v_pk_mul_f32 v[30:31], v[32:33], v[38:39]
	v_mul_f32_e32 v20, v33, v6
	v_add_f32_e32 v47, v30, v31
	ds_bpermute_b32 v25, v134, v20
	ds_bpermute_b32 v26, v134, v47
	v_mul_f32_e32 v18, v5, v8
	v_or_b32_e32 v32, s18, v229
	ds_bpermute_b32 v5, v55, v20
	ds_bpermute_b32 v8, v55, v47
	v_ashrrev_i32_e32 v33, 31, v32
	v_lshlrev_b64 v[30:31], 10, v[32:33]
	ds_bpermute_b32 v28, v54, v20
	ds_bpermute_b32 v33, v54, v47
	s_waitcnt lgkmcnt(4)
	v_fmac_f32_e32 v26, 0, v25
	v_cndmask_b32_e64 v26, v26, 0, s[8:9]
	v_cndmask_b32_e64 v25, v25, 1.0, s[8:9]
	s_waitcnt lgkmcnt(2)
	v_fmac_f32_e32 v8, v26, v5
	v_mul_f32_e32 v5, v25, v5
	v_cndmask_b32_e64 v8, v26, v8, s[4:5]
	v_cndmask_b32_e64 v5, v25, v5, s[4:5]
	s_waitcnt lgkmcnt(0)
	v_fmac_f32_e32 v33, v8, v28
	v_mul_f32_e32 v25, v5, v28
	v_cndmask_b32_e64 v8, v8, v33, s[6:7]
	v_cndmask_b32_e64 v5, v5, v25, s[6:7]
	v_fmac_f32_e32 v8, v5, v70
	v_mul_f32_e32 v5, v5, v72
	v_fmac_f32_e32 v21, v44, v8
	v_or_b32_e32 v38, v30, v208
	v_mov_b32_e32 v39, v31
	v_mul_f32_e32 v25, v44, v5
	v_fmac_f32_e32 v29, v17, v8
	v_mul_f32_e32 v17, v17, v5
	v_fmac_f32_e32 v50, v6, v8
	v_mul_f32_e32 v6, v6, v5
	v_fmac_f32_e32 v47, v20, v8
	v_mul_f32_e32 v5, v20, v5
	v_cvt_pk_bf16_f32 v8, v21, v1
	v_lshlrev_b64 v[20:21], 1, v[38:39]
	v_lshl_add_u64 v[38:39], s[62:63], 0, v[20:21]
	v_lshl_add_u64 v[20:21], s[64:65], 0, v[20:21]
	global_store_short v[38:39], v8, off
	v_cvt_pk_bf16_f32 v8, v25, v1
	global_store_short v[20:21], v8, off
	v_or_b32_e32 v20, 1, v32
	v_ashrrev_i32_e32 v21, 31, v20
	v_lshlrev_b64 v[20:21], 10, v[20:21]
	v_or_b32_e32 v38, v20, v208
	v_mov_b32_e32 v39, v21
	v_cvt_pk_bf16_f32 v8, v29, v1
	v_lshlrev_b64 v[28:29], 1, v[38:39]
	v_lshl_add_u64 v[38:39], s[62:63], 0, v[28:29]
	v_lshl_add_u64 v[28:29], s[64:65], 0, v[28:29]
	global_store_short v[38:39], v8, off
	v_cvt_pk_bf16_f32 v8, v17, v1
	global_store_short v[28:29], v8, off
	v_or_b32_e32 v28, 2, v32
	v_ashrrev_i32_e32 v29, 31, v28
	v_lshlrev_b64 v[28:29], 10, v[28:29]
	v_or_b32_e32 v38, v28, v208
	v_mov_b32_e32 v39, v29
	v_or_b32_e32 v32, 3, v32
	v_lshlrev_b64 v[38:39], 1, v[38:39]
	v_ashrrev_i32_e32 v33, 31, v32
	v_cvt_pk_bf16_f32 v8, v50, v1
	v_lshl_add_u64 v[50:51], s[62:63], 0, v[38:39]
	v_lshl_add_u64 v[38:39], s[64:65], 0, v[38:39]
	v_lshlrev_b64 v[32:33], 10, v[32:33]
	global_store_short v[50:51], v8, off
	v_cvt_pk_bf16_f32 v6, v6, v1
	global_store_short v[38:39], v6, off
	v_or_b32_e32 v38, v32, v208
	v_mov_b32_e32 v39, v33
	v_lshlrev_b64 v[38:39], 1, v[38:39]
	v_cvt_pk_bf16_f32 v6, v47, v1
	v_lshl_add_u64 v[50:51], s[62:63], 0, v[38:39]
	v_fma_f32 v25, v34, v23, v22
	global_store_short v[50:51], v6, off
	v_mul_f32_e32 v17, v34, v56
	v_mov_b32_e32 v34, v19
	v_mul_f32_e32 v6, v35, v25
	v_pk_fma_f32 v[50:51], v[34:35], v[24:25], v[6:7] op_sel_hi:[1,1,0]
	v_mul_f32_e32 v6, v35, v17
	v_mov_b32_e32 v41, v50
	v_pk_mul_f32 v[26:27], v[36:37], v[40:41]
	v_mul_f32_e32 v22, v37, v6
	v_add_f32_e32 v19, v26, v27
	ds_bpermute_b32 v24, v134, v22
	ds_bpermute_b32 v34, v134, v19
	v_cvt_pk_bf16_f32 v8, v5, v1
	v_lshl_add_u64 v[26:27], s[64:65], 0, v[38:39]
	global_store_short v[26:27], v8, off
	ds_bpermute_b32 v72, v0, v5
	ds_bpermute_b32 v5, v55, v22
	ds_bpermute_b32 v8, v55, v19
	s_waitcnt lgkmcnt(3)
	v_fmac_f32_e32 v34, 0, v24
	v_cndmask_b32_e64 v26, v34, 0, s[8:9]
	ds_bpermute_b32 v27, v54, v22
	ds_bpermute_b32 v34, v54, v19
	v_cndmask_b32_e64 v24, v24, 1.0, s[8:9]
	s_waitcnt lgkmcnt(2)
	v_fmac_f32_e32 v8, v26, v5
	v_mul_f32_e32 v5, v24, v5
	v_cndmask_b32_e64 v8, v26, v8, s[4:5]
	v_cndmask_b32_e64 v5, v24, v5, s[4:5]
	s_waitcnt lgkmcnt(0)
; __device__ __forceinline__ unsigned cvt_pk_bf16(float lo, float hi) { unsigned r; asm volatile("v_cvt_pk_bf16_f32 %0, %1, %2" : "=v"(r) : "v"(lo), "v"(hi)); return r; }
; template <int NT> ...
;     ...
;     for (int u = 0; u < NT; ++u) {
; #pragma unroll
;         for (int n = 0; n < 4; ++n) { const int ch = hc0 + 16 * n + fr;
;             float hl[4], pl[4];
;             hl[0] = bv[u][n][0]; pl[0] = av[u][n][0];
; #pragma unroll
;             for (int j = 1; j < 4; ++j) { hl[j] = av[u][n][j] * hl[j - 1] + bv[u][n][j]; pl[j] = av[u][n][j] * pl[j - 1]; }
;             float He = 0.f, Pe = 1.f;
; #pragma unroll
;             for (int g = 0; g < 3; ++g) { const float Pg = __shfl(pl[3], fr + 16 * g), Hg = __shfl(hl[3], fr + 16 * g); if (g < fq) { He = Pg * He + Hg; Pe = Pg * Pe; } }
;             const float Hin = Pe * Hc[n] + He, Pin = Pe * Pc[n];
;             float hf[4], pf[4];
; #pragma unroll
;             for (int j = 0; j < 4; ++j) { hf[j] = hl[j] + pl[j] * Hin; pf[j] = pl[j] * Pin; }
; #pragma unroll
;             for (int j = 0; j < 4; ++j) { const size_t o = (size_t)(m0 + 16 * u + 4 * fq + j) * D + ch; HLOC[o] = (bf16_t)(cvt_pk_bf16(hf[j], 0.f) & 0xffffu); PCUM[o] = (bf16_t)(cvt_pk_bf16(pf[j], 0.f) & 0xffffu); }
;             Hc[n] = __shfl(hf[3], fr + 48); Pc[n] = __shfl(pf[3], fr + 48);
;         } }
	v_fmac_f32_e32 v34, v8, v27
	v_mul_f32_e32 v24, v5, v27
	v_cndmask_b32_e64 v8, v8, v34, s[6:7]
	v_cndmask_b32_e64 v5, v5, v24, s[6:7]
	v_fmac_f32_e32 v8, v5, v71
	v_mul_f32_e32 v5, v5, v73
	v_fmac_f32_e32 v23, v56, v8
	v_or_b32_e32 v26, v30, v214
	v_mov_b32_e32 v27, v31
	v_mul_f32_e32 v24, v56, v5
	v_fmac_f32_e32 v25, v17, v8
	v_mul_f32_e32 v17, v17, v5
	v_fmac_f32_e32 v50, v6, v8
	v_mul_f32_e32 v6, v6, v5
	v_fmac_f32_e32 v19, v22, v8
	v_mul_f32_e32 v5, v22, v5
	v_cvt_pk_bf16_f32 v8, v23, v1
	v_lshlrev_b64 v[22:23], 1, v[26:27]
	v_lshl_add_u64 v[26:27], s[62:63], 0, v[22:23]
	v_lshl_add_u64 v[22:23], s[64:65], 0, v[22:23]
	global_store_short v[26:27], v8, off
	v_cvt_pk_bf16_f32 v8, v24, v1
	global_store_short v[22:23], v8, off
	v_or_b32_e32 v22, v20, v214
	v_mov_b32_e32 v23, v21
	v_lshlrev_b64 v[22:23], 1, v[22:23]
	v_cvt_pk_bf16_f32 v8, v25, v1
	v_lshl_add_u64 v[24:25], s[62:63], 0, v[22:23]
	v_lshl_add_u64 v[22:23], s[64:65], 0, v[22:23]
	global_store_short v[24:25], v8, off
	v_cvt_pk_bf16_f32 v8, v17, v1
	global_store_short v[22:23], v8, off
	v_or_b32_e32 v22, v28, v214
	v_mov_b32_e32 v23, v29
	v_lshlrev_b64 v[22:23], 1, v[22:23]
	v_lshl_add_u64 v[24:25], s[62:63], 0, v[22:23]
	v_lshl_add_u64 v[22:23], s[64:65], 0, v[22:23]
	v_cvt_pk_bf16_f32 v8, v50, v1
	global_store_short v[24:25], v8, off
	v_cvt_pk_bf16_f32 v6, v6, v1
	global_store_short v[22:23], v6, off
	v_or_b32_e32 v22, v32, v214
	v_mov_b32_e32 v23, v33
	v_lshlrev_b64 v[22:23], 1, v[22:23]
	v_cvt_pk_bf16_f32 v6, v19, v1
	v_lshl_add_u64 v[24:25], s[62:63], 0, v[22:23]
	v_fma_f32 v17, v42, v15, v14
	global_store_short v[24:25], v6, off
	v_mul_f32_e32 v14, v42, v57
	v_mov_b32_e32 v42, v10
	v_mul_f32_e32 v6, v43, v17
	v_pk_fma_f32 v[24:25], v[42:43], v[16:17], v[6:7] op_sel_hi:[1,1,0]
	ds_bpermute_b32 v70, v0, v47
	v_mov_b32_e32 v44, v12
	v_mov_b32_e32 v47, v24
	v_mul_f32_e32 v6, v43, v14
	v_pk_mul_f32 v[26:27], v[44:45], v[46:47]
	v_mul_f32_e32 v10, v45, v6
	v_add_f32_e32 v12, v26, v27
	ds_bpermute_b32 v16, v134, v10
	ds_bpermute_b32 v25, v134, v12
	v_cvt_pk_bf16_f32 v8, v5, v1
	v_lshl_add_u64 v[22:23], s[64:65], 0, v[22:23]
	global_store_short v[22:23], v8, off
	ds_bpermute_b32 v73, v0, v5
	ds_bpermute_b32 v5, v55, v10
	ds_bpermute_b32 v8, v55, v12
	ds_bpermute_b32 v22, v54, v10
	ds_bpermute_b32 v23, v54, v12
	s_waitcnt lgkmcnt(5)
	v_fmac_f32_e32 v25, 0, v16
	ds_bpermute_b32 v71, v0, v19
	v_cndmask_b32_e64 v19, v25, 0, s[8:9]
	v_cndmask_b32_e64 v16, v16, 1.0, s[8:9]
	s_waitcnt lgkmcnt(3)
	v_fmac_f32_e32 v8, v19, v5
	v_mul_f32_e32 v5, v16, v5
	v_cndmask_b32_e64 v8, v19, v8, s[4:5]
	v_cndmask_b32_e64 v5, v16, v5, s[4:5]
	s_waitcnt lgkmcnt(1)
	v_fmac_f32_e32 v23, v8, v22
	v_mul_f32_e32 v16, v5, v22
	v_cndmask_b32_e64 v8, v8, v23, s[6:7]
	v_cndmask_b32_e64 v5, v5, v16, s[6:7]
	v_fmac_f32_e32 v8, v5, v66
	v_mul_f32_e32 v5, v5, v68
	v_fmac_f32_e32 v15, v57, v8
	v_or_b32_e32 v22, v30, v212
	v_mov_b32_e32 v23, v31
	v_mul_f32_e32 v16, v57, v5
	v_fmac_f32_e32 v17, v14, v8
	v_mul_f32_e32 v19, v14, v5
	v_fmac_f32_e32 v24, v6, v8
	v_mul_f32_e32 v6, v6, v5
	v_mul_f32_e32 v25, v10, v5
	v_cvt_pk_bf16_f32 v5, v15, v1
	v_lshlrev_b64 v[14:15], 1, v[22:23]
	v_lshl_add_u64 v[22:23], s[62:63], 0, v[14:15]
	v_lshl_add_u64 v[14:15], s[64:65], 0, v[14:15]
	global_store_short v[22:23], v5, off
	v_cvt_pk_bf16_f32 v5, v16, v1
	global_store_short v[14:15], v5, off
	v_or_b32_e32 v14, v20, v212
	v_mov_b32_e32 v15, v21
	v_lshlrev_b64 v[14:15], 1, v[14:15]
	v_cvt_pk_bf16_f32 v5, v17, v1
	v_lshl_add_u64 v[16:17], s[62:63], 0, v[14:15]
	v_lshl_add_u64 v[14:15], s[64:65], 0, v[14:15]
	global_store_short v[16:17], v5, off
	v_cvt_pk_bf16_f32 v5, v19, v1
	global_store_short v[14:15], v5, off
	v_or_b32_e32 v14, v28, v212
	v_mov_b32_e32 v15, v29
	v_lshlrev_b64 v[14:15], 1, v[14:15]
	v_cvt_pk_bf16_f32 v5, v24, v1
	v_lshl_add_u64 v[16:17], s[62:63], 0, v[14:15]
	v_lshl_add_u64 v[14:15], s[64:65], 0, v[14:15]
	global_store_short v[16:17], v5, off
	v_cvt_pk_bf16_f32 v5, v6, v1
	global_store_short v[14:15], v5, off
	v_or_b32_e32 v14, v32, v212
	v_mov_b32_e32 v15, v33
	v_lshlrev_b64 v[14:15], 1, v[14:15]
	v_fmac_f32_e32 v12, v10, v8
	v_cvt_pk_bf16_f32 v5, v12, v1
	v_lshl_add_u64 v[16:17], s[62:63], 0, v[14:15]
	global_store_short v[16:17], v5, off
	v_fma_f32 v5, v60, v3, v2
	v_mov_b32_e32 v6, v11
	v_mul_f32_e32 v2, v7, v5
	v_pk_fma_f32 v[10:11], v[6:7], v[4:5], v[2:3] op_sel_hi:[1,1,0]
	v_mul_f32_e32 v17, v60, v48
	v_mov_b32_e32 v8, v13
	v_mov_b32_e32 v19, v10
	v_mul_f32_e32 v2, v7, v17
	v_pk_mul_f32 v[6:7], v[8:9], v[18:19]
	v_mul_f32_e32 v4, v9, v2
	v_add_f32_e32 v8, v6, v7
	ds_bpermute_b32 v9, v134, v4
	ds_bpermute_b32 v11, v134, v8
	v_lshl_add_u64 v[6:7], s[64:65], 0, v[14:15]
	v_cvt_pk_bf16_f32 v16, v25, v1
	global_store_short v[6:7], v16, off
	ds_bpermute_b32 v6, v55, v4
	ds_bpermute_b32 v7, v55, v8
	ds_bpermute_b32 v66, v0, v12
	ds_bpermute_b32 v12, v54, v4
	ds_bpermute_b32 v13, v54, v8
	s_waitcnt lgkmcnt(5)
	v_fmac_f32_e32 v11, 0, v9
	v_cndmask_b32_e64 v11, v11, 0, s[8:9]
	v_cndmask_b32_e64 v9, v9, 1.0, s[8:9]
	s_waitcnt lgkmcnt(3)
	v_fmac_f32_e32 v7, v11, v6
	v_mul_f32_e32 v6, v9, v6
	v_cndmask_b32_e64 v7, v11, v7, s[4:5]
	v_cndmask_b32_e64 v6, v9, v6, s[4:5]
	s_waitcnt lgkmcnt(0)
	v_fmac_f32_e32 v13, v7, v12
	v_mul_f32_e32 v9, v6, v12
	v_cndmask_b32_e64 v7, v7, v13, s[6:7]
	v_cndmask_b32_e64 v6, v6, v9, s[6:7]
	v_fmac_f32_e32 v7, v6, v67
	v_mul_f32_e32 v6, v6, v69
	v_fmac_f32_e32 v3, v48, v7
	v_or_b32_e32 v30, v30, v210
	v_fmac_f32_e32 v10, v2, v7
	v_mul_f32_e32 v12, v2, v6
	v_fmac_f32_e32 v8, v4, v7
	v_mul_f32_e32 v13, v4, v6
	v_cvt_pk_bf16_f32 v4, v3, v1
	v_lshlrev_b64 v[2:3], 1, v[30:31]
	v_mul_f32_e32 v9, v48, v6
	v_fmac_f32_e32 v5, v17, v7
	v_mul_f32_e32 v11, v17, v6
	v_lshl_add_u64 v[6:7], s[62:63], 0, v[2:3]
	v_lshl_add_u64 v[2:3], s[64:65], 0, v[2:3]
	v_or_b32_e32 v20, v20, v210
	global_store_short v[6:7], v4, off
	v_cvt_pk_bf16_f32 v4, v9, v1
	global_store_short v[2:3], v4, off
	v_lshlrev_b64 v[2:3], 1, v[20:21]
	ds_bpermute_b32 v68, v0, v25
	v_cvt_pk_bf16_f32 v6, v5, v1
	v_lshl_add_u64 v[4:5], s[62:63], 0, v[2:3]
	v_lshl_add_u64 v[2:3], s[64:65], 0, v[2:3]
	v_or_b32_e32 v28, v28, v210
	ds_bpermute_b32 v67, v0, v8
	ds_bpermute_b32 v69, v0, v13
	global_store_short v[4:5], v6, off
	v_cvt_pk_bf16_f32 v4, v11, v1
	global_store_short v[2:3], v4, off
	v_lshlrev_b64 v[2:3], 1, v[28:29]
	v_lshl_add_u64 v[4:5], s[62:63], 0, v[2:3]
	v_lshl_add_u64 v[2:3], s[64:65], 0, v[2:3]
	v_or_b32_e32 v32, v32, v210
	v_cvt_pk_bf16_f32 v6, v10, v1
	global_store_short v[4:5], v6, off
	v_cvt_pk_bf16_f32 v4, v12, v1
	global_store_short v[2:3], v4, off
	v_lshlrev_b64 v[2:3], 1, v[32:33]
	v_lshl_add_u64 v[4:5], s[62:63], 0, v[2:3]
	v_lshl_add_u64 v[2:3], s[64:65], 0, v[2:3]
	v_cvt_pk_bf16_f32 v6, v8, v1
	global_store_short v[4:5], v6, off
	v_cvt_pk_bf16_f32 v0, v13, v1
	global_store_short v[2:3], v0, off
